# GEMM epilogue stores of the four projection phases issued write-through (sc0 sc1) so the phase-end grid barrier's L2 write-back has less dirty data
# baseline (speedup 1.0000x reference)
.LBB0_377:
	ds_read_b128 v[152:155], v149
	ds_read_b128 v[156:159], v149 offset:1024
	ds_read_b128 v[160:163], v149 offset:2048
	ds_read_b128 v[168:171], v149 offset:3072
	s_add_u32 s26, s24, 0xfff80080
	s_addc_u32 s27, s25, -1
	s_cmp_eq_u32 s54, 28
	s_cselect_b32 s29, s17, s27
	s_cselect_b32 s28, s19, s26
	s_cselect_b32 s27, s15, s53
	s_cselect_b32 s26, s51, s52
	v_lshl_add_u64 v[144:145], s[24:25], 0, v[136:137]
	s_add_i32 m0, s39, 0xc000
	ds_read_b128 v[172:175], v150
	ds_read_b128 v[176:179], v150 offset:1024
	ds_read_b128 v[180:183], v150 offset:2048
	ds_read_b128 v[184:187], v150 offset:3072
	ds_read_b128 v[188:191], v150 offset:4096
	ds_read_b128 v[192:195], v150 offset:5120
	ds_read_b128 v[196:199], v150 offset:6144
	ds_read_b128 v[200:203], v150 offset:7168
	global_load_lds_dwordx4 v[144:145], off
	v_lshl_add_u64 v[144:145], s[24:25], 0, v[138:139]
	s_add_i32 m0, s39, 0xe000
	s_nop 0
	global_load_lds_dwordx4 v[144:145], off
	s_waitcnt lgkmcnt(8)
	s_barrier
	s_waitcnt lgkmcnt(0)
	s_setprio 1
	s_waitcnt lgkmcnt(0)
	v_mfma_f32_16x16x32_bf16 v[126:129], v[152:155], v[172:175], v[126:129]
	v_mfma_f32_16x16x32_bf16 v[122:125], v[160:163], v[172:175], v[122:125]
	v_mfma_f32_16x16x32_bf16 v[118:121], v[152:155], v[180:183], v[118:121]
	v_mfma_f32_16x16x32_bf16 v[114:117], v[160:163], v[180:183], v[114:117]
	v_mfma_f32_16x16x32_bf16 v[102:105], v[152:155], v[188:191], v[102:105]
	v_mfma_f32_16x16x32_bf16 v[98:101], v[160:163], v[188:191], v[98:101]
	v_mfma_f32_16x16x32_bf16 v[86:89], v[152:155], v[196:199], v[86:89]
	v_mfma_f32_16x16x32_bf16 v[82:85], v[160:163], v[196:199], v[82:85]
	v_mfma_f32_16x16x32_bf16 v[126:129], v[156:159], v[176:179], v[126:129]
	v_mfma_f32_16x16x32_bf16 v[122:125], v[168:171], v[176:179], v[122:125]
	v_mfma_f32_16x16x32_bf16 v[118:121], v[156:159], v[184:187], v[118:121]
	v_mfma_f32_16x16x32_bf16 v[114:117], v[168:171], v[184:187], v[114:117]
	v_mfma_f32_16x16x32_bf16 v[102:105], v[156:159], v[192:195], v[102:105]
	v_mfma_f32_16x16x32_bf16 v[98:101], v[168:171], v[192:195], v[98:101]
	v_mfma_f32_16x16x32_bf16 v[86:89], v[156:159], v[200:203], v[86:89]
	v_mfma_f32_16x16x32_bf16 v[82:85], v[168:171], v[200:203], v[82:85]
	s_setprio 0
	s_barrier
	s_add_i32 s55, s47, s34
	v_lshl_add_u64 v[144:145], s[26:27], 0, v[130:131]
	s_mov_b32 m0, s55
	ds_read_b128 v[204:207], v151
	ds_read_b128 v[208:211], v151 offset:1024
	ds_read_b128 v[212:215], v151 offset:2048
	ds_read_b128 v[216:219], v151 offset:3072
	global_load_lds_dwordx4 v[144:145], off
	v_lshl_add_u64 v[164:165], s[26:27], 0, v[132:133]
	s_add_i32 m0, s55, 0x2000
	s_nop 0
	global_load_lds_dwordx4 v[164:165], off
	s_barrier
	s_waitcnt lgkmcnt(0)
	s_setprio 1
	s_waitcnt lgkmcnt(0)
	v_mfma_f32_16x16x32_bf16 v[110:113], v[204:207], v[172:175], v[110:113]
	v_mfma_f32_16x16x32_bf16 v[106:109], v[212:215], v[172:175], v[106:109]
	v_mfma_f32_16x16x32_bf16 v[94:97], v[204:207], v[180:183], v[94:97]
	v_mfma_f32_16x16x32_bf16 v[90:93], v[212:215], v[180:183], v[90:93]
	v_mfma_f32_16x16x32_bf16 v[78:81], v[204:207], v[188:191], v[78:81]
	v_mfma_f32_16x16x32_bf16 v[74:77], v[212:215], v[188:191], v[74:77]
	v_mfma_f32_16x16x32_bf16 v[70:73], v[204:207], v[196:199], v[70:73]
	v_mfma_f32_16x16x32_bf16 v[66:69], v[212:215], v[196:199], v[66:69]
	v_mfma_f32_16x16x32_bf16 v[110:113], v[208:211], v[176:179], v[110:113]
	v_mfma_f32_16x16x32_bf16 v[106:109], v[216:219], v[176:179], v[106:109]
	v_mfma_f32_16x16x32_bf16 v[94:97], v[208:211], v[184:187], v[94:97]
	v_mfma_f32_16x16x32_bf16 v[90:93], v[216:219], v[184:187], v[90:93]
	v_mfma_f32_16x16x32_bf16 v[78:81], v[208:211], v[192:195], v[78:81]
	v_mfma_f32_16x16x32_bf16 v[74:77], v[216:219], v[192:195], v[74:77]
	v_mfma_f32_16x16x32_bf16 v[70:73], v[208:211], v[200:203], v[70:73]
	v_mfma_f32_16x16x32_bf16 v[66:69], v[216:219], v[200:203], v[66:69]
	s_setprio 0
	s_mov_b32 m0, s39
	v_lshl_add_u64 v[166:167], s[28:29], 0, v[130:131]
	s_barrier
	ds_read_b128 v[172:175], v150 offset:16384
	ds_read_b128 v[176:179], v150 offset:17408
	ds_read_b128 v[180:183], v150 offset:18432
	ds_read_b128 v[184:187], v150 offset:19456
	ds_read_b128 v[188:191], v150 offset:20480
	ds_read_b128 v[192:195], v150 offset:21504
	ds_read_b128 v[196:199], v150 offset:22528
	ds_read_b128 v[200:203], v150 offset:23552
	global_load_lds_dwordx4 v[166:167], off
	v_lshl_add_u64 v[220:221], s[28:29], 0, v[132:133]
	s_mov_b32 m0, s40
	s_nop 0
	global_load_lds_dwordx4 v[220:221], off
	s_barrier
	s_waitcnt lgkmcnt(0)
	s_setprio 1
	s_waitcnt lgkmcnt(0)
	v_mfma_f32_16x16x32_bf16 v[62:65], v[152:155], v[172:175], v[62:65]
	v_mfma_f32_16x16x32_bf16 v[58:61], v[160:163], v[172:175], v[58:61]
	v_mfma_f32_16x16x32_bf16 v[54:57], v[152:155], v[180:183], v[54:57]
	v_mfma_f32_16x16x32_bf16 v[50:53], v[160:163], v[180:183], v[50:53]
	v_mfma_f32_16x16x32_bf16 v[38:41], v[152:155], v[188:191], v[38:41]
	v_mfma_f32_16x16x32_bf16 v[34:37], v[160:163], v[188:191], v[34:37]
	v_mfma_f32_16x16x32_bf16 v[22:25], v[152:155], v[196:199], v[22:25]
	v_mfma_f32_16x16x32_bf16 v[18:21], v[160:163], v[196:199], v[18:21]
	v_mfma_f32_16x16x32_bf16 v[62:65], v[156:159], v[176:179], v[62:65]
	v_mfma_f32_16x16x32_bf16 v[58:61], v[168:171], v[176:179], v[58:61]
	v_mfma_f32_16x16x32_bf16 v[54:57], v[156:159], v[184:187], v[54:57]
	v_mfma_f32_16x16x32_bf16 v[50:53], v[168:171], v[184:187], v[50:53]
	v_mfma_f32_16x16x32_bf16 v[38:41], v[156:159], v[192:195], v[38:41]
	v_mfma_f32_16x16x32_bf16 v[34:37], v[168:171], v[192:195], v[34:37]
	v_mfma_f32_16x16x32_bf16 v[22:25], v[156:159], v[200:203], v[22:25]
	v_mfma_f32_16x16x32_bf16 v[18:21], v[168:171], v[200:203], v[18:21]
	s_setprio 0
	s_barrier
	s_add_u32 s56, s26, 0x80000
	s_addc_u32 s57, s27, 0
	s_add_i32 s55, s48, s34
	v_lshl_add_u64 v[152:153], s[56:57], 0, v[130:131]
	s_mov_b32 m0, s55
	s_nop 0
	global_load_lds_dwordx4 v[152:153], off
	v_lshl_add_u64 v[152:153], s[56:57], 0, v[132:133]
	s_add_i32 m0, s55, 0x2000
	s_nop 0
	global_load_lds_dwordx4 v[152:153], off
	s_waitcnt vmcnt(6)
	s_barrier
	s_setprio 1
	v_mfma_f32_16x16x32_bf16 v[46:49], v[204:207], v[172:175], v[46:49]
	v_mfma_f32_16x16x32_bf16 v[42:45], v[212:215], v[172:175], v[42:45]
	v_mfma_f32_16x16x32_bf16 v[30:33], v[204:207], v[180:183], v[30:33]
	v_mfma_f32_16x16x32_bf16 v[26:29], v[212:215], v[180:183], v[26:29]
	v_mfma_f32_16x16x32_bf16 v[14:17], v[204:207], v[188:191], v[14:17]
	v_mfma_f32_16x16x32_bf16 v[10:13], v[212:215], v[188:191], v[10:13]
	v_mfma_f32_16x16x32_bf16 v[6:9], v[204:207], v[196:199], v[6:9]
	v_mfma_f32_16x16x32_bf16 v[2:5], v[212:215], v[196:199], v[2:5]
	v_mfma_f32_16x16x32_bf16 v[46:49], v[208:211], v[176:179], v[46:49]
	v_mfma_f32_16x16x32_bf16 v[42:45], v[216:219], v[176:179], v[42:45]
	v_mfma_f32_16x16x32_bf16 v[30:33], v[208:211], v[184:187], v[30:33]
	v_mfma_f32_16x16x32_bf16 v[26:29], v[216:219], v[184:187], v[26:29]
	v_mfma_f32_16x16x32_bf16 v[14:17], v[208:211], v[192:195], v[14:17]
	v_mfma_f32_16x16x32_bf16 v[10:13], v[216:219], v[192:195], v[10:13]
	v_mfma_f32_16x16x32_bf16 v[6:9], v[208:211], v[200:203], v[6:9]
	v_mfma_f32_16x16x32_bf16 v[2:5], v[216:219], v[200:203], v[2:5]
	s_setprio 0
	s_add_i32 s55, 0, 0x18000
	v_add_u32_e32 v168, s55, v147
	s_barrier
	ds_read_b128 v[152:155], v168
	ds_read_b128 v[156:159], v168 offset:1024
	ds_read_b128 v[160:163], v168 offset:2048
	ds_read_b128 v[168:171], v168 offset:3072
	s_add_u32 s28, s28, 0x80000
	s_addc_u32 s29, s29, 0
	s_mov_b32 m0, s41
	v_lshl_add_u64 v[204:205], s[28:29], 0, v[130:131]
	ds_read_b128 v[172:175], v150 offset:32768
	ds_read_b128 v[176:179], v150 offset:33792
	ds_read_b128 v[180:183], v150 offset:34816
	ds_read_b128 v[184:187], v150 offset:35840
	ds_read_b128 v[188:191], v150 offset:36864
	ds_read_b128 v[192:195], v150 offset:37888
	ds_read_b128 v[196:199], v150 offset:38912
	ds_read_b128 v[200:203], v150 offset:39936
	global_load_lds_dwordx4 v[204:205], off
	v_lshl_add_u64 v[204:205], s[28:29], 0, v[132:133]
	s_mov_b32 m0, s42
	s_nop 0
	global_load_lds_dwordx4 v[204:205], off
	s_waitcnt lgkmcnt(8)
	s_barrier
	s_waitcnt lgkmcnt(0)
	s_setprio 1
	s_waitcnt lgkmcnt(0)
	v_mfma_f32_16x16x32_bf16 v[126:129], v[152:155], v[172:175], v[126:129]
	v_mfma_f32_16x16x32_bf16 v[122:125], v[160:163], v[172:175], v[122:125]
	v_mfma_f32_16x16x32_bf16 v[118:121], v[152:155], v[180:183], v[118:121]
	v_mfma_f32_16x16x32_bf16 v[114:117], v[160:163], v[180:183], v[114:117]
	v_mfma_f32_16x16x32_bf16 v[102:105], v[152:155], v[188:191], v[102:105]
	v_mfma_f32_16x16x32_bf16 v[98:101], v[160:163], v[188:191], v[98:101]
	v_mfma_f32_16x16x32_bf16 v[86:89], v[152:155], v[196:199], v[86:89]
	v_mfma_f32_16x16x32_bf16 v[82:85], v[160:163], v[196:199], v[82:85]
	v_mfma_f32_16x16x32_bf16 v[126:129], v[156:159], v[176:179], v[126:129]
	v_mfma_f32_16x16x32_bf16 v[122:125], v[168:171], v[176:179], v[122:125]
	v_mfma_f32_16x16x32_bf16 v[118:121], v[156:159], v[184:187], v[118:121]
	v_mfma_f32_16x16x32_bf16 v[114:117], v[168:171], v[184:187], v[114:117]
	v_mfma_f32_16x16x32_bf16 v[102:105], v[156:159], v[192:195], v[102:105]
	v_mfma_f32_16x16x32_bf16 v[98:101], v[168:171], v[192:195], v[98:101]
	v_mfma_f32_16x16x32_bf16 v[86:89], v[156:159], v[200:203], v[86:89]
	v_mfma_f32_16x16x32_bf16 v[82:85], v[168:171], v[200:203], v[82:85]
	s_setprio 0
	s_barrier
	s_add_i32 s28, 0, 0x1c000
	s_add_i32 s29, s55, s34
	v_add_u32_e32 v216, s28, v147
	v_lshl_add_u64 v[144:145], v[144:145], 0, s[10:11]
	s_mov_b32 m0, s29
	ds_read_b128 v[204:207], v216
	ds_read_b128 v[208:211], v216 offset:1024
	ds_read_b128 v[212:215], v216 offset:2048
	ds_read_b128 v[216:219], v216 offset:3072
	global_load_lds_dwordx4 v[144:145], off
	v_lshl_add_u64 v[144:145], v[164:165], 0, s[10:11]
	s_add_i32 m0, s29, 0x2000
	s_nop 0
	global_load_lds_dwordx4 v[144:145], off
	s_barrier
	s_waitcnt lgkmcnt(0)
	s_setprio 1
	s_waitcnt lgkmcnt(0)
	v_mfma_f32_16x16x32_bf16 v[110:113], v[204:207], v[172:175], v[110:113]
	v_mfma_f32_16x16x32_bf16 v[106:109], v[212:215], v[172:175], v[106:109]
	v_mfma_f32_16x16x32_bf16 v[94:97], v[204:207], v[180:183], v[94:97]
	v_mfma_f32_16x16x32_bf16 v[90:93], v[212:215], v[180:183], v[90:93]
	v_mfma_f32_16x16x32_bf16 v[78:81], v[204:207], v[188:191], v[78:81]
	v_mfma_f32_16x16x32_bf16 v[74:77], v[212:215], v[188:191], v[74:77]
	v_mfma_f32_16x16x32_bf16 v[70:73], v[204:207], v[196:199], v[70:73]
	v_mfma_f32_16x16x32_bf16 v[66:69], v[212:215], v[196:199], v[66:69]
	v_mfma_f32_16x16x32_bf16 v[110:113], v[208:211], v[176:179], v[110:113]
	v_mfma_f32_16x16x32_bf16 v[106:109], v[216:219], v[176:179], v[106:109]
	v_mfma_f32_16x16x32_bf16 v[94:97], v[208:211], v[184:187], v[94:97]
	v_mfma_f32_16x16x32_bf16 v[90:93], v[216:219], v[184:187], v[90:93]
	v_mfma_f32_16x16x32_bf16 v[78:81], v[208:211], v[192:195], v[78:81]
	v_mfma_f32_16x16x32_bf16 v[74:77], v[216:219], v[192:195], v[74:77]
	v_mfma_f32_16x16x32_bf16 v[70:73], v[208:211], v[200:203], v[70:73]
	v_mfma_f32_16x16x32_bf16 v[66:69], v[216:219], v[200:203], v[66:69]
	s_setprio 0
	s_mov_b32 m0, s45
	v_lshl_add_u64 v[144:145], v[166:167], 0, s[10:11]
	s_barrier
	ds_read_b128 v[172:175], v150 offset:49152
	ds_read_b128 v[176:179], v150 offset:50176
	ds_read_b128 v[180:183], v150 offset:51200
	ds_read_b128 v[184:187], v150 offset:52224
	ds_read_b128 v[188:191], v150 offset:53248
	ds_read_b128 v[192:195], v150 offset:54272
	ds_read_b128 v[196:199], v150 offset:55296
	ds_read_b128 v[200:203], v150 offset:56320
	global_load_lds_dwordx4 v[144:145], off
	v_lshl_add_u64 v[144:145], v[220:221], 0, s[10:11]
	s_mov_b32 m0, s46
	s_nop 0
	global_load_lds_dwordx4 v[144:145], off
	s_barrier
	s_waitcnt lgkmcnt(0)
	s_setprio 1
	s_waitcnt lgkmcnt(0)
	v_mfma_f32_16x16x32_bf16 v[62:65], v[152:155], v[172:175], v[62:65]
	v_mfma_f32_16x16x32_bf16 v[58:61], v[160:163], v[172:175], v[58:61]
	v_mfma_f32_16x16x32_bf16 v[54:57], v[152:155], v[180:183], v[54:57]
	v_mfma_f32_16x16x32_bf16 v[50:53], v[160:163], v[180:183], v[50:53]
	v_mfma_f32_16x16x32_bf16 v[38:41], v[152:155], v[188:191], v[38:41]
	v_mfma_f32_16x16x32_bf16 v[34:37], v[160:163], v[188:191], v[34:37]
	v_mfma_f32_16x16x32_bf16 v[22:25], v[152:155], v[196:199], v[22:25]
	v_mfma_f32_16x16x32_bf16 v[18:21], v[160:163], v[196:199], v[18:21]
	v_mfma_f32_16x16x32_bf16 v[62:65], v[156:159], v[176:179], v[62:65]
	v_mfma_f32_16x16x32_bf16 v[58:61], v[168:171], v[176:179], v[58:61]
	v_mfma_f32_16x16x32_bf16 v[54:57], v[156:159], v[184:187], v[54:57]
	v_mfma_f32_16x16x32_bf16 v[50:53], v[168:171], v[184:187], v[50:53]
	v_mfma_f32_16x16x32_bf16 v[38:41], v[156:159], v[192:195], v[38:41]
	v_mfma_f32_16x16x32_bf16 v[34:37], v[168:171], v[192:195], v[34:37]
	v_mfma_f32_16x16x32_bf16 v[22:25], v[156:159], v[200:203], v[22:25]
	v_mfma_f32_16x16x32_bf16 v[18:21], v[168:171], v[200:203], v[18:21]
	s_setprio 0
	s_barrier
	s_add_u32 s26, s26, 0x80080
	s_addc_u32 s27, s27, 0
	s_add_i32 s28, s28, s34
	v_lshl_add_u64 v[144:145], s[26:27], 0, v[130:131]
	s_mov_b32 m0, s28
	s_nop 0
	global_load_lds_dwordx4 v[144:145], off
	v_lshl_add_u64 v[144:145], s[26:27], 0, v[132:133]
	s_add_i32 m0, s28, 0x2000
	s_nop 0
	global_load_lds_dwordx4 v[144:145], off
	s_waitcnt vmcnt(6)
	s_barrier
	s_setprio 1
	v_mfma_f32_16x16x32_bf16 v[46:49], v[204:207], v[172:175], v[46:49]
	v_mfma_f32_16x16x32_bf16 v[42:45], v[212:215], v[172:175], v[42:45]
	v_mfma_f32_16x16x32_bf16 v[30:33], v[204:207], v[180:183], v[30:33]
	v_mfma_f32_16x16x32_bf16 v[26:29], v[212:215], v[180:183], v[26:29]
	v_mfma_f32_16x16x32_bf16 v[14:17], v[204:207], v[188:191], v[14:17]
	v_mfma_f32_16x16x32_bf16 v[10:13], v[212:215], v[188:191], v[10:13]
	v_mfma_f32_16x16x32_bf16 v[6:9], v[204:207], v[196:199], v[6:9]
	v_mfma_f32_16x16x32_bf16 v[2:5], v[212:215], v[196:199], v[2:5]
	v_mfma_f32_16x16x32_bf16 v[46:49], v[208:211], v[176:179], v[46:49]
	v_mfma_f32_16x16x32_bf16 v[42:45], v[216:219], v[176:179], v[42:45]
	v_mfma_f32_16x16x32_bf16 v[30:33], v[208:211], v[184:187], v[30:33]
	v_mfma_f32_16x16x32_bf16 v[26:29], v[216:219], v[184:187], v[26:29]
	v_mfma_f32_16x16x32_bf16 v[14:17], v[208:211], v[192:195], v[14:17]
	v_mfma_f32_16x16x32_bf16 v[10:13], v[216:219], v[192:195], v[10:13]
	v_mfma_f32_16x16x32_bf16 v[6:9], v[208:211], v[200:203], v[6:9]
	v_mfma_f32_16x16x32_bf16 v[2:5], v[216:219], v[200:203], v[2:5]
	s_setprio 0
	s_add_i32 s54, s54, 2
	s_add_u32 s24, s24, 0x100
	s_addc_u32 s25, s25, 0
	s_add_u32 s52, s52, 0x100
	s_addc_u32 s53, s53, 0
	s_cmp_gt_u32 s54, 29
	s_barrier
	s_cbranch_scc0 .LBB0_377
	v_lshl_add_u32 v144, s18, 8, v146
	s_cmp_gt_i32 s50, 21
	s_mov_b64 s[18:19], -1
	s_cbranch_scc0 .LBB0_382
	s_andn2_b64 vcc, exec, s[12:13]
	s_cbranch_vccnz .LBB0_381
	v_or_b32_e32 v154, 16, v144
	v_ashrrev_i32_e32 v155, 31, v154
	v_lshlrev_b64 v[154:155], 6, v[154:155]
	v_lshl_add_u64 v[154:155], v[134:135], 0, v[154:155]
	global_store_dwordx4 v[154:155], v[118:121], off sc0 sc1
	v_or_b32_e32 v154, 32, v144
	v_ashrrev_i32_e32 v155, 31, v154
	v_lshlrev_b64 v[154:155], 6, v[154:155]
	v_ashrrev_i32_e32 v145, 31, v144
	v_lshl_add_u64 v[154:155], v[134:135], 0, v[154:155]
	v_lshlrev_b64 v[152:153], 6, v[144:145]
	global_store_dwordx4 v[154:155], v[102:105], off sc0 sc1
	v_or_b32_e32 v154, 48, v144
	v_lshl_add_u64 v[152:153], v[134:135], 0, v[152:153]
	v_ashrrev_i32_e32 v155, 31, v154
	global_store_dwordx4 v[152:153], v[126:129], off sc0 sc1
	v_lshlrev_b64 v[154:155], 6, v[154:155]
	v_add_co_u32_e32 v152, vcc, 0x2000, v152
	v_lshl_add_u64 v[154:155], v[134:135], 0, v[154:155]
	s_nop 0
	v_addc_co_u32_e32 v153, vcc, 0, v153, vcc
	global_store_dwordx4 v[154:155], v[86:89], off sc0 sc1
	global_store_dwordx4 v[152:153], v[62:65], off sc0 sc1
	global_store_dwordx4 v[152:153], v[54:57], off offset:1024 sc0 sc1
	global_store_dwordx4 v[152:153], v[38:41], off offset:2048 sc0 sc1
	global_store_dwordx4 v[152:153], v[22:25], off offset:3072 sc0 sc1

.LBB0_382:
	s_andn2_b64 vcc, exec, s[18:19]
	s_cbranch_vccnz .LBB0_369
	v_lshl_or_b32 v152, s50, 8, v148
	v_ashrrev_i32_e32 v153, 31, v152
	v_mov_b64_e32 v[154:155], s[8:9]
	v_lshlrev_b64 v[152:153], 1, v[152:153]
	v_lshl_add_u64 v[154:155], v[154:155], 0, v[152:153]
	v_mad_i64_i32 v[160:161], s[18:19], v144, s49, v[154:155]
	v_or_b32_e32 v156, 16, v144
	v_mad_i64_i32 v[162:163], s[18:19], v156, s49, v[154:155]
	v_or_b32_e32 v156, 32, v144
	v_mad_i64_i32 v[164:165], s[18:19], v156, s49, v[154:155]
	v_or_b32_e32 v156, 48, v144
	v_mad_i64_i32 v[166:167], s[18:19], v156, s49, v[154:155]
	v_add_u32_e32 v156, 0x80, v144
	v_mad_i64_i32 v[168:169], s[18:19], v156, s49, v[154:155]
	v_add_u32_e32 v156, 0x90, v144
	v_mad_i64_i32 v[170:171], s[18:19], v156, s49, v[154:155]
	v_add_u32_e32 v156, 0xa0, v144
	v_mad_i64_i32 v[172:173], s[18:19], v156, s49, v[154:155]
	v_add_u32_e32 v156, 0xb0, v144
	v_mad_i64_i32 v[174:175], s[18:19], v156, s49, v[154:155]
	v_cvt_pk_bf16_f32 v126, v126, v127
	v_cvt_pk_bf16_f32 v127, v128, v129
	v_cvt_pk_bf16_f32 v128, v122, v123
	v_cvt_pk_bf16_f32 v129, v124, v125
	v_cvt_pk_bf16_f32 v110, v110, v111
	v_cvt_pk_bf16_f32 v111, v112, v113
	v_cvt_pk_bf16_f32 v112, v106, v107
	v_cvt_pk_bf16_f32 v113, v108, v109
	v_permlane16_swap_b32_e32 v126, v128
	v_permlane16_swap_b32_e32 v127, v129
	global_store_dwordx4 v[160:161], v[126:129], off sc0 sc1
	v_cvt_pk_bf16_f32 v118, v118, v119
	v_cvt_pk_bf16_f32 v119, v120, v121
	v_cvt_pk_bf16_f32 v120, v114, v115
	v_cvt_pk_bf16_f32 v121, v116, v117
	v_permlane16_swap_b32_e32 v110, v112
	v_permlane16_swap_b32_e32 v111, v113
	global_store_dwordx4 v[160:161], v[110:113], off offset:256 sc0 sc1
	v_cvt_pk_bf16_f32 v94, v94, v95
	v_cvt_pk_bf16_f32 v95, v96, v97
	v_cvt_pk_bf16_f32 v96, v90, v91
	v_cvt_pk_bf16_f32 v97, v92, v93
	v_permlane16_swap_b32_e32 v118, v120
	v_permlane16_swap_b32_e32 v119, v121
	global_store_dwordx4 v[162:163], v[118:121], off sc0 sc1
	v_cvt_pk_bf16_f32 v102, v102, v103
	v_cvt_pk_bf16_f32 v103, v104, v105
	v_cvt_pk_bf16_f32 v104, v98, v99
	v_cvt_pk_bf16_f32 v105, v100, v101
	v_permlane16_swap_b32_e32 v94, v96
	v_permlane16_swap_b32_e32 v95, v97
	global_store_dwordx4 v[162:163], v[94:97], off offset:256 sc0 sc1
	v_cvt_pk_bf16_f32 v78, v78, v79
	v_cvt_pk_bf16_f32 v79, v80, v81
	v_cvt_pk_bf16_f32 v80, v74, v75
	v_cvt_pk_bf16_f32 v81, v76, v77
	v_permlane16_swap_b32_e32 v102, v104
	v_permlane16_swap_b32_e32 v103, v105
	global_store_dwordx4 v[164:165], v[102:105], off sc0 sc1
	v_cvt_pk_bf16_f32 v86, v86, v87
	v_cvt_pk_bf16_f32 v87, v88, v89
	v_cvt_pk_bf16_f32 v88, v82, v83
	v_cvt_pk_bf16_f32 v89, v84, v85
	v_permlane16_swap_b32_e32 v78, v80
	v_permlane16_swap_b32_e32 v79, v81
	global_store_dwordx4 v[164:165], v[78:81], off offset:256 sc0 sc1
	v_cvt_pk_bf16_f32 v70, v70, v71
	v_cvt_pk_bf16_f32 v71, v72, v73
	v_cvt_pk_bf16_f32 v72, v66, v67
	v_cvt_pk_bf16_f32 v73, v68, v69
	v_permlane16_swap_b32_e32 v86, v88
	v_permlane16_swap_b32_e32 v87, v89
	global_store_dwordx4 v[166:167], v[86:89], off sc0 sc1
	v_cvt_pk_bf16_f32 v62, v62, v63
	v_cvt_pk_bf16_f32 v63, v64, v65
	v_cvt_pk_bf16_f32 v64, v58, v59
	v_cvt_pk_bf16_f32 v65, v60, v61
	v_permlane16_swap_b32_e32 v70, v72
	v_permlane16_swap_b32_e32 v71, v73
	global_store_dwordx4 v[166:167], v[70:73], off offset:256 sc0 sc1
	v_cvt_pk_bf16_f32 v46, v46, v47
	v_cvt_pk_bf16_f32 v47, v48, v49
	v_cvt_pk_bf16_f32 v48, v42, v43
	v_cvt_pk_bf16_f32 v49, v44, v45
	v_permlane16_swap_b32_e32 v62, v64
	v_permlane16_swap_b32_e32 v63, v65
	global_store_dwordx4 v[168:169], v[62:65], off sc0 sc1
	v_cvt_pk_bf16_f32 v54, v54, v55
	v_cvt_pk_bf16_f32 v55, v56, v57
	v_cvt_pk_bf16_f32 v56, v50, v51
	v_cvt_pk_bf16_f32 v57, v52, v53
	v_permlane16_swap_b32_e32 v46, v48
	v_permlane16_swap_b32_e32 v47, v49
	global_store_dwordx4 v[168:169], v[46:49], off offset:256 sc0 sc1
	v_cvt_pk_bf16_f32 v30, v30, v31
	v_cvt_pk_bf16_f32 v31, v32, v33
	v_cvt_pk_bf16_f32 v32, v26, v27
	v_cvt_pk_bf16_f32 v33, v28, v29
	v_permlane16_swap_b32_e32 v54, v56
	v_permlane16_swap_b32_e32 v55, v57
	global_store_dwordx4 v[170:171], v[54:57], off sc0 sc1
	v_cvt_pk_bf16_f32 v38, v38, v39
	v_cvt_pk_bf16_f32 v39, v40, v41
	v_cvt_pk_bf16_f32 v40, v34, v35
	v_cvt_pk_bf16_f32 v41, v36, v37
	v_permlane16_swap_b32_e32 v30, v32
	v_permlane16_swap_b32_e32 v31, v33
	global_store_dwordx4 v[170:171], v[30:33], off offset:256 sc0 sc1
	v_cvt_pk_bf16_f32 v14, v14, v15
	v_cvt_pk_bf16_f32 v15, v16, v17
	v_cvt_pk_bf16_f32 v16, v10, v11
	v_cvt_pk_bf16_f32 v17, v12, v13
	v_permlane16_swap_b32_e32 v38, v40
	v_permlane16_swap_b32_e32 v39, v41
	global_store_dwordx4 v[172:173], v[38:41], off sc0 sc1
	v_cvt_pk_bf16_f32 v22, v22, v23
	v_cvt_pk_bf16_f32 v23, v24, v25
	v_cvt_pk_bf16_f32 v24, v18, v19
	v_cvt_pk_bf16_f32 v25, v20, v21
	v_permlane16_swap_b32_e32 v14, v16
	v_permlane16_swap_b32_e32 v15, v17
	global_store_dwordx4 v[172:173], v[14:17], off offset:256 sc0 sc1
	v_cvt_pk_bf16_f32 v6, v6, v7
	v_cvt_pk_bf16_f32 v7, v8, v9
	v_cvt_pk_bf16_f32 v8, v2, v3
	v_cvt_pk_bf16_f32 v9, v4, v5
	v_permlane16_swap_b32_e32 v22, v24
	v_permlane16_swap_b32_e32 v23, v25
	global_store_dwordx4 v[174:175], v[22:25], off sc0 sc1
	s_nop 1
	v_permlane16_swap_b32_e32 v6, v8
	v_permlane16_swap_b32_e32 v7, v9
	global_store_dwordx4 v[174:175], v[6:9], off offset:256 sc0 sc1
	s_branch .LBB0_369

.LBB0_945:
	ds_read_b128 v[130:133], v167
	ds_read_b128 v[134:137], v167 offset:1024
	ds_read_b128 v[138:141], v167 offset:2048
	ds_read_b128 v[142:145], v167 offset:3072
	s_add_u32 s40, s38, 0xfff80080
	s_addc_u32 s41, s39, -1
	s_cmp_eq_u32 s67, 28
	s_cselect_b32 s43, s29, s41
	s_cselect_b32 s42, s63, s40
	s_cselect_b32 s41, s27, s66
	s_cselect_b32 s40, s64, s65
	v_lshl_add_u64 v[158:159], s[38:39], 0, v[150:151]
	s_add_i32 m0, s37, 0xc000
	ds_read_b128 v[172:175], v170
	ds_read_b128 v[176:179], v170 offset:1024
	ds_read_b128 v[180:183], v170 offset:2048
	ds_read_b128 v[184:187], v170 offset:3072
	ds_read_b128 v[188:191], v170 offset:4096
	ds_read_b128 v[192:195], v170 offset:5120
	ds_read_b128 v[196:199], v170 offset:6144
	ds_read_b128 v[200:203], v170 offset:7168
	global_load_lds_dwordx4 v[158:159], off
	v_lshl_add_u64 v[158:159], s[38:39], 0, v[152:153]
	s_add_i32 m0, s37, 0xe000
	s_nop 0
	global_load_lds_dwordx4 v[158:159], off
	s_waitcnt lgkmcnt(8)
	s_barrier
	s_waitcnt lgkmcnt(0)
	s_setprio 1
	s_waitcnt lgkmcnt(0)
	v_mfma_f32_16x16x32_bf16 v[126:129], v[130:133], v[172:175], v[126:129]
	v_mfma_f32_16x16x32_bf16 v[122:125], v[138:141], v[172:175], v[122:125]
	v_mfma_f32_16x16x32_bf16 v[114:117], v[130:133], v[180:183], v[114:117]
	v_mfma_f32_16x16x32_bf16 v[106:109], v[138:141], v[180:183], v[106:109]
	v_mfma_f32_16x16x32_bf16 v[98:101], v[130:133], v[188:191], v[98:101]
	v_mfma_f32_16x16x32_bf16 v[90:93], v[138:141], v[188:191], v[90:93]
	v_mfma_f32_16x16x32_bf16 v[82:85], v[130:133], v[196:199], v[82:85]
	v_mfma_f32_16x16x32_bf16 v[74:77], v[138:141], v[196:199], v[74:77]
	v_mfma_f32_16x16x32_bf16 v[126:129], v[134:137], v[176:179], v[126:129]
	v_mfma_f32_16x16x32_bf16 v[122:125], v[142:145], v[176:179], v[122:125]
	v_mfma_f32_16x16x32_bf16 v[114:117], v[134:137], v[184:187], v[114:117]
	v_mfma_f32_16x16x32_bf16 v[106:109], v[142:145], v[184:187], v[106:109]
	v_mfma_f32_16x16x32_bf16 v[98:101], v[134:137], v[192:195], v[98:101]
	v_mfma_f32_16x16x32_bf16 v[90:93], v[142:145], v[192:195], v[90:93]
	v_mfma_f32_16x16x32_bf16 v[82:85], v[134:137], v[200:203], v[82:85]
	v_mfma_f32_16x16x32_bf16 v[74:77], v[142:145], v[200:203], v[74:77]
	s_setprio 0
	s_barrier
	s_add_i32 s68, s59, s47
	v_lshl_add_u64 v[158:159], s[40:41], 0, v[146:147]
	s_mov_b32 m0, s68
	ds_read_b128 v[204:207], v171
	ds_read_b128 v[208:211], v171 offset:1024
	ds_read_b128 v[212:215], v171 offset:2048
	ds_read_b128 v[216:219], v171 offset:3072
	global_load_lds_dwordx4 v[158:159], off
	v_lshl_add_u64 v[168:169], s[40:41], 0, v[148:149]
	s_add_i32 m0, s68, 0x2000
	s_nop 0
	global_load_lds_dwordx4 v[168:169], off
	s_barrier
	s_waitcnt lgkmcnt(0)
	s_setprio 1
	s_waitcnt lgkmcnt(0)
	v_mfma_f32_16x16x32_bf16 v[118:121], v[204:207], v[172:175], v[118:121]
	v_mfma_f32_16x16x32_bf16 v[110:113], v[212:215], v[172:175], v[110:113]
	v_mfma_f32_16x16x32_bf16 v[102:105], v[204:207], v[180:183], v[102:105]
	v_mfma_f32_16x16x32_bf16 v[94:97], v[212:215], v[180:183], v[94:97]
	v_mfma_f32_16x16x32_bf16 v[86:89], v[204:207], v[188:191], v[86:89]
	v_mfma_f32_16x16x32_bf16 v[78:81], v[212:215], v[188:191], v[78:81]
	v_mfma_f32_16x16x32_bf16 v[70:73], v[204:207], v[196:199], v[70:73]
	v_mfma_f32_16x16x32_bf16 v[66:69], v[212:215], v[196:199], v[66:69]
	v_mfma_f32_16x16x32_bf16 v[118:121], v[208:211], v[176:179], v[118:121]
	v_mfma_f32_16x16x32_bf16 v[110:113], v[216:219], v[176:179], v[110:113]
	v_mfma_f32_16x16x32_bf16 v[102:105], v[208:211], v[184:187], v[102:105]
	v_mfma_f32_16x16x32_bf16 v[94:97], v[216:219], v[184:187], v[94:97]
	v_mfma_f32_16x16x32_bf16 v[86:89], v[208:211], v[192:195], v[86:89]
	v_mfma_f32_16x16x32_bf16 v[78:81], v[216:219], v[192:195], v[78:81]
	v_mfma_f32_16x16x32_bf16 v[70:73], v[208:211], v[200:203], v[70:73]
	v_mfma_f32_16x16x32_bf16 v[66:69], v[216:219], v[200:203], v[66:69]
	s_setprio 0
	s_mov_b32 m0, s37
	v_lshl_add_u64 v[220:221], s[42:43], 0, v[146:147]
	s_barrier
	ds_read_b128 v[172:175], v170 offset:16384
	ds_read_b128 v[176:179], v170 offset:17408
	ds_read_b128 v[180:183], v170 offset:18432
	ds_read_b128 v[184:187], v170 offset:19456
	ds_read_b128 v[188:191], v170 offset:20480
	ds_read_b128 v[192:195], v170 offset:21504
	ds_read_b128 v[196:199], v170 offset:22528
	ds_read_b128 v[200:203], v170 offset:23552
	global_load_lds_dwordx4 v[220:221], off
	v_lshl_add_u64 v[222:223], s[42:43], 0, v[148:149]
	s_mov_b32 m0, s50
	s_nop 0
	global_load_lds_dwordx4 v[222:223], off
	s_barrier
	s_waitcnt lgkmcnt(0)
	s_setprio 1
	s_waitcnt lgkmcnt(0)
	v_mfma_f32_16x16x32_bf16 v[62:65], v[130:133], v[172:175], v[62:65]
	v_mfma_f32_16x16x32_bf16 v[58:61], v[138:141], v[172:175], v[58:61]
	v_mfma_f32_16x16x32_bf16 v[54:57], v[130:133], v[180:183], v[54:57]
	v_mfma_f32_16x16x32_bf16 v[46:49], v[138:141], v[180:183], v[46:49]
	v_mfma_f32_16x16x32_bf16 v[38:41], v[130:133], v[188:191], v[38:41]
	v_mfma_f32_16x16x32_bf16 v[30:33], v[138:141], v[188:191], v[30:33]
	v_mfma_f32_16x16x32_bf16 v[22:25], v[130:133], v[196:199], v[22:25]
	v_mfma_f32_16x16x32_bf16 v[14:17], v[138:141], v[196:199], v[14:17]
	v_mfma_f32_16x16x32_bf16 v[62:65], v[134:137], v[176:179], v[62:65]
	v_mfma_f32_16x16x32_bf16 v[58:61], v[142:145], v[176:179], v[58:61]
	v_mfma_f32_16x16x32_bf16 v[54:57], v[134:137], v[184:187], v[54:57]
	v_mfma_f32_16x16x32_bf16 v[46:49], v[142:145], v[184:187], v[46:49]
	v_mfma_f32_16x16x32_bf16 v[38:41], v[134:137], v[192:195], v[38:41]
	v_mfma_f32_16x16x32_bf16 v[30:33], v[142:145], v[192:195], v[30:33]
	v_mfma_f32_16x16x32_bf16 v[22:25], v[134:137], v[200:203], v[22:25]
	v_mfma_f32_16x16x32_bf16 v[14:17], v[142:145], v[200:203], v[14:17]
	s_setprio 0
	s_barrier
	s_add_u32 s68, s40, 0x80000
	s_addc_u32 s69, s41, 0
	s_add_i32 s70, s60, s47
	v_lshl_add_u64 v[130:131], s[68:69], 0, v[146:147]
	s_mov_b32 m0, s70
	s_nop 0
	global_load_lds_dwordx4 v[130:131], off
	v_lshl_add_u64 v[130:131], s[68:69], 0, v[148:149]
	s_add_i32 m0, s70, 0x2000
	s_nop 0
	global_load_lds_dwordx4 v[130:131], off
	s_waitcnt vmcnt(6)
	s_barrier
	s_setprio 1
	v_mfma_f32_16x16x32_bf16 v[50:53], v[204:207], v[172:175], v[50:53]
	v_mfma_f32_16x16x32_bf16 v[42:45], v[212:215], v[172:175], v[42:45]
	v_mfma_f32_16x16x32_bf16 v[34:37], v[204:207], v[180:183], v[34:37]
	v_mfma_f32_16x16x32_bf16 v[26:29], v[212:215], v[180:183], v[26:29]
	v_mfma_f32_16x16x32_bf16 v[18:21], v[204:207], v[188:191], v[18:21]
	v_mfma_f32_16x16x32_bf16 v[10:13], v[212:215], v[188:191], v[10:13]
	v_mfma_f32_16x16x32_bf16 v[6:9], v[204:207], v[196:199], v[6:9]
	v_mfma_f32_16x16x32_bf16 v[2:5], v[212:215], v[196:199], v[2:5]
	v_mfma_f32_16x16x32_bf16 v[50:53], v[208:211], v[176:179], v[50:53]
	v_mfma_f32_16x16x32_bf16 v[42:45], v[216:219], v[176:179], v[42:45]
	v_mfma_f32_16x16x32_bf16 v[34:37], v[208:211], v[184:187], v[34:37]
	v_mfma_f32_16x16x32_bf16 v[26:29], v[216:219], v[184:187], v[26:29]
	v_mfma_f32_16x16x32_bf16 v[18:21], v[208:211], v[192:195], v[18:21]
	v_mfma_f32_16x16x32_bf16 v[10:13], v[216:219], v[192:195], v[10:13]
	v_mfma_f32_16x16x32_bf16 v[6:9], v[208:211], v[200:203], v[6:9]
	v_mfma_f32_16x16x32_bf16 v[2:5], v[216:219], v[200:203], v[2:5]
	s_setprio 0
	s_add_i32 s68, 0, 0x18000
	v_add_u32_e32 v142, s68, v164
	s_barrier
	ds_read_b128 v[130:133], v142
	ds_read_b128 v[134:137], v142 offset:1024
	ds_read_b128 v[138:141], v142 offset:2048
	ds_read_b128 v[142:145], v142 offset:3072
	s_add_u32 s42, s42, 0x80000
	s_addc_u32 s43, s43, 0
	s_mov_b32 m0, s51
	v_lshl_add_u64 v[204:205], s[42:43], 0, v[146:147]
	ds_read_b128 v[172:175], v170 offset:32768
	ds_read_b128 v[176:179], v170 offset:33792
	ds_read_b128 v[180:183], v170 offset:34816
	ds_read_b128 v[184:187], v170 offset:35840
	ds_read_b128 v[188:191], v170 offset:36864
	ds_read_b128 v[192:195], v170 offset:37888
	ds_read_b128 v[196:199], v170 offset:38912
	ds_read_b128 v[200:203], v170 offset:39936
	global_load_lds_dwordx4 v[204:205], off
	v_lshl_add_u64 v[204:205], s[42:43], 0, v[148:149]
	s_mov_b32 m0, s52
	s_nop 0
	global_load_lds_dwordx4 v[204:205], off
	s_waitcnt lgkmcnt(8)
	s_barrier
	s_waitcnt lgkmcnt(0)
	s_setprio 1
	s_waitcnt lgkmcnt(0)
	v_mfma_f32_16x16x32_bf16 v[126:129], v[130:133], v[172:175], v[126:129]
	v_mfma_f32_16x16x32_bf16 v[122:125], v[138:141], v[172:175], v[122:125]
	v_mfma_f32_16x16x32_bf16 v[114:117], v[130:133], v[180:183], v[114:117]
	v_mfma_f32_16x16x32_bf16 v[106:109], v[138:141], v[180:183], v[106:109]
	v_mfma_f32_16x16x32_bf16 v[98:101], v[130:133], v[188:191], v[98:101]
	v_mfma_f32_16x16x32_bf16 v[90:93], v[138:141], v[188:191], v[90:93]
	v_mfma_f32_16x16x32_bf16 v[82:85], v[130:133], v[196:199], v[82:85]
	v_mfma_f32_16x16x32_bf16 v[74:77], v[138:141], v[196:199], v[74:77]
	v_mfma_f32_16x16x32_bf16 v[126:129], v[134:137], v[176:179], v[126:129]
	v_mfma_f32_16x16x32_bf16 v[122:125], v[142:145], v[176:179], v[122:125]
	v_mfma_f32_16x16x32_bf16 v[114:117], v[134:137], v[184:187], v[114:117]
	v_mfma_f32_16x16x32_bf16 v[106:109], v[142:145], v[184:187], v[106:109]
	v_mfma_f32_16x16x32_bf16 v[98:101], v[134:137], v[192:195], v[98:101]
	v_mfma_f32_16x16x32_bf16 v[90:93], v[142:145], v[192:195], v[90:93]
	v_mfma_f32_16x16x32_bf16 v[82:85], v[134:137], v[200:203], v[82:85]
	v_mfma_f32_16x16x32_bf16 v[74:77], v[142:145], v[200:203], v[74:77]
	s_setprio 0
	s_barrier
	s_add_i32 s42, 0, 0x1c000
	s_add_i32 s43, s68, s47
	v_add_u32_e32 v166, s42, v164
	v_lshl_add_u64 v[158:159], v[158:159], 0, s[14:15]
	s_mov_b32 m0, s43
	ds_read_b128 v[204:207], v166
	ds_read_b128 v[208:211], v166 offset:1024
	ds_read_b128 v[212:215], v166 offset:2048
	ds_read_b128 v[216:219], v166 offset:3072
	global_load_lds_dwordx4 v[158:159], off
	v_lshl_add_u64 v[158:159], v[168:169], 0, s[14:15]
	s_add_i32 m0, s43, 0x2000
	s_nop 0
	global_load_lds_dwordx4 v[158:159], off
	s_barrier
	s_waitcnt lgkmcnt(0)
	s_setprio 1
	s_waitcnt lgkmcnt(0)
	v_mfma_f32_16x16x32_bf16 v[118:121], v[204:207], v[172:175], v[118:121]
	v_mfma_f32_16x16x32_bf16 v[110:113], v[212:215], v[172:175], v[110:113]
	v_mfma_f32_16x16x32_bf16 v[102:105], v[204:207], v[180:183], v[102:105]
	v_mfma_f32_16x16x32_bf16 v[94:97], v[212:215], v[180:183], v[94:97]
	v_mfma_f32_16x16x32_bf16 v[86:89], v[204:207], v[188:191], v[86:89]
	v_mfma_f32_16x16x32_bf16 v[78:81], v[212:215], v[188:191], v[78:81]
	v_mfma_f32_16x16x32_bf16 v[70:73], v[204:207], v[196:199], v[70:73]
	v_mfma_f32_16x16x32_bf16 v[66:69], v[212:215], v[196:199], v[66:69]
	v_mfma_f32_16x16x32_bf16 v[118:121], v[208:211], v[176:179], v[118:121]
	v_mfma_f32_16x16x32_bf16 v[110:113], v[216:219], v[176:179], v[110:113]
	v_mfma_f32_16x16x32_bf16 v[102:105], v[208:211], v[184:187], v[102:105]
	v_mfma_f32_16x16x32_bf16 v[94:97], v[216:219], v[184:187], v[94:97]
	v_mfma_f32_16x16x32_bf16 v[86:89], v[208:211], v[192:195], v[86:89]
	v_mfma_f32_16x16x32_bf16 v[78:81], v[216:219], v[192:195], v[78:81]
	v_mfma_f32_16x16x32_bf16 v[70:73], v[208:211], v[200:203], v[70:73]
	v_mfma_f32_16x16x32_bf16 v[66:69], v[216:219], v[200:203], v[66:69]
	s_setprio 0
	s_mov_b32 m0, s57
	v_lshl_add_u64 v[158:159], v[220:221], 0, s[14:15]
	s_barrier
	ds_read_b128 v[172:175], v170 offset:49152
	ds_read_b128 v[176:179], v170 offset:50176
	ds_read_b128 v[180:183], v170 offset:51200
	ds_read_b128 v[184:187], v170 offset:52224
	ds_read_b128 v[188:191], v170 offset:53248
	ds_read_b128 v[192:195], v170 offset:54272
	ds_read_b128 v[196:199], v170 offset:55296
	ds_read_b128 v[200:203], v170 offset:56320
	global_load_lds_dwordx4 v[158:159], off
	v_lshl_add_u64 v[158:159], v[222:223], 0, s[14:15]
	s_mov_b32 m0, s58
	s_nop 0
	global_load_lds_dwordx4 v[158:159], off
	s_barrier
	s_waitcnt lgkmcnt(0)
	s_setprio 1
	s_waitcnt lgkmcnt(0)
	v_mfma_f32_16x16x32_bf16 v[62:65], v[130:133], v[172:175], v[62:65]
	v_mfma_f32_16x16x32_bf16 v[58:61], v[138:141], v[172:175], v[58:61]
	v_mfma_f32_16x16x32_bf16 v[54:57], v[130:133], v[180:183], v[54:57]
	v_mfma_f32_16x16x32_bf16 v[46:49], v[138:141], v[180:183], v[46:49]
	v_mfma_f32_16x16x32_bf16 v[38:41], v[130:133], v[188:191], v[38:41]
	v_mfma_f32_16x16x32_bf16 v[30:33], v[138:141], v[188:191], v[30:33]
	v_mfma_f32_16x16x32_bf16 v[22:25], v[130:133], v[196:199], v[22:25]
	v_mfma_f32_16x16x32_bf16 v[14:17], v[138:141], v[196:199], v[14:17]
	v_mfma_f32_16x16x32_bf16 v[62:65], v[134:137], v[176:179], v[62:65]
	v_mfma_f32_16x16x32_bf16 v[58:61], v[142:145], v[176:179], v[58:61]
	v_mfma_f32_16x16x32_bf16 v[54:57], v[134:137], v[184:187], v[54:57]
	v_mfma_f32_16x16x32_bf16 v[46:49], v[142:145], v[184:187], v[46:49]
	v_mfma_f32_16x16x32_bf16 v[38:41], v[134:137], v[192:195], v[38:41]
	v_mfma_f32_16x16x32_bf16 v[30:33], v[142:145], v[192:195], v[30:33]
	v_mfma_f32_16x16x32_bf16 v[22:25], v[134:137], v[200:203], v[22:25]
	v_mfma_f32_16x16x32_bf16 v[14:17], v[142:145], v[200:203], v[14:17]
	s_setprio 0
	s_barrier
	s_add_u32 s40, s40, 0x80080
	s_addc_u32 s41, s41, 0
	s_add_i32 s42, s42, s47
	v_lshl_add_u64 v[130:131], s[40:41], 0, v[146:147]
	s_mov_b32 m0, s42
	s_nop 0
	global_load_lds_dwordx4 v[130:131], off
	v_lshl_add_u64 v[130:131], s[40:41], 0, v[148:149]
	s_add_i32 m0, s42, 0x2000
	s_nop 0
	global_load_lds_dwordx4 v[130:131], off
	s_waitcnt vmcnt(6)
	s_barrier
	s_setprio 1
	v_mfma_f32_16x16x32_bf16 v[50:53], v[204:207], v[172:175], v[50:53]
	v_mfma_f32_16x16x32_bf16 v[42:45], v[212:215], v[172:175], v[42:45]
	v_mfma_f32_16x16x32_bf16 v[34:37], v[204:207], v[180:183], v[34:37]
	v_mfma_f32_16x16x32_bf16 v[26:29], v[212:215], v[180:183], v[26:29]
	v_mfma_f32_16x16x32_bf16 v[18:21], v[204:207], v[188:191], v[18:21]
	v_mfma_f32_16x16x32_bf16 v[10:13], v[212:215], v[188:191], v[10:13]
	v_mfma_f32_16x16x32_bf16 v[6:9], v[204:207], v[196:199], v[6:9]
	v_mfma_f32_16x16x32_bf16 v[2:5], v[212:215], v[196:199], v[2:5]
	v_mfma_f32_16x16x32_bf16 v[50:53], v[208:211], v[176:179], v[50:53]
	v_mfma_f32_16x16x32_bf16 v[42:45], v[216:219], v[176:179], v[42:45]
	v_mfma_f32_16x16x32_bf16 v[34:37], v[208:211], v[184:187], v[34:37]
	v_mfma_f32_16x16x32_bf16 v[26:29], v[216:219], v[184:187], v[26:29]
	v_mfma_f32_16x16x32_bf16 v[18:21], v[208:211], v[192:195], v[18:21]
	v_mfma_f32_16x16x32_bf16 v[10:13], v[216:219], v[192:195], v[10:13]
	v_mfma_f32_16x16x32_bf16 v[6:9], v[208:211], v[200:203], v[6:9]
	v_mfma_f32_16x16x32_bf16 v[2:5], v[216:219], v[200:203], v[2:5]
	s_setprio 0
	s_add_i32 s67, s67, 2
	s_add_u32 s38, s38, 0x100
	s_addc_u32 s39, s39, 0
	s_add_u32 s65, s65, 0x100
	s_addc_u32 s66, s66, 0
	s_cmp_gt_u32 s67, 29
	s_barrier
	s_cbranch_scc0 .LBB0_945
	s_lshl_b32 s27, s36, 8
	s_add_i32 s38, s27, 0xffffc000
	s_lshr_b32 s38, s38, 4
	s_ashr_i32 s29, s36, 4
	s_or_b32 s38, s38, 4
	s_cmp_lt_i32 s36, 64
	s_cselect_b32 s29, s29, s38
	v_lshl_or_b32 v130, s62, 8, v165
	s_mul_hi_i32 s36, s29, 0xc000
	s_mul_i32 s29, s29, 0xc000
	v_add_u32_e32 v168, s27, v163
	s_add_u32 s38, s10, s29
	v_ashrrev_i32_e32 v131, 31, v130
	v_ashrrev_i32_e32 v169, 31, v168
	s_addc_u32 s39, s11, s36
	v_lshlrev_b64 v[158:159], 2, v[130:131]
	v_lshlrev_b64 v[238:239], 13, v[168:169]
	v_or_b32_e32 v188, 16, v168
	v_or_b32_e32 v204, 32, v168
	v_or_b32_e32 v168, 48, v168
	v_lshl_add_u64 v[130:131], s[38:39], 0, v[158:159]
	v_ashrrev_i32_e32 v189, 31, v188
	v_ashrrev_i32_e32 v205, 31, v204
	v_ashrrev_i32_e32 v169, 31, v168
	v_lshl_add_u64 v[132:133], v[130:131], 0, s[16:17]
	v_add_co_u32_e32 v130, vcc, s61, v130
	v_lshl_add_u64 v[236:237], s[6:7], 0, v[158:159]
	v_lshlrev_b64 v[240:241], 13, v[188:189]
	v_lshlrev_b64 v[242:243], 13, v[204:205]
	v_lshlrev_b64 v[168:169], 13, v[168:169]
	v_addc_co_u32_e32 v131, vcc, 0, v131, vcc
	v_lshl_add_u64 v[184:185], v[236:237], 0, v[238:239]
	v_lshl_add_u64 v[200:201], v[236:237], 0, v[240:241]
	v_lshl_add_u64 v[216:217], v[236:237], 0, v[242:243]
	v_lshl_add_u64 v[232:233], v[236:237], 0, v[168:169]
	global_load_dwordx4 v[138:141], v[132:133], off offset:64
	global_load_dwordx4 v[134:137], v[132:133], off offset:512
	global_load_dwordx4 v[142:145], v[130:131], off
	s_nop 0
	global_load_dwordx4 v[130:133], v[132:133], off offset:576
	s_nop 0
	global_load_dwordx4 v[172:175], v[184:185], off
	global_load_dwordx4 v[176:179], v[184:185], off offset:64
	global_load_dwordx4 v[180:183], v[184:185], off offset:512
	s_nop 0
	global_load_dwordx4 v[184:187], v[184:185], off offset:576
	s_nop 0
	global_load_dwordx4 v[188:191], v[200:201], off
	global_load_dwordx4 v[192:195], v[200:201], off offset:64
	global_load_dwordx4 v[196:199], v[200:201], off offset:512
	s_nop 0
	global_load_dwordx4 v[200:203], v[200:201], off offset:576
	s_nop 0
	global_load_dwordx4 v[204:207], v[216:217], off
	global_load_dwordx4 v[208:211], v[216:217], off offset:64
	global_load_dwordx4 v[212:215], v[216:217], off offset:512
	s_nop 0
	global_load_dwordx4 v[216:219], v[216:217], off offset:576
	s_nop 0
	global_load_dwordx4 v[220:223], v[232:233], off
	global_load_dwordx4 v[224:227], v[232:233], off offset:64
	global_load_dwordx4 v[228:231], v[232:233], off offset:512
	s_nop 0
	global_load_dwordx4 v[232:235], v[232:233], off offset:576
	v_lshl_add_u64 v[244:245], s[8:9], 0, v[238:239]
	v_lshl_add_u64 v[244:245], v[244:245], 0, v[158:159]
	s_waitcnt vmcnt(0)
	v_pk_fma_f32 v[112:113], v[112:113], v[132:133], v[186:187]
	v_pk_fma_f32 v[110:111], v[110:111], v[130:131], v[184:185]
	v_pk_fma_f32 v[120:121], v[120:121], v[136:137], v[182:183]
	v_pk_fma_f32 v[118:119], v[118:119], v[134:135], v[180:181]
	global_store_dwordx4 v[244:245], v[110:113], off offset:576 sc0 sc1
	global_store_dwordx4 v[244:245], v[118:121], off offset:512 sc0 sc1
	v_pk_fma_f32 v[96:97], v[96:97], v[132:133], v[202:203]
	v_lshl_add_u64 v[110:111], s[8:9], 0, v[240:241]
	v_lshl_add_u64 v[118:119], v[110:111], 0, v[158:159]
	v_pk_fma_f32 v[94:95], v[94:95], v[130:131], v[200:201]
	v_pk_fma_f32 v[104:105], v[104:105], v[136:137], v[198:199]
	v_pk_fma_f32 v[102:103], v[102:103], v[134:135], v[196:197]
	global_store_dwordx4 v[118:119], v[94:97], off offset:576 sc0 sc1
	global_store_dwordx4 v[118:119], v[102:105], off offset:512 sc0 sc1
	v_pk_fma_f32 v[80:81], v[80:81], v[132:133], v[218:219]
	v_lshl_add_u64 v[94:95], s[8:9], 0, v[242:243]
	v_lshl_add_u64 v[102:103], v[94:95], 0, v[158:159]
	v_pk_fma_f32 v[78:79], v[78:79], v[130:131], v[216:217]
	v_pk_fma_f32 v[88:89], v[88:89], v[136:137], v[214:215]
	v_pk_fma_f32 v[86:87], v[86:87], v[134:135], v[212:213]
	global_store_dwordx4 v[102:103], v[78:81], off offset:576 sc0 sc1
	v_pk_fma_f32 v[128:129], v[128:129], v[144:145], v[174:175]
	v_pk_fma_f32 v[126:127], v[126:127], v[142:143], v[172:173]
	v_lshl_add_u64 v[78:79], s[8:9], 0, v[168:169]
	v_pk_fma_f32 v[124:125], v[124:125], v[140:141], v[178:179]
	v_pk_fma_f32 v[122:123], v[122:123], v[138:139], v[176:177]
	v_pk_fma_f32 v[112:113], v[116:117], v[144:145], v[190:191]
	v_pk_fma_f32 v[110:111], v[114:115], v[142:143], v[188:189]
	v_pk_fma_f32 v[108:109], v[108:109], v[140:141], v[194:195]
	v_pk_fma_f32 v[106:107], v[106:107], v[138:139], v[192:193]
	v_pk_fma_f32 v[96:97], v[100:101], v[144:145], v[206:207]
	v_pk_fma_f32 v[94:95], v[98:99], v[142:143], v[204:205]
	v_pk_fma_f32 v[92:93], v[92:93], v[140:141], v[210:211]
	v_pk_fma_f32 v[90:91], v[90:91], v[138:139], v[208:209]
	global_store_dwordx4 v[102:103], v[86:89], off offset:512 sc0 sc1
	v_pk_fma_f32 v[80:81], v[84:85], v[144:145], v[222:223]
	v_pk_fma_f32 v[76:77], v[76:77], v[140:141], v[226:227]
	v_lshl_add_u64 v[86:87], v[78:79], 0, v[158:159]
	v_pk_fma_f32 v[78:79], v[82:83], v[142:143], v[220:221]
	v_pk_fma_f32 v[74:75], v[74:75], v[138:139], v[224:225]
	v_pk_fma_f32 v[72:73], v[72:73], v[136:137], v[230:231]
	v_pk_fma_f32 v[70:71], v[70:71], v[134:135], v[228:229]
	v_pk_fma_f32 v[68:69], v[68:69], v[132:133], v[234:235]
	v_pk_fma_f32 v[66:67], v[66:67], v[130:131], v[232:233]
	v_lshl_add_u64 v[168:169], v[238:239], 0, s[18:19]
	v_lshl_add_u64 v[172:173], v[238:239], 0, s[20:21]
	v_lshl_add_u64 v[174:175], v[238:239], 0, s[22:23]
	v_lshl_add_u64 v[176:177], v[238:239], 0, s[24:25]
	global_store_dwordx4 v[244:245], v[126:129], off sc0 sc1
	global_store_dwordx4 v[244:245], v[122:125], off offset:64 sc0 sc1
	global_store_dwordx4 v[118:119], v[110:113], off sc0 sc1
	global_store_dwordx4 v[118:119], v[106:109], off offset:64 sc0 sc1
	global_store_dwordx4 v[102:103], v[94:97], off sc0 sc1
	global_store_dwordx4 v[102:103], v[90:93], off offset:64 sc0 sc1
	global_store_dwordx4 v[86:87], v[78:81], off sc0 sc1
	global_store_dwordx4 v[86:87], v[74:77], off offset:64 sc0 sc1
	global_store_dwordx4 v[86:87], v[70:73], off offset:512 sc0 sc1
	global_store_dwordx4 v[86:87], v[66:69], off offset:576 sc0 sc1
	v_lshl_add_u64 v[78:79], v[236:237], 0, v[168:169]
	v_lshl_add_u64 v[94:95], v[236:237], 0, v[172:173]
	v_lshl_add_u64 v[110:111], v[236:237], 0, v[174:175]
	v_lshl_add_u64 v[126:127], v[236:237], 0, v[176:177]
	global_load_dwordx4 v[66:69], v[78:79], off
	global_load_dwordx4 v[70:73], v[78:79], off offset:64
	global_load_dwordx4 v[74:77], v[78:79], off offset:512
	s_nop 0
	global_load_dwordx4 v[78:81], v[78:79], off offset:576
	s_nop 0
	global_load_dwordx4 v[82:85], v[94:95], off
	global_load_dwordx4 v[86:89], v[94:95], off offset:64
	global_load_dwordx4 v[90:93], v[94:95], off offset:512
	s_nop 0
	global_load_dwordx4 v[94:97], v[94:95], off offset:576
	s_nop 0
	global_load_dwordx4 v[98:101], v[110:111], off
	global_load_dwordx4 v[102:105], v[110:111], off offset:64
	global_load_dwordx4 v[106:109], v[110:111], off offset:512
	s_nop 0
	global_load_dwordx4 v[110:113], v[110:111], off offset:576
	s_nop 0
	global_load_dwordx4 v[114:117], v[126:127], off
	global_load_dwordx4 v[118:121], v[126:127], off offset:64
	global_load_dwordx4 v[122:125], v[126:127], off offset:512
	s_nop 0
	global_load_dwordx4 v[126:129], v[126:127], off offset:576
	v_lshl_add_u64 v[168:169], s[8:9], 0, v[168:169]
	v_lshl_add_u64 v[168:169], v[168:169], 0, v[158:159]
	s_waitcnt vmcnt(0)
	v_pk_fma_f32 v[44:45], v[44:45], v[132:133], v[80:81]
	v_pk_fma_f32 v[42:43], v[42:43], v[130:131], v[78:79]
	v_pk_fma_f32 v[52:53], v[52:53], v[136:137], v[76:77]
	v_pk_fma_f32 v[50:51], v[50:51], v[134:135], v[74:75]
	global_store_dwordx4 v[168:169], v[42:45], off offset:576 sc0 sc1
	global_store_dwordx4 v[168:169], v[50:53], off offset:512 sc0 sc1
	v_pk_fma_f32 v[28:29], v[28:29], v[132:133], v[96:97]
	v_lshl_add_u64 v[42:43], s[8:9], 0, v[172:173]
	v_lshl_add_u64 v[50:51], v[42:43], 0, v[158:159]
	v_pk_fma_f32 v[26:27], v[26:27], v[130:131], v[94:95]
	v_pk_fma_f32 v[36:37], v[36:37], v[136:137], v[92:93]
	v_pk_fma_f32 v[34:35], v[34:35], v[134:135], v[90:91]
	global_store_dwordx4 v[50:51], v[26:29], off offset:576 sc0 sc1
	global_store_dwordx4 v[50:51], v[34:37], off offset:512 sc0 sc1
	v_pk_fma_f32 v[12:13], v[12:13], v[132:133], v[112:113]
	v_lshl_add_u64 v[26:27], s[8:9], 0, v[174:175]
	v_lshl_add_u64 v[34:35], v[26:27], 0, v[158:159]
	v_pk_fma_f32 v[10:11], v[10:11], v[130:131], v[110:111]
	v_pk_fma_f32 v[20:21], v[20:21], v[136:137], v[108:109]
	v_pk_fma_f32 v[18:19], v[18:19], v[134:135], v[106:107]
	global_store_dwordx4 v[34:35], v[10:13], off offset:576 sc0 sc1
	v_pk_fma_f32 v[44:45], v[56:57], v[144:145], v[84:85]
	v_pk_fma_f32 v[42:43], v[54:55], v[142:143], v[82:83]
	v_lshl_add_u64 v[10:11], s[8:9], 0, v[176:177]
	v_pk_fma_f32 v[28:29], v[40:41], v[144:145], v[100:101]
	v_pk_fma_f32 v[26:27], v[38:39], v[142:143], v[98:99]
	global_store_dwordx4 v[34:35], v[18:21], off offset:512 sc0 sc1
	v_pk_fma_f32 v[12:13], v[24:25], v[144:145], v[116:117]
	v_pk_fma_f32 v[64:65], v[64:65], v[144:145], v[68:69]
	v_lshl_add_u64 v[18:19], v[10:11], 0, v[158:159]
	v_pk_fma_f32 v[10:11], v[22:23], v[142:143], v[114:115]
	v_pk_fma_f32 v[62:63], v[62:63], v[142:143], v[66:67]
	v_pk_fma_f32 v[60:61], v[60:61], v[140:141], v[72:73]
	v_pk_fma_f32 v[58:59], v[58:59], v[138:139], v[70:71]
	global_store_dwordx4 v[50:51], v[42:45], off sc0 sc1
	global_store_dwordx4 v[34:35], v[26:29], off sc0 sc1
	global_store_dwordx4 v[18:19], v[10:13], off sc0 sc1
	v_pk_fma_f32 v[44:45], v[48:49], v[140:141], v[88:89]
	v_pk_fma_f32 v[42:43], v[46:47], v[138:139], v[86:87]
	v_pk_fma_f32 v[28:29], v[32:33], v[140:141], v[104:105]
	v_pk_fma_f32 v[26:27], v[30:31], v[138:139], v[102:103]
	v_pk_fma_f32 v[12:13], v[16:17], v[140:141], v[120:121]
	v_pk_fma_f32 v[10:11], v[14:15], v[138:139], v[118:119]
	v_pk_fma_f32 v[8:9], v[8:9], v[136:137], v[124:125]
	v_pk_fma_f32 v[6:7], v[6:7], v[134:135], v[122:123]
	v_pk_fma_f32 v[4:5], v[4:5], v[132:133], v[128:129]
	v_pk_fma_f32 v[2:3], v[2:3], v[130:131], v[126:127]
	s_and_b64 vcc, exec, s[4:5]
	s_mov_b32 s62, s26
	s_mov_b32 s36, s28
	s_mov_b64 s[40:41], s[34:35]
	s_mov_b64 s[38:39], s[30:31]
	global_store_dwordx4 v[168:169], v[62:65], off sc0 sc1
	global_store_dwordx4 v[168:169], v[58:61], off offset:64 sc0 sc1
	global_store_dwordx4 v[50:51], v[42:45], off offset:64 sc0 sc1
	global_store_dwordx4 v[34:35], v[26:29], off offset:64 sc0 sc1
	global_store_dwordx4 v[18:19], v[10:13], off offset:64 sc0 sc1
	global_store_dwordx4 v[18:19], v[6:9], off offset:512 sc0 sc1
	global_store_dwordx4 v[18:19], v[2:5], off offset:576 sc0 sc1
	s_cbranch_vccz .LBB0_938
	s_waitcnt vmcnt(0)
	s_cmpk_gt_u32 s45, 0xff
	s_cbranch_scc1 .LBB0_949
	s_barrier

.LBB0_1098:
	ds_read_b128 v[130:133], v240
	ds_read_b128 v[134:137], v240 offset:1024
	ds_read_b128 v[138:141], v240 offset:2048
	ds_read_b128 v[142:145], v240 offset:3072
	s_add_u32 s50, s48, 0xfff80080
	s_addc_u32 s51, s49, -1
	s_cmp_eq_u32 s80, 28
	s_cselect_b32 s53, s41, s51
	s_cselect_b32 s52, s47, s50
	s_cselect_b32 s51, s39, s75
	s_cselect_b32 s50, s73, s74
	v_lshl_add_u64 v[168:169], s[48:49], 0, v[166:167]
	s_add_i32 m0, s21, 0xc000
	ds_read_b128 v[146:149], v241
	ds_read_b128 v[150:153], v241 offset:1024
	ds_read_b128 v[154:157], v241 offset:2048
	ds_read_b128 v[158:161], v241 offset:3072
	ds_read_b128 v[176:179], v241 offset:4096
	ds_read_b128 v[180:183], v241 offset:5120
	ds_read_b128 v[184:187], v241 offset:6144
	ds_read_b128 v[188:191], v241 offset:7168
	global_load_lds_dwordx4 v[168:169], off
	v_lshl_add_u64 v[168:169], s[48:49], 0, v[170:171]
	s_add_i32 m0, s21, 0xe000
	s_nop 0
	global_load_lds_dwordx4 v[168:169], off
	s_waitcnt lgkmcnt(8)
	s_barrier
	s_waitcnt lgkmcnt(0)
	s_setprio 1
	s_waitcnt lgkmcnt(0)
	v_mfma_f32_16x16x32_bf16 v[126:129], v[130:133], v[146:149], v[126:129]
	v_mfma_f32_16x16x32_bf16 v[122:125], v[138:141], v[146:149], v[122:125]
	v_mfma_f32_16x16x32_bf16 v[118:121], v[130:133], v[154:157], v[118:121]
	v_mfma_f32_16x16x32_bf16 v[114:117], v[138:141], v[154:157], v[114:117]
	v_mfma_f32_16x16x32_bf16 v[106:109], v[130:133], v[176:179], v[106:109]
	v_mfma_f32_16x16x32_bf16 v[98:101], v[138:141], v[176:179], v[98:101]
	v_mfma_f32_16x16x32_bf16 v[90:93], v[130:133], v[184:187], v[90:93]
	v_mfma_f32_16x16x32_bf16 v[82:85], v[138:141], v[184:187], v[82:85]
	v_mfma_f32_16x16x32_bf16 v[126:129], v[134:137], v[150:153], v[126:129]
	v_mfma_f32_16x16x32_bf16 v[122:125], v[142:145], v[150:153], v[122:125]
	v_mfma_f32_16x16x32_bf16 v[118:121], v[134:137], v[158:161], v[118:121]
	v_mfma_f32_16x16x32_bf16 v[114:117], v[142:145], v[158:161], v[114:117]
	v_mfma_f32_16x16x32_bf16 v[106:109], v[134:137], v[180:183], v[106:109]
	v_mfma_f32_16x16x32_bf16 v[98:101], v[142:145], v[180:183], v[98:101]
	v_mfma_f32_16x16x32_bf16 v[90:93], v[134:137], v[188:191], v[90:93]
	v_mfma_f32_16x16x32_bf16 v[82:85], v[142:145], v[188:191], v[82:85]
	s_setprio 0
	s_barrier
	s_add_i32 s81, s68, s56
	v_lshl_add_u64 v[168:169], s[50:51], 0, v[162:163]
	s_mov_b32 m0, s81
	ds_read_b128 v[192:195], v242
	ds_read_b128 v[196:199], v242 offset:1024
	ds_read_b128 v[200:203], v242 offset:2048
	ds_read_b128 v[204:207], v242 offset:3072
	global_load_lds_dwordx4 v[168:169], off
	v_lshl_add_u64 v[208:209], s[50:51], 0, v[164:165]
	s_add_i32 m0, s81, 0x2000
	s_nop 0
	global_load_lds_dwordx4 v[208:209], off
	s_barrier
	s_waitcnt lgkmcnt(0)
	s_setprio 1
	s_waitcnt lgkmcnt(0)
	v_mfma_f32_16x16x32_bf16 v[110:113], v[192:195], v[146:149], v[110:113]
	v_mfma_f32_16x16x32_bf16 v[102:105], v[200:203], v[146:149], v[102:105]
	v_mfma_f32_16x16x32_bf16 v[94:97], v[192:195], v[154:157], v[94:97]
	v_mfma_f32_16x16x32_bf16 v[86:89], v[200:203], v[154:157], v[86:89]
	v_mfma_f32_16x16x32_bf16 v[78:81], v[192:195], v[176:179], v[78:81]
	v_mfma_f32_16x16x32_bf16 v[74:77], v[200:203], v[176:179], v[74:77]
	v_mfma_f32_16x16x32_bf16 v[70:73], v[192:195], v[184:187], v[70:73]
	v_mfma_f32_16x16x32_bf16 v[66:69], v[200:203], v[184:187], v[66:69]
	v_mfma_f32_16x16x32_bf16 v[110:113], v[196:199], v[150:153], v[110:113]
	v_mfma_f32_16x16x32_bf16 v[102:105], v[204:207], v[150:153], v[102:105]
	v_mfma_f32_16x16x32_bf16 v[94:97], v[196:199], v[158:161], v[94:97]
	v_mfma_f32_16x16x32_bf16 v[86:89], v[204:207], v[158:161], v[86:89]
	v_mfma_f32_16x16x32_bf16 v[78:81], v[196:199], v[180:183], v[78:81]
	v_mfma_f32_16x16x32_bf16 v[74:77], v[204:207], v[180:183], v[74:77]
	v_mfma_f32_16x16x32_bf16 v[70:73], v[196:199], v[188:191], v[70:73]
	v_mfma_f32_16x16x32_bf16 v[66:69], v[204:207], v[188:191], v[66:69]
	s_setprio 0
	s_mov_b32 m0, s21
	v_lshl_add_u64 v[210:211], s[52:53], 0, v[162:163]
	s_barrier
	ds_read_b128 v[146:149], v241 offset:16384
	ds_read_b128 v[150:153], v241 offset:17408
	ds_read_b128 v[154:157], v241 offset:18432
	ds_read_b128 v[158:161], v241 offset:19456
	ds_read_b128 v[176:179], v241 offset:20480
	ds_read_b128 v[180:183], v241 offset:21504
	ds_read_b128 v[184:187], v241 offset:22528
	ds_read_b128 v[188:191], v241 offset:23552
	global_load_lds_dwordx4 v[210:211], off
	v_lshl_add_u64 v[212:213], s[52:53], 0, v[164:165]
	s_mov_b32 m0, s59
	s_nop 0
	global_load_lds_dwordx4 v[212:213], off
	s_barrier
	s_waitcnt lgkmcnt(0)
	s_setprio 1
	s_waitcnt lgkmcnt(0)
	v_mfma_f32_16x16x32_bf16 v[62:65], v[130:133], v[146:149], v[62:65]
	v_mfma_f32_16x16x32_bf16 v[58:61], v[138:141], v[146:149], v[58:61]
	v_mfma_f32_16x16x32_bf16 v[54:57], v[130:133], v[154:157], v[54:57]
	v_mfma_f32_16x16x32_bf16 v[50:53], v[138:141], v[154:157], v[50:53]
	v_mfma_f32_16x16x32_bf16 v[42:45], v[130:133], v[176:179], v[42:45]
	v_mfma_f32_16x16x32_bf16 v[34:37], v[138:141], v[176:179], v[34:37]
	v_mfma_f32_16x16x32_bf16 v[26:29], v[130:133], v[184:187], v[26:29]
	v_mfma_f32_16x16x32_bf16 v[18:21], v[138:141], v[184:187], v[18:21]
	v_mfma_f32_16x16x32_bf16 v[62:65], v[134:137], v[150:153], v[62:65]
	v_mfma_f32_16x16x32_bf16 v[58:61], v[142:145], v[150:153], v[58:61]
	v_mfma_f32_16x16x32_bf16 v[54:57], v[134:137], v[158:161], v[54:57]
	v_mfma_f32_16x16x32_bf16 v[50:53], v[142:145], v[158:161], v[50:53]
	v_mfma_f32_16x16x32_bf16 v[42:45], v[134:137], v[180:183], v[42:45]
	v_mfma_f32_16x16x32_bf16 v[34:37], v[142:145], v[180:183], v[34:37]
	v_mfma_f32_16x16x32_bf16 v[26:29], v[134:137], v[188:191], v[26:29]
	v_mfma_f32_16x16x32_bf16 v[18:21], v[142:145], v[188:191], v[18:21]
	s_setprio 0
	s_barrier
	s_add_u32 s82, s50, 0x80000
	s_addc_u32 s83, s51, 0
	s_add_i32 s81, s69, s56
	v_lshl_add_u64 v[130:131], s[82:83], 0, v[162:163]
	s_mov_b32 m0, s81
	s_nop 0
	global_load_lds_dwordx4 v[130:131], off
	v_lshl_add_u64 v[130:131], s[82:83], 0, v[164:165]
	s_add_i32 m0, s81, 0x2000
	s_nop 0
	global_load_lds_dwordx4 v[130:131], off
	s_waitcnt vmcnt(6)
	s_barrier
	s_setprio 1
	v_mfma_f32_16x16x32_bf16 v[46:49], v[192:195], v[146:149], v[46:49]
	v_mfma_f32_16x16x32_bf16 v[38:41], v[200:203], v[146:149], v[38:41]
	v_mfma_f32_16x16x32_bf16 v[30:33], v[192:195], v[154:157], v[30:33]
	v_mfma_f32_16x16x32_bf16 v[22:25], v[200:203], v[154:157], v[22:25]
	v_mfma_f32_16x16x32_bf16 v[14:17], v[192:195], v[176:179], v[14:17]
	v_mfma_f32_16x16x32_bf16 v[10:13], v[200:203], v[176:179], v[10:13]
	v_mfma_f32_16x16x32_bf16 v[6:9], v[192:195], v[184:187], v[6:9]
	v_mfma_f32_16x16x32_bf16 v[2:5], v[200:203], v[184:187], v[2:5]
	v_mfma_f32_16x16x32_bf16 v[46:49], v[196:199], v[150:153], v[46:49]
	v_mfma_f32_16x16x32_bf16 v[38:41], v[204:207], v[150:153], v[38:41]
	v_mfma_f32_16x16x32_bf16 v[30:33], v[196:199], v[158:161], v[30:33]
	v_mfma_f32_16x16x32_bf16 v[22:25], v[204:207], v[158:161], v[22:25]
	v_mfma_f32_16x16x32_bf16 v[14:17], v[196:199], v[180:183], v[14:17]
	v_mfma_f32_16x16x32_bf16 v[10:13], v[204:207], v[180:183], v[10:13]
	v_mfma_f32_16x16x32_bf16 v[6:9], v[196:199], v[188:191], v[6:9]
	v_mfma_f32_16x16x32_bf16 v[2:5], v[204:207], v[188:191], v[2:5]
	s_setprio 0
	s_add_i32 s81, 0, 0x18000
	v_add_u32_e32 v142, s81, v236
	s_barrier
	ds_read_b128 v[130:133], v142
	ds_read_b128 v[134:137], v142 offset:1024
	ds_read_b128 v[138:141], v142 offset:2048
	ds_read_b128 v[142:145], v142 offset:3072
	s_add_u32 s52, s52, 0x80000
	s_addc_u32 s53, s53, 0
	s_mov_b32 m0, s60
	v_lshl_add_u64 v[192:193], s[52:53], 0, v[162:163]
	ds_read_b128 v[146:149], v241 offset:32768
	ds_read_b128 v[150:153], v241 offset:33792
	ds_read_b128 v[154:157], v241 offset:34816
	ds_read_b128 v[158:161], v241 offset:35840
	ds_read_b128 v[176:179], v241 offset:36864
	ds_read_b128 v[180:183], v241 offset:37888
	ds_read_b128 v[184:187], v241 offset:38912
	ds_read_b128 v[188:191], v241 offset:39936
	global_load_lds_dwordx4 v[192:193], off
	v_lshl_add_u64 v[192:193], s[52:53], 0, v[164:165]
	s_mov_b32 m0, s61
	s_nop 0
	global_load_lds_dwordx4 v[192:193], off
	s_waitcnt lgkmcnt(8)
	s_barrier
	s_waitcnt lgkmcnt(0)
	s_setprio 1
	s_waitcnt lgkmcnt(0)
	v_mfma_f32_16x16x32_bf16 v[126:129], v[130:133], v[146:149], v[126:129]
	v_mfma_f32_16x16x32_bf16 v[122:125], v[138:141], v[146:149], v[122:125]
	v_mfma_f32_16x16x32_bf16 v[118:121], v[130:133], v[154:157], v[118:121]
	v_mfma_f32_16x16x32_bf16 v[114:117], v[138:141], v[154:157], v[114:117]
	v_mfma_f32_16x16x32_bf16 v[106:109], v[130:133], v[176:179], v[106:109]
	v_mfma_f32_16x16x32_bf16 v[98:101], v[138:141], v[176:179], v[98:101]
	v_mfma_f32_16x16x32_bf16 v[90:93], v[130:133], v[184:187], v[90:93]
	v_mfma_f32_16x16x32_bf16 v[82:85], v[138:141], v[184:187], v[82:85]
	v_mfma_f32_16x16x32_bf16 v[126:129], v[134:137], v[150:153], v[126:129]
	v_mfma_f32_16x16x32_bf16 v[122:125], v[142:145], v[150:153], v[122:125]
	v_mfma_f32_16x16x32_bf16 v[118:121], v[134:137], v[158:161], v[118:121]
	v_mfma_f32_16x16x32_bf16 v[114:117], v[142:145], v[158:161], v[114:117]
	v_mfma_f32_16x16x32_bf16 v[106:109], v[134:137], v[180:183], v[106:109]
	v_mfma_f32_16x16x32_bf16 v[98:101], v[142:145], v[180:183], v[98:101]
	v_mfma_f32_16x16x32_bf16 v[90:93], v[134:137], v[188:191], v[90:93]
	v_mfma_f32_16x16x32_bf16 v[82:85], v[142:145], v[188:191], v[82:85]
	s_setprio 0
	s_barrier
	s_add_i32 s52, 0, 0x1c000
	s_add_i32 s53, s81, s56
	v_add_u32_e32 v204, s52, v236
	v_lshl_add_u64 v[168:169], v[168:169], 0, s[36:37]
	s_mov_b32 m0, s53
	ds_read_b128 v[192:195], v204
	ds_read_b128 v[196:199], v204 offset:1024
	ds_read_b128 v[200:203], v204 offset:2048
	ds_read_b128 v[204:207], v204 offset:3072
	global_load_lds_dwordx4 v[168:169], off
	v_lshl_add_u64 v[168:169], v[208:209], 0, s[36:37]
	s_add_i32 m0, s53, 0x2000
	s_nop 0
	global_load_lds_dwordx4 v[168:169], off
	s_barrier
	s_waitcnt lgkmcnt(0)
	s_setprio 1
	s_waitcnt lgkmcnt(0)
	v_mfma_f32_16x16x32_bf16 v[110:113], v[192:195], v[146:149], v[110:113]
	v_mfma_f32_16x16x32_bf16 v[102:105], v[200:203], v[146:149], v[102:105]
	v_mfma_f32_16x16x32_bf16 v[94:97], v[192:195], v[154:157], v[94:97]
	v_mfma_f32_16x16x32_bf16 v[86:89], v[200:203], v[154:157], v[86:89]
	v_mfma_f32_16x16x32_bf16 v[78:81], v[192:195], v[176:179], v[78:81]
	v_mfma_f32_16x16x32_bf16 v[74:77], v[200:203], v[176:179], v[74:77]
	v_mfma_f32_16x16x32_bf16 v[70:73], v[192:195], v[184:187], v[70:73]
	v_mfma_f32_16x16x32_bf16 v[66:69], v[200:203], v[184:187], v[66:69]
	v_mfma_f32_16x16x32_bf16 v[110:113], v[196:199], v[150:153], v[110:113]
	v_mfma_f32_16x16x32_bf16 v[102:105], v[204:207], v[150:153], v[102:105]
	v_mfma_f32_16x16x32_bf16 v[94:97], v[196:199], v[158:161], v[94:97]
	v_mfma_f32_16x16x32_bf16 v[86:89], v[204:207], v[158:161], v[86:89]
	v_mfma_f32_16x16x32_bf16 v[78:81], v[196:199], v[180:183], v[78:81]
	v_mfma_f32_16x16x32_bf16 v[74:77], v[204:207], v[180:183], v[74:77]
	v_mfma_f32_16x16x32_bf16 v[70:73], v[196:199], v[188:191], v[70:73]
	v_mfma_f32_16x16x32_bf16 v[66:69], v[204:207], v[188:191], v[66:69]
	s_setprio 0
	s_mov_b32 m0, s64
	v_lshl_add_u64 v[168:169], v[210:211], 0, s[36:37]
	s_barrier
	ds_read_b128 v[146:149], v241 offset:49152
	ds_read_b128 v[150:153], v241 offset:50176
	ds_read_b128 v[154:157], v241 offset:51200
	ds_read_b128 v[158:161], v241 offset:52224
	ds_read_b128 v[176:179], v241 offset:53248
	ds_read_b128 v[180:183], v241 offset:54272
	ds_read_b128 v[184:187], v241 offset:55296
	ds_read_b128 v[188:191], v241 offset:56320
	global_load_lds_dwordx4 v[168:169], off
	v_lshl_add_u64 v[168:169], v[212:213], 0, s[36:37]
	s_mov_b32 m0, s65
	s_nop 0
	global_load_lds_dwordx4 v[168:169], off
	s_barrier
	s_waitcnt lgkmcnt(0)
	s_setprio 1
	s_waitcnt lgkmcnt(0)
	v_mfma_f32_16x16x32_bf16 v[62:65], v[130:133], v[146:149], v[62:65]
	v_mfma_f32_16x16x32_bf16 v[58:61], v[138:141], v[146:149], v[58:61]
	v_mfma_f32_16x16x32_bf16 v[54:57], v[130:133], v[154:157], v[54:57]
	v_mfma_f32_16x16x32_bf16 v[50:53], v[138:141], v[154:157], v[50:53]
	v_mfma_f32_16x16x32_bf16 v[42:45], v[130:133], v[176:179], v[42:45]
	v_mfma_f32_16x16x32_bf16 v[34:37], v[138:141], v[176:179], v[34:37]
	v_mfma_f32_16x16x32_bf16 v[26:29], v[130:133], v[184:187], v[26:29]
	v_mfma_f32_16x16x32_bf16 v[18:21], v[138:141], v[184:187], v[18:21]
	v_mfma_f32_16x16x32_bf16 v[62:65], v[134:137], v[150:153], v[62:65]
	v_mfma_f32_16x16x32_bf16 v[58:61], v[142:145], v[150:153], v[58:61]
	v_mfma_f32_16x16x32_bf16 v[54:57], v[134:137], v[158:161], v[54:57]
	v_mfma_f32_16x16x32_bf16 v[50:53], v[142:145], v[158:161], v[50:53]
	v_mfma_f32_16x16x32_bf16 v[42:45], v[134:137], v[180:183], v[42:45]
	v_mfma_f32_16x16x32_bf16 v[34:37], v[142:145], v[180:183], v[34:37]
	v_mfma_f32_16x16x32_bf16 v[26:29], v[134:137], v[188:191], v[26:29]
	v_mfma_f32_16x16x32_bf16 v[18:21], v[142:145], v[188:191], v[18:21]
	s_setprio 0
	s_barrier
	s_add_u32 s50, s50, 0x80080
	s_addc_u32 s51, s51, 0
	s_add_i32 s52, s52, s56
	v_lshl_add_u64 v[130:131], s[50:51], 0, v[162:163]
	s_mov_b32 m0, s52
	s_nop 0
	global_load_lds_dwordx4 v[130:131], off
	v_lshl_add_u64 v[130:131], s[50:51], 0, v[164:165]
	s_add_i32 m0, s52, 0x2000
	s_nop 0
	global_load_lds_dwordx4 v[130:131], off
	s_waitcnt vmcnt(6)
	s_barrier
	s_setprio 1
	v_mfma_f32_16x16x32_bf16 v[46:49], v[192:195], v[146:149], v[46:49]
	v_mfma_f32_16x16x32_bf16 v[38:41], v[200:203], v[146:149], v[38:41]
	v_mfma_f32_16x16x32_bf16 v[30:33], v[192:195], v[154:157], v[30:33]
	v_mfma_f32_16x16x32_bf16 v[22:25], v[200:203], v[154:157], v[22:25]
	v_mfma_f32_16x16x32_bf16 v[14:17], v[192:195], v[176:179], v[14:17]
	v_mfma_f32_16x16x32_bf16 v[10:13], v[200:203], v[176:179], v[10:13]
	v_mfma_f32_16x16x32_bf16 v[6:9], v[192:195], v[184:187], v[6:9]
	v_mfma_f32_16x16x32_bf16 v[2:5], v[200:203], v[184:187], v[2:5]
	v_mfma_f32_16x16x32_bf16 v[46:49], v[196:199], v[150:153], v[46:49]
	v_mfma_f32_16x16x32_bf16 v[38:41], v[204:207], v[150:153], v[38:41]
	v_mfma_f32_16x16x32_bf16 v[30:33], v[196:199], v[158:161], v[30:33]
	v_mfma_f32_16x16x32_bf16 v[22:25], v[204:207], v[158:161], v[22:25]
	v_mfma_f32_16x16x32_bf16 v[14:17], v[196:199], v[180:183], v[14:17]
	v_mfma_f32_16x16x32_bf16 v[10:13], v[204:207], v[180:183], v[10:13]
	v_mfma_f32_16x16x32_bf16 v[6:9], v[196:199], v[188:191], v[6:9]
	v_mfma_f32_16x16x32_bf16 v[2:5], v[204:207], v[188:191], v[2:5]
	s_setprio 0
	s_add_i32 s80, s80, 2
	s_add_u32 s48, s48, 0x100
	s_addc_u32 s49, s49, 0
	s_add_u32 s74, s74, 0x100
	s_addc_u32 s75, s75, 0
	s_cmp_gt_u32 s80, 29
	s_barrier
	s_cbranch_scc0 .LBB0_1098
	v_lshl_or_b32 v176, s46, 7, v239
	s_cmp_gt_i32 s20, 63
	v_ashrrev_i32_e32 v177, 31, v176
	s_mov_b64 s[46:47], -1
	s_cbranch_scc1 .LBB0_1141
	v_lshlrev_b64 v[130:131], 2, v[176:177]
	v_lshl_add_u64 v[186:187], s[12:13], 0, v[130:131]
	v_add_co_u32_e32 v146, vcc, 0x5000, v186
	v_lshl_add_u64 v[184:185], s[30:31], 0, v[130:131]
	s_nop 0
	v_addc_co_u32_e32 v147, vcc, 0, v187, vcc
	v_add_co_u32_e32 v150, vcc, 0x5000, v184
	v_lshl_add_u64 v[182:183], s[34:35], 0, v[130:131]
	v_lshl_add_u64 v[180:181], s[14:15], 0, v[130:131]
	v_addc_co_u32_e32 v151, vcc, 0, v185, vcc
	global_load_dwordx4 v[134:137], v[186:187], off
	global_load_dwordx4 v[142:145], v[184:185], off
	global_load_dwordx4 v[138:141], v[182:183], off
	global_load_dwordx4 v[130:133], v[180:181], off
	s_nop 0
	global_load_dwordx4 v[146:149], v[146:147], off offset:2048
	s_nop 0
	global_load_dwordx4 v[154:157], v[150:151], off offset:2048
	v_add_co_u32_e32 v150, vcc, 0x5000, v182
	s_lshl_b32 s39, s20, 2
	s_nop 0
	v_addc_co_u32_e32 v151, vcc, 0, v183, vcc
	global_load_dwordx4 v[158:161], v[150:151], off offset:2048
	v_add_co_u32_e32 v150, vcc, 0x5000, v180
	s_add_i32 s39, s39, s55
	s_nop 0
	v_addc_co_u32_e32 v151, vcc, 0, v181, vcc
	global_load_dwordx4 v[150:153], v[150:151], off offset:2048
	s_lshl_b32 s41, s39, 1
	v_add_u32_e32 v168, s41, v1
	v_mad_i64_i32 v[168:169], s[46:47], v168, s71, 0
	v_lshl_add_u64 v[168:169], s[24:25], 0, v[168:169]
	v_mov_b32_dpp v206, v126 row_shr:1 row_mask:0xf bank_mask:0xf bound_ctrl:1
	v_mov_b32_dpp v188, v126 row_shr:2 row_mask:0xf bank_mask:0xf bound_ctrl:1
	v_mov_b32_dpp v200, v126 row_shl:15 row_mask:0xf bank_mask:0xf bound_ctrl:1
	v_mov_b32_dpp v198, v126 row_shl:14 row_mask:0xf bank_mask:0xf bound_ctrl:1
	v_mov_b32_dpp v207, v127 row_shr:1 row_mask:0xf bank_mask:0xf bound_ctrl:1
	v_mov_b32_dpp v189, v127 row_shr:2 row_mask:0xf bank_mask:0xf bound_ctrl:1
	v_mov_b32_dpp v201, v127 row_shl:15 row_mask:0xf bank_mask:0xf bound_ctrl:1
	v_mov_b32_dpp v199, v127 row_shl:14 row_mask:0xf bank_mask:0xf bound_ctrl:1
	v_mov_b32_dpp v210, v128 row_shr:1 row_mask:0xf bank_mask:0xf bound_ctrl:1
	v_mov_b32_dpp v208, v128 row_shr:2 row_mask:0xf bank_mask:0xf bound_ctrl:1
	v_mov_b32_dpp v204, v128 row_shl:15 row_mask:0xf bank_mask:0xf bound_ctrl:1
	v_mov_b32_dpp v202, v128 row_shl:14 row_mask:0xf bank_mask:0xf bound_ctrl:1
	v_mov_b32_dpp v211, v129 row_shr:1 row_mask:0xf bank_mask:0xf bound_ctrl:1
	v_mov_b32_dpp v209, v129 row_shr:2 row_mask:0xf bank_mask:0xf bound_ctrl:1
	v_mov_b32_dpp v205, v129 row_shl:15 row_mask:0xf bank_mask:0xf bound_ctrl:1
	v_mov_b32_dpp v203, v129 row_shl:14 row_mask:0xf bank_mask:0xf bound_ctrl:1
	v_lshl_add_u64 v[178:179], v[176:177], 2, v[168:169]
	s_and_saveexec_b64 s[46:47], s[4:5]
	s_cbranch_execz .LBB0_1102
	global_store_dwordx4 v[178:179], v[126:129], off sc0 sc1
.LBB0_1102:
	s_or_b64 exec, exec, s[46:47]
	v_mov_b32_dpp v214, v110 row_shr:1 row_mask:0xf bank_mask:0xf bound_ctrl:1
	v_mov_b32_dpp v212, v110 row_shr:2 row_mask:0xf bank_mask:0xf bound_ctrl:1
	v_mov_b32_dpp v192, v110 row_shl:15 row_mask:0xf bank_mask:0xf bound_ctrl:1
	v_mov_b32_dpp v190, v110 row_shl:14 row_mask:0xf bank_mask:0xf bound_ctrl:1
	v_mov_b32_dpp v215, v111 row_shr:1 row_mask:0xf bank_mask:0xf bound_ctrl:1
	v_mov_b32_dpp v213, v111 row_shr:2 row_mask:0xf bank_mask:0xf bound_ctrl:1
	v_mov_b32_dpp v193, v111 row_shl:15 row_mask:0xf bank_mask:0xf bound_ctrl:1
	v_mov_b32_dpp v191, v111 row_shl:14 row_mask:0xf bank_mask:0xf bound_ctrl:1
	v_mov_b32_dpp v218, v112 row_shr:1 row_mask:0xf bank_mask:0xf bound_ctrl:1
	v_mov_b32_dpp v216, v112 row_shr:2 row_mask:0xf bank_mask:0xf bound_ctrl:1
	v_mov_b32_dpp v196, v112 row_shl:15 row_mask:0xf bank_mask:0xf bound_ctrl:1
	v_mov_b32_dpp v194, v112 row_shl:14 row_mask:0xf bank_mask:0xf bound_ctrl:1
	v_mov_b32_dpp v219, v113 row_shr:1 row_mask:0xf bank_mask:0xf bound_ctrl:1
	v_mov_b32_dpp v217, v113 row_shr:2 row_mask:0xf bank_mask:0xf bound_ctrl:1
	v_mov_b32_dpp v197, v113 row_shl:15 row_mask:0xf bank_mask:0xf bound_ctrl:1
	v_mov_b32_dpp v195, v113 row_shl:14 row_mask:0xf bank_mask:0xf bound_ctrl:1
	s_and_saveexec_b64 s[46:47], s[4:5]
	s_cbranch_execz .LBB0_1104
	v_add_co_u32_e32 v168, vcc, 0x5000, v178
	s_nop 1
	v_addc_co_u32_e32 v169, vcc, 0, v179, vcc
	global_store_dwordx4 v[168:169], v[110:113], off offset:2048 sc0 sc1
.LBB0_1104:
	s_or_b64 exec, exec, s[46:47]
	v_lshl_or_b32 v243, s39, 6, v1
	s_and_saveexec_b64 s[46:47], s[8:9]
	s_cbranch_execz .LBB0_1106
	v_pk_add_f32 v[206:207], v[206:207], 0 op_sel_hi:[1,0]
	v_pk_add_f32 v[210:211], v[210:211], 0 op_sel_hi:[1,0]
	s_waitcnt vmcnt(0)
	v_pk_mul_f32 v[206:207], v[142:143], v[206:207]
	v_pk_add_f32 v[188:189], v[188:189], 0 op_sel_hi:[1,0]
	v_pk_mul_f32 v[210:211], v[144:145], v[210:211]
	v_pk_fma_f32 v[206:207], v[126:127], v[138:139], v[206:207]
	v_pk_add_f32 v[208:209], v[208:209], 0 op_sel_hi:[1,0]
	v_pk_fma_f32 v[210:211], v[128:129], v[140:141], v[210:211]
	v_pk_fma_f32 v[188:189], v[134:135], v[188:189], v[206:207]
	v_pk_fma_f32 v[206:207], v[136:137], v[208:209], v[210:211]
	v_pk_add_f32 v[188:189], v[130:131], v[188:189]
	v_pk_add_f32 v[206:207], v[132:133], v[206:207]
	v_mul_f32_e32 v208, 0xbfb8aa3b, v188
	v_mul_f32_e32 v209, 0xbfb8aa3b, v189
	v_exp_f32_e32 v208, v208
	v_exp_f32_e32 v209, v209
	v_mul_f32_e32 v210, 0xbfb8aa3b, v206
	v_mul_f32_e32 v211, 0xbfb8aa3b, v207
	v_exp_f32_e32 v210, v210
	v_exp_f32_e32 v211, v211
	v_add_f32_e32 v208, 1.0, v208
	v_add_f32_e32 v209, 1.0, v209
	v_pk_add_f32 v[168:169], v[214:215], 0 op_sel_hi:[1,0]
	v_rcp_f32_e32 v208, v208
	v_rcp_f32_e32 v209, v209
	v_add_f32_e32 v210, 1.0, v210
	v_add_f32_e32 v211, 1.0, v211
	v_pk_add_f32 v[214:215], v[218:219], 0 op_sel_hi:[1,0]
	v_pk_mul_f32 v[168:169], v[154:155], v[168:169]
	v_rcp_f32_e32 v210, v210
	v_rcp_f32_e32 v211, v211
	v_pk_add_f32 v[212:213], v[212:213], 0 op_sel_hi:[1,0]
	v_pk_mul_f32 v[214:215], v[156:157], v[214:215]
	v_pk_fma_f32 v[168:169], v[110:111], v[158:159], v[168:169]
	v_pk_add_f32 v[216:217], v[216:217], 0 op_sel_hi:[1,0]
	v_pk_fma_f32 v[214:215], v[112:113], v[160:161], v[214:215]
	v_pk_fma_f32 v[168:169], v[146:147], v[212:213], v[168:169]
	v_pk_fma_f32 v[212:213], v[148:149], v[216:217], v[214:215]
	v_pk_add_f32 v[168:169], v[150:151], v[168:169]
	v_pk_mul_f32 v[188:189], v[188:189], v[208:209]
	v_pk_add_f32 v[212:213], v[152:153], v[212:213]
	v_pk_mul_f32 v[168:169], v[188:189], v[168:169]
	v_pk_mul_f32 v[188:189], v[206:207], v[210:211]
	v_cvt_pk_bf16_f32 v168, v168, v169
	v_pk_mul_f32 v[188:189], v[188:189], v[212:213]
	s_nop 0
	v_cvt_pk_bf16_f32 v169, v188, v189
	v_mov_b64_e32 v[188:189], s[22:23]
	v_mad_i64_i32 v[188:189], s[48:49], v243, s72, v[188:189]
	v_lshl_add_u64 v[188:189], v[176:177], 1, v[188:189]
	global_store_dwordx2 v[188:189], v[168:169], off sc0 sc1
.LBB0_1106:
	s_or_b64 exec, exec, s[46:47]
	v_add_u32_e32 v168, s41, v237
	v_mad_i64_i32 v[188:189], s[46:47], v168, s71, 0
	s_nop 0
	v_mov_b32_dpp v168, v118 row_shr:1 row_mask:0xf bank_mask:0xf bound_ctrl:1
	v_mov_b32_dpp v169, v119 row_shr:1 row_mask:0xf bank_mask:0xf bound_ctrl:1
	v_mov_b32_dpp v212, v120 row_shr:1 row_mask:0xf bank_mask:0xf bound_ctrl:1
	v_mov_b32_dpp v213, v121 row_shr:1 row_mask:0xf bank_mask:0xf bound_ctrl:1
	v_mov_b32_dpp v214, v120 row_shr:2 row_mask:0xf bank_mask:0xf bound_ctrl:1
	v_pk_add_f32 v[204:205], v[204:205], v[212:213]
	v_pk_add_f32 v[168:169], v[200:201], v[168:169]
	v_mov_b32_dpp v215, v121 row_shr:2 row_mask:0xf bank_mask:0xf bound_ctrl:1
	v_mov_b32_dpp v206, v118 row_shr:2 row_mask:0xf bank_mask:0xf bound_ctrl:1
	v_mov_b32_dpp v207, v119 row_shr:2 row_mask:0xf bank_mask:0xf bound_ctrl:1
	v_pk_add_f32 v[200:201], v[202:203], v[214:215]
	s_waitcnt vmcnt(0)
	v_pk_mul_f32 v[168:169], v[142:143], v[168:169]
	v_pk_mul_f32 v[202:203], v[144:145], v[204:205]
	v_pk_add_f32 v[198:199], v[198:199], v[206:207]
	v_pk_fma_f32 v[202:203], v[120:121], v[140:141], v[202:203]
	v_pk_fma_f32 v[168:169], v[118:119], v[138:139], v[168:169]
	v_mov_b32_dpp v204, v96 row_shr:1 row_mask:0xf bank_mask:0xf bound_ctrl:1
	v_pk_fma_f32 v[168:169], v[134:135], v[198:199], v[168:169]
	v_pk_fma_f32 v[198:199], v[136:137], v[200:201], v[202:203]
	v_mov_b32_dpp v200, v94 row_shr:1 row_mask:0xf bank_mask:0xf bound_ctrl:1
	v_mov_b32_dpp v201, v95 row_shr:1 row_mask:0xf bank_mask:0xf bound_ctrl:1
	v_mov_b32_dpp v205, v97 row_shr:1 row_mask:0xf bank_mask:0xf bound_ctrl:1
	v_pk_add_f32 v[196:197], v[196:197], v[204:205]
	v_pk_add_f32 v[192:193], v[192:193], v[200:201]
	v_mov_b32_dpp v202, v94 row_shr:2 row_mask:0xf bank_mask:0xf bound_ctrl:1
	v_mov_b32_dpp v203, v95 row_shr:2 row_mask:0xf bank_mask:0xf bound_ctrl:1
	v_mov_b32_dpp v206, v96 row_shr:2 row_mask:0xf bank_mask:0xf bound_ctrl:1
	v_mov_b32_dpp v207, v97 row_shr:2 row_mask:0xf bank_mask:0xf bound_ctrl:1
	v_pk_mul_f32 v[192:193], v[154:155], v[192:193]
	v_pk_mul_f32 v[196:197], v[156:157], v[196:197]
	v_pk_add_f32 v[168:169], v[130:131], v[168:169]
	v_pk_add_f32 v[194:195], v[194:195], v[206:207]
	v_pk_add_f32 v[190:191], v[190:191], v[202:203]
	v_pk_fma_f32 v[196:197], v[96:97], v[160:161], v[196:197]
	v_pk_fma_f32 v[192:193], v[94:95], v[158:159], v[192:193]
	v_pk_add_f32 v[198:199], v[132:133], v[198:199]
	v_pk_fma_f32 v[190:191], v[146:147], v[190:191], v[192:193]
	v_pk_fma_f32 v[192:193], v[148:149], v[194:195], v[196:197]
	v_mul_f32_e32 v194, 0xbfb8aa3b, v168
	v_mul_f32_e32 v195, 0xbfb8aa3b, v169
	v_exp_f32_e32 v194, v194
	v_exp_f32_e32 v195, v195
	v_mul_f32_e32 v196, 0xbfb8aa3b, v198
	v_mul_f32_e32 v197, 0xbfb8aa3b, v199
	v_exp_f32_e32 v196, v196
	v_exp_f32_e32 v197, v197
	v_add_f32_e32 v194, 1.0, v194
	v_add_f32_e32 v195, 1.0, v195
	v_rcp_f32_e32 v194, v194
	v_rcp_f32_e32 v195, v195
	v_add_f32_e32 v196, 1.0, v196
	v_add_f32_e32 v197, 1.0, v197
	v_rcp_f32_e32 v196, v196
	v_rcp_f32_e32 v197, v197
	v_pk_add_f32 v[190:191], v[150:151], v[190:191]
	v_pk_mul_f32 v[168:169], v[168:169], v[194:195]
	v_pk_add_f32 v[192:193], v[152:153], v[192:193]
	v_pk_mul_f32 v[168:169], v[168:169], v[190:191]
	v_pk_mul_f32 v[190:191], v[198:199], v[196:197]
	v_cvt_pk_bf16_f32 v168, v168, v169
	v_pk_mul_f32 v[190:191], v[190:191], v[192:193]
	v_mov_b64_e32 v[194:195], s[22:23]
	v_cvt_pk_bf16_f32 v169, v190, v191
	v_or_b32_e32 v190, 16, v243
	v_mad_i64_i32 v[190:191], s[46:47], v190, s72, v[194:195]
	v_lshlrev_b64 v[196:197], 1, v[176:177]
	v_lshl_add_u64 v[192:193], v[190:191], 0, v[196:197]
	v_mov_b32_dpp v208, v118 row_shl:15 row_mask:0xf bank_mask:0xf bound_ctrl:1
	v_mov_b32_dpp v209, v119 row_shl:15 row_mask:0xf bank_mask:0xf bound_ctrl:1
	global_store_dwordx2 v[192:193], v[168:169], off sc0 sc1
	v_mov_b32_dpp v168, v106 row_shr:1 row_mask:0xf bank_mask:0xf bound_ctrl:1
	v_mov_b32_dpp v169, v107 row_shr:1 row_mask:0xf bank_mask:0xf bound_ctrl:1
	v_mov_b32_dpp v216, v120 row_shl:15 row_mask:0xf bank_mask:0xf bound_ctrl:1
	v_mov_b32_dpp v218, v120 row_shl:14 row_mask:0xf bank_mask:0xf bound_ctrl:1
	v_mov_b32_dpp v217, v121 row_shl:15 row_mask:0xf bank_mask:0xf bound_ctrl:1
	v_mov_b32_dpp v219, v121 row_shl:14 row_mask:0xf bank_mask:0xf bound_ctrl:1
	v_mov_b32_dpp v206, v108 row_shr:1 row_mask:0xf bank_mask:0xf bound_ctrl:1
	v_mov_b32_dpp v224, v108 row_shr:2 row_mask:0xf bank_mask:0xf bound_ctrl:1
	v_mov_b32_dpp v207, v109 row_shr:1 row_mask:0xf bank_mask:0xf bound_ctrl:1
	v_pk_add_f32 v[168:169], v[208:209], v[168:169]
	v_mov_b32_dpp v225, v109 row_shr:2 row_mask:0xf bank_mask:0xf bound_ctrl:1
	v_mov_b32_dpp v210, v118 row_shl:14 row_mask:0xf bank_mask:0xf bound_ctrl:1
	v_mov_b32_dpp v211, v119 row_shl:14 row_mask:0xf bank_mask:0xf bound_ctrl:1
	v_mov_b32_dpp v212, v94 row_shl:15 row_mask:0xf bank_mask:0xf bound_ctrl:1
	v_mov_b32_dpp v213, v95 row_shl:15 row_mask:0xf bank_mask:0xf bound_ctrl:1
	v_mov_b32_dpp v220, v96 row_shl:15 row_mask:0xf bank_mask:0xf bound_ctrl:1
	v_mov_b32_dpp v221, v97 row_shl:15 row_mask:0xf bank_mask:0xf bound_ctrl:1
	v_mov_b32_dpp v204, v106 row_shr:2 row_mask:0xf bank_mask:0xf bound_ctrl:1
	v_mov_b32_dpp v205, v107 row_shr:2 row_mask:0xf bank_mask:0xf bound_ctrl:1
	v_pk_add_f32 v[206:207], v[216:217], v[206:207]
	v_pk_add_f32 v[208:209], v[218:219], v[224:225]
	v_pk_mul_f32 v[168:169], v[142:143], v[168:169]
	v_mov_b32_dpp v218, v78 row_shr:1 row_mask:0xf bank_mask:0xf bound_ctrl:1
	v_mov_b32_dpp v219, v79 row_shr:1 row_mask:0xf bank_mask:0xf bound_ctrl:1
	v_mov_b32_dpp v226, v80 row_shr:1 row_mask:0xf bank_mask:0xf bound_ctrl:1
	v_mov_b32_dpp v227, v81 row_shr:1 row_mask:0xf bank_mask:0xf bound_ctrl:1
	v_pk_add_f32 v[204:205], v[210:211], v[204:205]
	v_pk_mul_f32 v[206:207], v[144:145], v[206:207]
	v_pk_fma_f32 v[168:169], v[106:107], v[138:139], v[168:169]
	v_pk_add_f32 v[220:221], v[220:221], v[226:227]
	v_pk_add_f32 v[212:213], v[212:213], v[218:219]
	v_mov_b32_dpp v214, v94 row_shl:14 row_mask:0xf bank_mask:0xf bound_ctrl:1
	v_mov_b32_dpp v215, v95 row_shl:14 row_mask:0xf bank_mask:0xf bound_ctrl:1
	v_mov_b32_dpp v222, v96 row_shl:14 row_mask:0xf bank_mask:0xf bound_ctrl:1
	v_mov_b32_dpp v223, v97 row_shl:14 row_mask:0xf bank_mask:0xf bound_ctrl:1
	v_pk_fma_f32 v[206:207], v[108:109], v[140:141], v[206:207]
	v_pk_fma_f32 v[168:169], v[134:135], v[204:205], v[168:169]
	v_mov_b32_dpp v224, v78 row_shr:2 row_mask:0xf bank_mask:0xf bound_ctrl:1
	v_mov_b32_dpp v225, v79 row_shr:2 row_mask:0xf bank_mask:0xf bound_ctrl:1
	v_mov_b32_dpp v228, v80 row_shr:2 row_mask:0xf bank_mask:0xf bound_ctrl:1
	v_mov_b32_dpp v229, v81 row_shr:2 row_mask:0xf bank_mask:0xf bound_ctrl:1
	v_pk_mul_f32 v[212:213], v[154:155], v[212:213]
	v_pk_mul_f32 v[220:221], v[156:157], v[220:221]
	v_pk_fma_f32 v[204:205], v[136:137], v[208:209], v[206:207]
	v_pk_add_f32 v[168:169], v[130:131], v[168:169]
	v_pk_add_f32 v[218:219], v[222:223], v[228:229]
	v_pk_add_f32 v[214:215], v[214:215], v[224:225]
	v_pk_fma_f32 v[220:221], v[80:81], v[160:161], v[220:221]
	v_pk_fma_f32 v[212:213], v[78:79], v[158:159], v[212:213]
	v_pk_add_f32 v[216:217], v[132:133], v[204:205]
	v_pk_fma_f32 v[212:213], v[146:147], v[214:215], v[212:213]
	v_pk_fma_f32 v[214:215], v[148:149], v[218:219], v[220:221]
	v_mul_f32_e32 v218, 0xbfb8aa3b, v168
	v_mul_f32_e32 v219, 0xbfb8aa3b, v169
	v_exp_f32_e32 v218, v218
	v_exp_f32_e32 v219, v219
	v_mul_f32_e32 v220, 0xbfb8aa3b, v216
	v_mul_f32_e32 v221, 0xbfb8aa3b, v217
	v_exp_f32_e32 v220, v220
	v_exp_f32_e32 v221, v221
	v_add_f32_e32 v218, 1.0, v218
	v_add_f32_e32 v219, 1.0, v219
	v_rcp_f32_e32 v218, v218
	v_rcp_f32_e32 v219, v219
	v_add_f32_e32 v220, 1.0, v220
	v_add_f32_e32 v221, 1.0, v221
	v_rcp_f32_e32 v220, v220
	v_rcp_f32_e32 v221, v221
	v_pk_add_f32 v[212:213], v[150:151], v[212:213]
	v_pk_mul_f32 v[168:169], v[168:169], v[218:219]
	v_pk_add_f32 v[214:215], v[152:153], v[214:215]
	v_pk_mul_f32 v[168:169], v[168:169], v[212:213]
	v_pk_mul_f32 v[212:213], v[216:217], v[220:221]
	v_cvt_pk_bf16_f32 v168, v168, v169
	v_pk_mul_f32 v[212:213], v[212:213], v[214:215]
	v_mov_b32_dpp v198, v106 row_shl:15 row_mask:0xf bank_mask:0xf bound_ctrl:1
	v_cvt_pk_bf16_f32 v169, v212, v213
	v_or_b32_e32 v212, 32, v243
	v_mad_i64_i32 v[194:195], s[46:47], v212, s72, v[194:195]
	v_lshl_add_u64 v[194:195], v[194:195], 0, v[196:197]
	global_store_dwordx2 v[194:195], v[168:169], off sc0 sc1
	v_lshl_add_u64 v[168:169], s[26:27], 0, v[188:189]
	v_mov_b32_dpp v190, v106 row_shl:14 row_mask:0xf bank_mask:0xf bound_ctrl:1
	v_mov_b32_dpp v199, v107 row_shl:15 row_mask:0xf bank_mask:0xf bound_ctrl:1
	v_mov_b32_dpp v191, v107 row_shl:14 row_mask:0xf bank_mask:0xf bound_ctrl:1
	v_mov_b32_dpp v202, v108 row_shl:15 row_mask:0xf bank_mask:0xf bound_ctrl:1
	v_mov_b32_dpp v200, v108 row_shl:14 row_mask:0xf bank_mask:0xf bound_ctrl:1
	v_mov_b32_dpp v203, v109 row_shl:15 row_mask:0xf bank_mask:0xf bound_ctrl:1
	v_mov_b32_dpp v201, v109 row_shl:14 row_mask:0xf bank_mask:0xf bound_ctrl:1
	v_mov_b32_dpp v206, v78 row_shl:15 row_mask:0xf bank_mask:0xf bound_ctrl:1
	v_mov_b32_dpp v204, v78 row_shl:14 row_mask:0xf bank_mask:0xf bound_ctrl:1
	v_mov_b32_dpp v207, v79 row_shl:15 row_mask:0xf bank_mask:0xf bound_ctrl:1
	v_mov_b32_dpp v205, v79 row_shl:14 row_mask:0xf bank_mask:0xf bound_ctrl:1
	v_mov_b32_dpp v210, v80 row_shl:15 row_mask:0xf bank_mask:0xf bound_ctrl:1
	v_mov_b32_dpp v208, v80 row_shl:14 row_mask:0xf bank_mask:0xf bound_ctrl:1
	v_mov_b32_dpp v211, v81 row_shl:15 row_mask:0xf bank_mask:0xf bound_ctrl:1
	v_mov_b32_dpp v209, v81 row_shl:14 row_mask:0xf bank_mask:0xf bound_ctrl:1
	v_mov_b32_dpp v216, v90 row_shr:1 row_mask:0xf bank_mask:0xf bound_ctrl:1
	v_mov_b32_dpp v212, v90 row_shr:2 row_mask:0xf bank_mask:0xf bound_ctrl:1
	v_mov_b32_dpp v217, v91 row_shr:1 row_mask:0xf bank_mask:0xf bound_ctrl:1
	v_mov_b32_dpp v213, v91 row_shr:2 row_mask:0xf bank_mask:0xf bound_ctrl:1
	v_mov_b32_dpp v218, v92 row_shr:1 row_mask:0xf bank_mask:0xf bound_ctrl:1
	v_mov_b32_dpp v214, v92 row_shr:2 row_mask:0xf bank_mask:0xf bound_ctrl:1
	v_mov_b32_dpp v219, v93 row_shr:1 row_mask:0xf bank_mask:0xf bound_ctrl:1
	v_mov_b32_dpp v215, v93 row_shr:2 row_mask:0xf bank_mask:0xf bound_ctrl:1
	v_lshl_add_u64 v[188:189], v[176:177], 2, v[168:169]
	s_and_saveexec_b64 s[46:47], s[6:7]
	s_cbranch_execz .LBB0_1108
	global_store_dwordx4 v[188:189], v[90:93], off sc0 sc1
.LBB0_1108:
	s_or_b64 exec, exec, s[46:47]
	v_mov_b32_dpp v224, v70 row_shr:1 row_mask:0xf bank_mask:0xf bound_ctrl:1
	v_mov_b32_dpp v220, v70 row_shr:2 row_mask:0xf bank_mask:0xf bound_ctrl:1
	v_mov_b32_dpp v225, v71 row_shr:1 row_mask:0xf bank_mask:0xf bound_ctrl:1
	v_mov_b32_dpp v221, v71 row_shr:2 row_mask:0xf bank_mask:0xf bound_ctrl:1
	v_mov_b32_dpp v226, v72 row_shr:1 row_mask:0xf bank_mask:0xf bound_ctrl:1
	v_mov_b32_dpp v222, v72 row_shr:2 row_mask:0xf bank_mask:0xf bound_ctrl:1
	v_mov_b32_dpp v227, v73 row_shr:1 row_mask:0xf bank_mask:0xf bound_ctrl:1
	v_mov_b32_dpp v223, v73 row_shr:2 row_mask:0xf bank_mask:0xf bound_ctrl:1
	s_and_saveexec_b64 s[46:47], s[6:7]
	s_cbranch_execz .LBB0_1110
	v_add_co_u32_e32 v168, vcc, 0x5000, v188
	s_nop 1
	v_addc_co_u32_e32 v169, vcc, 0, v189, vcc
	global_store_dwordx4 v[168:169], v[70:73], off offset:2048 sc0 sc1
.LBB0_1110:
	s_or_b64 exec, exec, s[46:47]
	v_pk_add_f32 v[202:203], v[202:203], v[218:219]
	v_pk_add_f32 v[198:199], v[198:199], v[216:217]
	v_pk_mul_f32 v[202:203], v[144:145], v[202:203]
	v_pk_mul_f32 v[198:199], v[142:143], v[198:199]
	v_pk_add_f32 v[200:201], v[200:201], v[214:215]
	v_pk_add_f32 v[190:191], v[190:191], v[212:213]
	v_pk_fma_f32 v[202:203], v[92:93], v[140:141], v[202:203]
	v_pk_fma_f32 v[198:199], v[90:91], v[138:139], v[198:199]
	v_pk_add_f32 v[168:169], v[210:211], v[226:227]
	v_pk_fma_f32 v[190:191], v[134:135], v[190:191], v[198:199]
	v_pk_fma_f32 v[198:199], v[136:137], v[200:201], v[202:203]
	v_pk_add_f32 v[190:191], v[130:131], v[190:191]
	v_pk_add_f32 v[198:199], v[132:133], v[198:199]
	v_mul_f32_e32 v200, 0xbfb8aa3b, v190
	v_mul_f32_e32 v201, 0xbfb8aa3b, v191
	v_mul_f32_e32 v202, 0xbfb8aa3b, v198
	v_mul_f32_e32 v203, 0xbfb8aa3b, v199
	v_exp_f32_e32 v200, v200
	v_exp_f32_e32 v201, v201
	v_exp_f32_e32 v202, v202
	v_exp_f32_e32 v203, v203
	v_add_f32_e32 v200, 1.0, v200
	v_add_f32_e32 v201, 1.0, v201
	v_add_f32_e32 v202, 1.0, v202
	v_add_f32_e32 v203, 1.0, v203
	v_pk_add_f32 v[206:207], v[206:207], v[224:225]
	v_rcp_f32_e32 v200, v200
	v_rcp_f32_e32 v201, v201
	v_rcp_f32_e32 v202, v202
	v_rcp_f32_e32 v203, v203
	v_pk_mul_f32 v[206:207], v[154:155], v[206:207]
	v_pk_mul_f32 v[168:169], v[156:157], v[168:169]
	v_pk_add_f32 v[208:209], v[208:209], v[222:223]
	v_pk_add_f32 v[204:205], v[204:205], v[220:221]
	v_pk_fma_f32 v[168:169], v[72:73], v[160:161], v[168:169]
	v_pk_fma_f32 v[206:207], v[70:71], v[158:159], v[206:207]
	v_pk_fma_f32 v[168:169], v[148:149], v[208:209], v[168:169]
	v_pk_fma_f32 v[204:205], v[146:147], v[204:205], v[206:207]
	v_pk_add_f32 v[168:169], v[152:153], v[168:169]
	v_pk_add_f32 v[204:205], v[150:151], v[204:205]
	v_pk_mul_f32 v[190:191], v[190:191], v[200:201]
	v_pk_mul_f32 v[198:199], v[198:199], v[202:203]
	v_pk_mul_f32 v[190:191], v[190:191], v[204:205]
	v_pk_mul_f32 v[168:169], v[198:199], v[168:169]
	v_cvt_pk_bf16_f32 v190, v190, v191
	v_cvt_pk_bf16_f32 v191, v168, v169
	v_or_b32_e32 v198, 48, v243
	v_mov_b64_e32 v[168:169], s[22:23]
	s_add_i32 s41, s39, 2
	v_mad_i64_i32 v[168:169], s[46:47], v198, s72, v[168:169]
	s_lshl_b32 s39, s41, 1
	v_lshl_add_u64 v[198:199], v[176:177], 1, v[168:169]
	v_add_u32_e32 v168, s39, v1
	v_mad_i64_i32 v[168:169], s[46:47], v168, s71, 0
	v_lshl_add_u64 v[168:169], s[24:25], 0, v[168:169]
	global_store_dwordx2 v[198:199], v[190:191], off sc0 sc1
	v_mov_b32_dpp v218, v62 row_shr:1 row_mask:0xf bank_mask:0xf bound_ctrl:1
	v_mov_b32_dpp v204, v62 row_shr:2 row_mask:0xf bank_mask:0xf bound_ctrl:1
	v_mov_b32_dpp v212, v62 row_shl:15 row_mask:0xf bank_mask:0xf bound_ctrl:1
	v_mov_b32_dpp v210, v62 row_shl:14 row_mask:0xf bank_mask:0xf bound_ctrl:1
	v_mov_b32_dpp v219, v63 row_shr:1 row_mask:0xf bank_mask:0xf bound_ctrl:1
	v_mov_b32_dpp v205, v63 row_shr:2 row_mask:0xf bank_mask:0xf bound_ctrl:1
	v_mov_b32_dpp v213, v63 row_shl:15 row_mask:0xf bank_mask:0xf bound_ctrl:1
	v_mov_b32_dpp v211, v63 row_shl:14 row_mask:0xf bank_mask:0xf bound_ctrl:1
	v_mov_b32_dpp v222, v64 row_shr:1 row_mask:0xf bank_mask:0xf bound_ctrl:1
	v_mov_b32_dpp v220, v64 row_shr:2 row_mask:0xf bank_mask:0xf bound_ctrl:1
	v_mov_b32_dpp v216, v64 row_shl:15 row_mask:0xf bank_mask:0xf bound_ctrl:1
	v_mov_b32_dpp v214, v64 row_shl:14 row_mask:0xf bank_mask:0xf bound_ctrl:1
	v_mov_b32_dpp v223, v65 row_shr:1 row_mask:0xf bank_mask:0xf bound_ctrl:1
	v_mov_b32_dpp v221, v65 row_shr:2 row_mask:0xf bank_mask:0xf bound_ctrl:1
	v_mov_b32_dpp v217, v65 row_shl:15 row_mask:0xf bank_mask:0xf bound_ctrl:1
	v_mov_b32_dpp v215, v65 row_shl:14 row_mask:0xf bank_mask:0xf bound_ctrl:1
	v_lshl_add_u64 v[190:191], v[176:177], 2, v[168:169]
	s_and_saveexec_b64 s[46:47], s[4:5]
	s_cbranch_execz .LBB0_1112
	global_store_dwordx4 v[190:191], v[62:65], off sc0 sc1
.LBB0_1112:
	s_or_b64 exec, exec, s[46:47]
	v_mov_b32_dpp v226, v46 row_shr:1 row_mask:0xf bank_mask:0xf bound_ctrl:1
	v_mov_b32_dpp v224, v46 row_shr:2 row_mask:0xf bank_mask:0xf bound_ctrl:1
	v_mov_b32_dpp v202, v46 row_shl:15 row_mask:0xf bank_mask:0xf bound_ctrl:1
	v_mov_b32_dpp v200, v46 row_shl:14 row_mask:0xf bank_mask:0xf bound_ctrl:1
	v_mov_b32_dpp v227, v47 row_shr:1 row_mask:0xf bank_mask:0xf bound_ctrl:1
	v_mov_b32_dpp v225, v47 row_shr:2 row_mask:0xf bank_mask:0xf bound_ctrl:1
	v_mov_b32_dpp v203, v47 row_shl:15 row_mask:0xf bank_mask:0xf bound_ctrl:1
	v_mov_b32_dpp v201, v47 row_shl:14 row_mask:0xf bank_mask:0xf bound_ctrl:1
	v_mov_b32_dpp v230, v48 row_shr:1 row_mask:0xf bank_mask:0xf bound_ctrl:1
	v_mov_b32_dpp v228, v48 row_shr:2 row_mask:0xf bank_mask:0xf bound_ctrl:1
	v_mov_b32_dpp v208, v48 row_shl:15 row_mask:0xf bank_mask:0xf bound_ctrl:1
	v_mov_b32_dpp v206, v48 row_shl:14 row_mask:0xf bank_mask:0xf bound_ctrl:1
	v_mov_b32_dpp v231, v49 row_shr:1 row_mask:0xf bank_mask:0xf bound_ctrl:1
	v_mov_b32_dpp v229, v49 row_shr:2 row_mask:0xf bank_mask:0xf bound_ctrl:1
	v_mov_b32_dpp v209, v49 row_shl:15 row_mask:0xf bank_mask:0xf bound_ctrl:1
	v_mov_b32_dpp v207, v49 row_shl:14 row_mask:0xf bank_mask:0xf bound_ctrl:1
	s_and_saveexec_b64 s[46:47], s[4:5]
	s_cbranch_execz .LBB0_1114
	v_add_co_u32_e32 v168, vcc, 0x5000, v190
	s_nop 1
	v_addc_co_u32_e32 v169, vcc, 0, v191, vcc
	global_store_dwordx4 v[168:169], v[46:49], off offset:2048 sc0 sc1
.LBB0_1114:
	s_or_b64 exec, exec, s[46:47]
	v_lshl_or_b32 v244, s41, 6, v1
	s_and_saveexec_b64 s[46:47], s[8:9]
	s_cbranch_execz .LBB0_1116
	v_pk_add_f32 v[218:219], v[218:219], 0 op_sel_hi:[1,0]
	v_pk_add_f32 v[222:223], v[222:223], 0 op_sel_hi:[1,0]
	v_pk_mul_f32 v[218:219], v[142:143], v[218:219]
	v_pk_add_f32 v[204:205], v[204:205], 0 op_sel_hi:[1,0]
	v_pk_mul_f32 v[222:223], v[144:145], v[222:223]
	v_pk_fma_f32 v[218:219], v[62:63], v[138:139], v[218:219]
	v_pk_add_f32 v[220:221], v[220:221], 0 op_sel_hi:[1,0]
	v_pk_fma_f32 v[222:223], v[64:65], v[140:141], v[222:223]
	v_pk_fma_f32 v[204:205], v[134:135], v[204:205], v[218:219]
	v_pk_fma_f32 v[218:219], v[136:137], v[220:221], v[222:223]
	v_pk_add_f32 v[204:205], v[130:131], v[204:205]
	v_pk_add_f32 v[218:219], v[132:133], v[218:219]
	v_mul_f32_e32 v220, 0xbfb8aa3b, v204
	v_mul_f32_e32 v221, 0xbfb8aa3b, v205
	v_exp_f32_e32 v220, v220
	v_exp_f32_e32 v221, v221
	v_mul_f32_e32 v222, 0xbfb8aa3b, v218
	v_mul_f32_e32 v223, 0xbfb8aa3b, v219
	v_exp_f32_e32 v222, v222
	v_exp_f32_e32 v223, v223
	v_add_f32_e32 v220, 1.0, v220
	v_add_f32_e32 v221, 1.0, v221
	v_pk_add_f32 v[168:169], v[226:227], 0 op_sel_hi:[1,0]
	v_rcp_f32_e32 v220, v220
	v_rcp_f32_e32 v221, v221
	v_add_f32_e32 v222, 1.0, v222
	v_add_f32_e32 v223, 1.0, v223
	v_pk_add_f32 v[226:227], v[230:231], 0 op_sel_hi:[1,0]
	v_pk_mul_f32 v[168:169], v[154:155], v[168:169]
	v_rcp_f32_e32 v222, v222
	v_rcp_f32_e32 v223, v223
	v_pk_add_f32 v[224:225], v[224:225], 0 op_sel_hi:[1,0]
	v_pk_mul_f32 v[226:227], v[156:157], v[226:227]
	v_pk_fma_f32 v[168:169], v[46:47], v[158:159], v[168:169]
	v_pk_add_f32 v[228:229], v[228:229], 0 op_sel_hi:[1,0]
	v_pk_fma_f32 v[226:227], v[48:49], v[160:161], v[226:227]
	v_pk_fma_f32 v[168:169], v[146:147], v[224:225], v[168:169]
	v_pk_fma_f32 v[224:225], v[148:149], v[228:229], v[226:227]
	v_pk_add_f32 v[168:169], v[150:151], v[168:169]
	v_pk_mul_f32 v[204:205], v[204:205], v[220:221]
	v_pk_add_f32 v[224:225], v[152:153], v[224:225]
	v_pk_mul_f32 v[168:169], v[204:205], v[168:169]
	v_pk_mul_f32 v[204:205], v[218:219], v[222:223]
	v_cvt_pk_bf16_f32 v168, v168, v169
	v_pk_mul_f32 v[204:205], v[204:205], v[224:225]
	s_nop 0
	v_cvt_pk_bf16_f32 v169, v204, v205
	v_mov_b64_e32 v[204:205], s[22:23]
	v_mad_i64_i32 v[204:205], s[48:49], v244, s72, v[204:205]
	v_lshl_add_u64 v[204:205], v[176:177], 1, v[204:205]
	global_store_dwordx2 v[204:205], v[168:169], off sc0 sc1
.LBB0_1116:
	s_or_b64 exec, exec, s[46:47]
	v_add_u32_e32 v168, s39, v237
	v_mad_i64_i32 v[204:205], s[46:47], v168, s71, 0
	s_nop 0
	v_mov_b32_dpp v168, v54 row_shr:1 row_mask:0xf bank_mask:0xf bound_ctrl:1
	v_mov_b32_dpp v169, v55 row_shr:1 row_mask:0xf bank_mask:0xf bound_ctrl:1
	v_mov_b32_dpp v224, v56 row_shr:1 row_mask:0xf bank_mask:0xf bound_ctrl:1
	v_mov_b32_dpp v225, v57 row_shr:1 row_mask:0xf bank_mask:0xf bound_ctrl:1
	v_mov_b32_dpp v226, v56 row_shr:2 row_mask:0xf bank_mask:0xf bound_ctrl:1
	v_pk_add_f32 v[216:217], v[216:217], v[224:225]
	v_pk_add_f32 v[168:169], v[212:213], v[168:169]
	v_mov_b32_dpp v227, v57 row_shr:2 row_mask:0xf bank_mask:0xf bound_ctrl:1
	v_mov_b32_dpp v218, v54 row_shr:2 row_mask:0xf bank_mask:0xf bound_ctrl:1
	v_mov_b32_dpp v219, v55 row_shr:2 row_mask:0xf bank_mask:0xf bound_ctrl:1
	v_pk_add_f32 v[212:213], v[214:215], v[226:227]
	v_pk_mul_f32 v[168:169], v[142:143], v[168:169]
	v_pk_mul_f32 v[214:215], v[144:145], v[216:217]
	v_pk_add_f32 v[210:211], v[210:211], v[218:219]
	v_pk_fma_f32 v[214:215], v[56:57], v[140:141], v[214:215]
	v_pk_fma_f32 v[168:169], v[54:55], v[138:139], v[168:169]
	v_mov_b32_dpp v216, v32 row_shr:1 row_mask:0xf bank_mask:0xf bound_ctrl:1
	v_pk_fma_f32 v[168:169], v[134:135], v[210:211], v[168:169]
	v_pk_fma_f32 v[210:211], v[136:137], v[212:213], v[214:215]
	v_mov_b32_dpp v212, v30 row_shr:1 row_mask:0xf bank_mask:0xf bound_ctrl:1
	v_mov_b32_dpp v213, v31 row_shr:1 row_mask:0xf bank_mask:0xf bound_ctrl:1
	v_mov_b32_dpp v217, v33 row_shr:1 row_mask:0xf bank_mask:0xf bound_ctrl:1
	v_pk_add_f32 v[208:209], v[208:209], v[216:217]
	v_pk_add_f32 v[202:203], v[202:203], v[212:213]
	v_mov_b32_dpp v214, v30 row_shr:2 row_mask:0xf bank_mask:0xf bound_ctrl:1
	v_mov_b32_dpp v215, v31 row_shr:2 row_mask:0xf bank_mask:0xf bound_ctrl:1
	v_mov_b32_dpp v218, v32 row_shr:2 row_mask:0xf bank_mask:0xf bound_ctrl:1
	v_mov_b32_dpp v219, v33 row_shr:2 row_mask:0xf bank_mask:0xf bound_ctrl:1
	v_pk_mul_f32 v[202:203], v[154:155], v[202:203]
	v_pk_mul_f32 v[208:209], v[156:157], v[208:209]
	v_pk_add_f32 v[168:169], v[130:131], v[168:169]
	v_pk_add_f32 v[206:207], v[206:207], v[218:219]
	v_pk_add_f32 v[200:201], v[200:201], v[214:215]
	v_pk_fma_f32 v[208:209], v[32:33], v[160:161], v[208:209]
	v_pk_fma_f32 v[202:203], v[30:31], v[158:159], v[202:203]
	v_pk_add_f32 v[210:211], v[132:133], v[210:211]
	v_pk_fma_f32 v[200:201], v[146:147], v[200:201], v[202:203]
	v_pk_fma_f32 v[202:203], v[148:149], v[206:207], v[208:209]
	v_mul_f32_e32 v206, 0xbfb8aa3b, v168
	v_mul_f32_e32 v207, 0xbfb8aa3b, v169
	v_exp_f32_e32 v206, v206
	v_exp_f32_e32 v207, v207
	v_mul_f32_e32 v208, 0xbfb8aa3b, v210
	v_mul_f32_e32 v209, 0xbfb8aa3b, v211
	v_exp_f32_e32 v208, v208
	v_exp_f32_e32 v209, v209
	v_add_f32_e32 v206, 1.0, v206
	v_add_f32_e32 v207, 1.0, v207
	v_rcp_f32_e32 v206, v206
	v_rcp_f32_e32 v207, v207
	v_add_f32_e32 v208, 1.0, v208
	v_add_f32_e32 v209, 1.0, v209
	v_rcp_f32_e32 v208, v208
	v_rcp_f32_e32 v209, v209
	v_pk_add_f32 v[200:201], v[150:151], v[200:201]
	v_pk_mul_f32 v[168:169], v[168:169], v[206:207]
	v_pk_add_f32 v[202:203], v[152:153], v[202:203]
	v_pk_mul_f32 v[168:169], v[168:169], v[200:201]
	v_pk_mul_f32 v[200:201], v[210:211], v[208:209]
	v_cvt_pk_bf16_f32 v168, v168, v169
	v_pk_mul_f32 v[200:201], v[200:201], v[202:203]
	v_mov_b64_e32 v[202:203], s[22:23]
	v_cvt_pk_bf16_f32 v169, v200, v201
	v_or_b32_e32 v200, 16, v244
	v_mad_i64_i32 v[200:201], s[46:47], v200, s72, v[202:203]
	v_lshl_add_u64 v[200:201], v[200:201], 0, v[196:197]
	v_mov_b32_dpp v220, v54 row_shl:15 row_mask:0xf bank_mask:0xf bound_ctrl:1
	v_mov_b32_dpp v221, v55 row_shl:15 row_mask:0xf bank_mask:0xf bound_ctrl:1
	v_mov_b32_dpp v228, v56 row_shl:15 row_mask:0xf bank_mask:0xf bound_ctrl:1
	v_mov_b32_dpp v229, v57 row_shl:15 row_mask:0xf bank_mask:0xf bound_ctrl:1
	global_store_dwordx2 v[200:201], v[168:169], off sc0 sc1
	v_mov_b32_dpp v168, v42 row_shr:1 row_mask:0xf bank_mask:0xf bound_ctrl:1
	v_mov_b32_dpp v169, v43 row_shr:1 row_mask:0xf bank_mask:0xf bound_ctrl:1
	v_mov_b32_dpp v216, v44 row_shr:1 row_mask:0xf bank_mask:0xf bound_ctrl:1
	v_mov_b32_dpp v217, v45 row_shr:1 row_mask:0xf bank_mask:0xf bound_ctrl:1
	v_pk_add_f32 v[216:217], v[228:229], v[216:217]
	v_pk_add_f32 v[168:169], v[220:221], v[168:169]
	v_mov_b32_dpp v222, v54 row_shl:14 row_mask:0xf bank_mask:0xf bound_ctrl:1
	v_mov_b32_dpp v223, v55 row_shl:14 row_mask:0xf bank_mask:0xf bound_ctrl:1
	v_mov_b32_dpp v230, v56 row_shl:14 row_mask:0xf bank_mask:0xf bound_ctrl:1
	v_mov_b32_dpp v231, v57 row_shl:14 row_mask:0xf bank_mask:0xf bound_ctrl:1
	v_mov_b32_dpp v224, v30 row_shl:15 row_mask:0xf bank_mask:0xf bound_ctrl:1
	v_mov_b32_dpp v225, v31 row_shl:15 row_mask:0xf bank_mask:0xf bound_ctrl:1
	v_mov_b32_dpp v232, v32 row_shl:15 row_mask:0xf bank_mask:0xf bound_ctrl:1
	v_mov_b32_dpp v233, v33 row_shl:15 row_mask:0xf bank_mask:0xf bound_ctrl:1
	v_mov_b32_dpp v214, v42 row_shr:2 row_mask:0xf bank_mask:0xf bound_ctrl:1
	v_mov_b32_dpp v215, v43 row_shr:2 row_mask:0xf bank_mask:0xf bound_ctrl:1
	v_mov_b32_dpp v218, v44 row_shr:2 row_mask:0xf bank_mask:0xf bound_ctrl:1
	v_mov_b32_dpp v219, v45 row_shr:2 row_mask:0xf bank_mask:0xf bound_ctrl:1
	v_pk_mul_f32 v[168:169], v[142:143], v[168:169]
	v_pk_mul_f32 v[216:217], v[144:145], v[216:217]
	v_mov_b32_dpp v228, v14 row_shr:1 row_mask:0xf bank_mask:0xf bound_ctrl:1
	v_mov_b32_dpp v229, v15 row_shr:1 row_mask:0xf bank_mask:0xf bound_ctrl:1
	v_mov_b32_dpp v246, v16 row_shr:1 row_mask:0xf bank_mask:0xf bound_ctrl:1
	v_mov_b32_dpp v247, v17 row_shr:1 row_mask:0xf bank_mask:0xf bound_ctrl:1
	v_mov_b32_dpp v226, v30 row_shl:14 row_mask:0xf bank_mask:0xf bound_ctrl:1
	v_mov_b32_dpp v227, v31 row_shl:14 row_mask:0xf bank_mask:0xf bound_ctrl:1
	v_pk_add_f32 v[218:219], v[230:231], v[218:219]
	v_pk_add_f32 v[214:215], v[222:223], v[214:215]
	v_pk_fma_f32 v[216:217], v[44:45], v[140:141], v[216:217]
	v_pk_fma_f32 v[168:169], v[42:43], v[138:139], v[168:169]
	v_mov_b32_dpp v230, v14 row_shr:2 row_mask:0xf bank_mask:0xf bound_ctrl:1
	v_mov_b32_dpp v231, v15 row_shr:2 row_mask:0xf bank_mask:0xf bound_ctrl:1
	v_pk_add_f32 v[232:233], v[232:233], v[246:247]
	v_pk_add_f32 v[224:225], v[224:225], v[228:229]
	v_mov_b32_dpp v234, v32 row_shl:14 row_mask:0xf bank_mask:0xf bound_ctrl:1
	v_mov_b32_dpp v235, v33 row_shl:14 row_mask:0xf bank_mask:0xf bound_ctrl:1
	v_pk_fma_f32 v[168:169], v[134:135], v[214:215], v[168:169]
	v_pk_fma_f32 v[214:215], v[136:137], v[218:219], v[216:217]
	v_mov_b32_dpp v248, v16 row_shr:2 row_mask:0xf bank_mask:0xf bound_ctrl:1
	v_mov_b32_dpp v249, v17 row_shr:2 row_mask:0xf bank_mask:0xf bound_ctrl:1
	v_pk_add_f32 v[226:227], v[226:227], v[230:231]
	v_pk_mul_f32 v[224:225], v[154:155], v[224:225]
	v_pk_mul_f32 v[230:231], v[156:157], v[232:233]
	v_pk_add_f32 v[222:223], v[132:133], v[214:215]
	v_pk_add_f32 v[168:169], v[130:131], v[168:169]
	v_pk_add_f32 v[228:229], v[234:235], v[248:249]
	v_pk_fma_f32 v[230:231], v[16:17], v[160:161], v[230:231]
	v_pk_fma_f32 v[224:225], v[14:15], v[158:159], v[224:225]
	v_mov_b32_dpp v208, v42 row_shl:15 row_mask:0xf bank_mask:0xf bound_ctrl:1
	v_pk_fma_f32 v[224:225], v[146:147], v[226:227], v[224:225]
	v_pk_fma_f32 v[226:227], v[148:149], v[228:229], v[230:231]
	v_mul_f32_e32 v228, 0xbfb8aa3b, v168
	v_mul_f32_e32 v229, 0xbfb8aa3b, v169
	v_mul_f32_e32 v230, 0xbfb8aa3b, v222
	v_mul_f32_e32 v231, 0xbfb8aa3b, v223
	v_exp_f32_e32 v228, v228
	v_exp_f32_e32 v229, v229
	v_exp_f32_e32 v230, v230
	v_exp_f32_e32 v231, v231
	v_add_f32_e32 v228, 1.0, v228
	v_add_f32_e32 v229, 1.0, v229
	v_add_f32_e32 v230, 1.0, v230
	v_add_f32_e32 v231, 1.0, v231
	v_rcp_f32_e32 v228, v228
	v_rcp_f32_e32 v229, v229
	v_rcp_f32_e32 v230, v230
	v_rcp_f32_e32 v231, v231
	v_pk_add_f32 v[226:227], v[152:153], v[226:227]
	v_pk_add_f32 v[224:225], v[150:151], v[224:225]
	v_pk_mul_f32 v[168:169], v[168:169], v[228:229]
	v_pk_mul_f32 v[222:223], v[222:223], v[230:231]
	v_pk_mul_f32 v[168:169], v[168:169], v[224:225]
	v_pk_mul_f32 v[222:223], v[222:223], v[226:227]
	v_cvt_pk_bf16_f32 v168, v168, v169
	v_cvt_pk_bf16_f32 v169, v222, v223
	v_or_b32_e32 v222, 32, v244
	v_mad_i64_i32 v[202:203], s[46:47], v222, s72, v[202:203]
	v_lshl_add_u64 v[202:203], v[202:203], 0, v[196:197]
	global_store_dwordx2 v[202:203], v[168:169], off sc0 sc1
	v_lshl_add_u64 v[168:169], s[26:27], 0, v[204:205]
	v_mov_b32_dpp v206, v42 row_shl:14 row_mask:0xf bank_mask:0xf bound_ctrl:1
	v_mov_b32_dpp v209, v43 row_shl:15 row_mask:0xf bank_mask:0xf bound_ctrl:1
	v_mov_b32_dpp v207, v43 row_shl:14 row_mask:0xf bank_mask:0xf bound_ctrl:1
	v_mov_b32_dpp v212, v44 row_shl:15 row_mask:0xf bank_mask:0xf bound_ctrl:1
	v_mov_b32_dpp v210, v44 row_shl:14 row_mask:0xf bank_mask:0xf bound_ctrl:1
	v_mov_b32_dpp v213, v45 row_shl:15 row_mask:0xf bank_mask:0xf bound_ctrl:1
	v_mov_b32_dpp v211, v45 row_shl:14 row_mask:0xf bank_mask:0xf bound_ctrl:1
	v_mov_b32_dpp v216, v14 row_shl:15 row_mask:0xf bank_mask:0xf bound_ctrl:1
	v_mov_b32_dpp v214, v14 row_shl:14 row_mask:0xf bank_mask:0xf bound_ctrl:1
	v_mov_b32_dpp v217, v15 row_shl:15 row_mask:0xf bank_mask:0xf bound_ctrl:1
	v_mov_b32_dpp v215, v15 row_shl:14 row_mask:0xf bank_mask:0xf bound_ctrl:1
	v_mov_b32_dpp v220, v16 row_shl:15 row_mask:0xf bank_mask:0xf bound_ctrl:1
	v_mov_b32_dpp v218, v16 row_shl:14 row_mask:0xf bank_mask:0xf bound_ctrl:1
	v_mov_b32_dpp v221, v17 row_shl:15 row_mask:0xf bank_mask:0xf bound_ctrl:1
	v_mov_b32_dpp v219, v17 row_shl:14 row_mask:0xf bank_mask:0xf bound_ctrl:1
	v_mov_b32_dpp v226, v26 row_shr:1 row_mask:0xf bank_mask:0xf bound_ctrl:1
	v_mov_b32_dpp v222, v26 row_shr:2 row_mask:0xf bank_mask:0xf bound_ctrl:1
	v_mov_b32_dpp v227, v27 row_shr:1 row_mask:0xf bank_mask:0xf bound_ctrl:1
	v_mov_b32_dpp v223, v27 row_shr:2 row_mask:0xf bank_mask:0xf bound_ctrl:1
	v_mov_b32_dpp v228, v28 row_shr:1 row_mask:0xf bank_mask:0xf bound_ctrl:1
	v_mov_b32_dpp v224, v28 row_shr:2 row_mask:0xf bank_mask:0xf bound_ctrl:1
	v_mov_b32_dpp v229, v29 row_shr:1 row_mask:0xf bank_mask:0xf bound_ctrl:1
	v_mov_b32_dpp v225, v29 row_shr:2 row_mask:0xf bank_mask:0xf bound_ctrl:1
	v_lshl_add_u64 v[196:197], v[176:177], 2, v[168:169]
	s_and_saveexec_b64 s[46:47], s[6:7]
	s_cbranch_execz .LBB0_1118
	global_store_dwordx4 v[196:197], v[26:29], off sc0 sc1
.LBB0_1118:
	s_or_b64 exec, exec, s[46:47]
	v_mov_b32_dpp v232, v6 row_shr:1 row_mask:0xf bank_mask:0xf bound_ctrl:1
	v_mov_b32_dpp v204, v6 row_shr:2 row_mask:0xf bank_mask:0xf bound_ctrl:1
	v_mov_b32_dpp v233, v7 row_shr:1 row_mask:0xf bank_mask:0xf bound_ctrl:1
	v_mov_b32_dpp v205, v7 row_shr:2 row_mask:0xf bank_mask:0xf bound_ctrl:1
	v_mov_b32_dpp v234, v8 row_shr:1 row_mask:0xf bank_mask:0xf bound_ctrl:1
	v_mov_b32_dpp v230, v8 row_shr:2 row_mask:0xf bank_mask:0xf bound_ctrl:1
	v_mov_b32_dpp v235, v9 row_shr:1 row_mask:0xf bank_mask:0xf bound_ctrl:1
	v_mov_b32_dpp v231, v9 row_shr:2 row_mask:0xf bank_mask:0xf bound_ctrl:1
	s_and_saveexec_b64 s[46:47], s[6:7]
	s_cbranch_execz .LBB0_1120
	v_add_co_u32_e32 v168, vcc, 0x5000, v196
	s_nop 1
	v_addc_co_u32_e32 v169, vcc, 0, v197, vcc
	global_store_dwordx4 v[168:169], v[6:9], off offset:2048 sc0 sc1
.LBB0_1120:
	s_or_b64 exec, exec, s[46:47]
	v_pk_add_f32 v[168:169], v[220:221], v[234:235]
	v_pk_add_f32 v[216:217], v[216:217], v[232:233]
	v_pk_mul_f32 v[156:157], v[156:157], v[168:169]
	v_pk_mul_f32 v[154:155], v[154:155], v[216:217]
	v_pk_add_f32 v[218:219], v[218:219], v[230:231]
	v_pk_add_f32 v[204:205], v[214:215], v[204:205]
	v_pk_fma_f32 v[156:157], v[8:9], v[160:161], v[156:157]
	v_pk_fma_f32 v[154:155], v[6:7], v[158:159], v[154:155]
	v_pk_fma_f32 v[148:149], v[148:149], v[218:219], v[156:157]
	v_pk_fma_f32 v[146:147], v[146:147], v[204:205], v[154:155]
	v_pk_add_f32 v[148:149], v[152:153], v[148:149]
	v_pk_add_f32 v[146:147], v[150:151], v[146:147]
	v_pk_add_f32 v[150:151], v[212:213], v[228:229]
	v_pk_add_f32 v[152:153], v[208:209], v[226:227]
	v_pk_mul_f32 v[144:145], v[144:145], v[150:151]
	v_pk_mul_f32 v[142:143], v[142:143], v[152:153]
	v_pk_add_f32 v[154:155], v[210:211], v[224:225]
	v_pk_add_f32 v[156:157], v[206:207], v[222:223]
	v_pk_fma_f32 v[140:141], v[28:29], v[140:141], v[144:145]
	v_pk_fma_f32 v[138:139], v[26:27], v[138:139], v[142:143]
	v_pk_fma_f32 v[136:137], v[136:137], v[154:155], v[140:141]
	v_pk_fma_f32 v[134:135], v[134:135], v[156:157], v[138:139]
	v_pk_add_f32 v[132:133], v[132:133], v[136:137]
	v_pk_add_f32 v[130:131], v[130:131], v[134:135]
	v_mul_f32_e32 v136, 0xbfb8aa3b, v132
	v_mul_f32_e32 v134, 0xbfb8aa3b, v130
	v_mul_f32_e32 v135, 0xbfb8aa3b, v131
	v_mul_f32_e32 v137, 0xbfb8aa3b, v133
	v_exp_f32_e32 v134, v134
	v_exp_f32_e32 v135, v135
	v_exp_f32_e32 v136, v136
	v_exp_f32_e32 v137, v137
	v_add_f32_e32 v134, 1.0, v134
	v_add_f32_e32 v135, 1.0, v135
	v_add_f32_e32 v136, 1.0, v136
	v_add_f32_e32 v137, 1.0, v137
	v_rcp_f32_e32 v134, v134
	v_rcp_f32_e32 v135, v135
	v_rcp_f32_e32 v136, v136
	v_rcp_f32_e32 v137, v137
	v_mov_b32_dpp v216, v122 row_shr:1 row_mask:0xf bank_mask:0xf bound_ctrl:1
	v_pk_mul_f32 v[130:131], v[130:131], v[134:135]
	v_or_b32_e32 v134, 48, v244
	v_pk_mul_f32 v[132:133], v[132:133], v[136:137]
	v_pk_mul_f32 v[130:131], v[130:131], v[146:147]
	v_pk_mul_f32 v[132:133], v[132:133], v[148:149]
	v_cvt_pk_bf16_f32 v130, v130, v131
	v_cvt_pk_bf16_f32 v131, v132, v133
	v_mov_b64_e32 v[132:133], s[22:23]
	v_mad_i64_i32 v[132:133], s[46:47], v134, s72, v[132:133]
	v_lshl_add_u64 v[204:205], v[176:177], 1, v[132:133]
	global_store_dwordx2 v[204:205], v[130:131], off sc0 sc1
	v_or_b32_e32 v130, 16, v176
	v_add_co_u32_e32 v146, vcc, s70, v186
	v_ashrrev_i32_e32 v131, 31, v130
	s_nop 0
	v_addc_co_u32_e32 v147, vcc, 0, v187, vcc
	v_lshlrev_b64 v[130:131], 2, v[130:131]
	v_add_co_u32_e32 v150, vcc, s70, v184
	v_lshl_add_u64 v[132:133], s[30:31], 0, v[130:131]
	v_lshl_add_u64 v[130:131], s[34:35], 0, v[130:131]
	v_addc_co_u32_e32 v151, vcc, 0, v185, vcc
	global_load_dwordx4 v[134:137], v[186:187], off offset:64
	global_load_dwordx4 v[142:145], v[132:133], off
	global_load_dwordx4 v[138:141], v[130:131], off
	s_nop 0
	global_load_dwordx4 v[130:133], v[180:181], off offset:64
	s_nop 0
	global_load_dwordx4 v[146:149], v[146:147], off offset:2112
	s_nop 0
	global_load_dwordx4 v[158:161], v[150:151], off offset:2112
	v_add_co_u32_e32 v150, vcc, s70, v182
	v_mov_b32_dpp v214, v122 row_shr:2 row_mask:0xf bank_mask:0xf bound_ctrl:1
	s_nop 0
	v_addc_co_u32_e32 v151, vcc, 0, v183, vcc
	global_load_dwordx4 v[154:157], v[150:151], off offset:2112
	v_add_co_u32_e32 v150, vcc, s70, v180
	v_mov_b32_dpp v208, v122 row_shl:15 row_mask:0xf bank_mask:0xf bound_ctrl:1
	s_nop 0
	v_addc_co_u32_e32 v151, vcc, 0, v181, vcc
	global_load_dwordx4 v[150:153], v[150:151], off offset:2112
	v_mov_b32_dpp v206, v122 row_shl:14 row_mask:0xf bank_mask:0xf bound_ctrl:1
	v_mov_b32_dpp v217, v123 row_shr:1 row_mask:0xf bank_mask:0xf bound_ctrl:1
	v_mov_b32_dpp v215, v123 row_shr:2 row_mask:0xf bank_mask:0xf bound_ctrl:1
	v_mov_b32_dpp v209, v123 row_shl:15 row_mask:0xf bank_mask:0xf bound_ctrl:1
	v_mov_b32_dpp v207, v123 row_shl:14 row_mask:0xf bank_mask:0xf bound_ctrl:1
	v_mov_b32_dpp v220, v124 row_shr:1 row_mask:0xf bank_mask:0xf bound_ctrl:1
	v_mov_b32_dpp v218, v124 row_shr:2 row_mask:0xf bank_mask:0xf bound_ctrl:1
	v_mov_b32_dpp v212, v124 row_shl:15 row_mask:0xf bank_mask:0xf bound_ctrl:1
	v_mov_b32_dpp v210, v124 row_shl:14 row_mask:0xf bank_mask:0xf bound_ctrl:1
	v_mov_b32_dpp v221, v125 row_shr:1 row_mask:0xf bank_mask:0xf bound_ctrl:1
	v_mov_b32_dpp v219, v125 row_shr:2 row_mask:0xf bank_mask:0xf bound_ctrl:1
	v_mov_b32_dpp v213, v125 row_shl:15 row_mask:0xf bank_mask:0xf bound_ctrl:1
	v_mov_b32_dpp v211, v125 row_shl:14 row_mask:0xf bank_mask:0xf bound_ctrl:1
	s_and_saveexec_b64 s[46:47], s[4:5]
	s_cbranch_execz .LBB0_1122
	global_store_dwordx4 v[178:179], v[122:125], off offset:64 sc0 sc1
.LBB0_1122:
	s_or_b64 exec, exec, s[46:47]
	v_mov_b32_dpp v224, v102 row_shr:1 row_mask:0xf bank_mask:0xf bound_ctrl:1
	v_mov_b32_dpp v222, v102 row_shr:2 row_mask:0xf bank_mask:0xf bound_ctrl:1
	v_mov_b32_dpp v182, v102 row_shl:15 row_mask:0xf bank_mask:0xf bound_ctrl:1
	v_mov_b32_dpp v180, v102 row_shl:14 row_mask:0xf bank_mask:0xf bound_ctrl:1
	v_mov_b32_dpp v225, v103 row_shr:1 row_mask:0xf bank_mask:0xf bound_ctrl:1
	v_mov_b32_dpp v223, v103 row_shr:2 row_mask:0xf bank_mask:0xf bound_ctrl:1
	v_mov_b32_dpp v183, v103 row_shl:15 row_mask:0xf bank_mask:0xf bound_ctrl:1
	v_mov_b32_dpp v181, v103 row_shl:14 row_mask:0xf bank_mask:0xf bound_ctrl:1
	v_mov_b32_dpp v228, v104 row_shr:1 row_mask:0xf bank_mask:0xf bound_ctrl:1
	v_mov_b32_dpp v226, v104 row_shr:2 row_mask:0xf bank_mask:0xf bound_ctrl:1
	v_mov_b32_dpp v186, v104 row_shl:15 row_mask:0xf bank_mask:0xf bound_ctrl:1
	v_mov_b32_dpp v184, v104 row_shl:14 row_mask:0xf bank_mask:0xf bound_ctrl:1
	v_mov_b32_dpp v229, v105 row_shr:1 row_mask:0xf bank_mask:0xf bound_ctrl:1
	v_mov_b32_dpp v227, v105 row_shr:2 row_mask:0xf bank_mask:0xf bound_ctrl:1
	v_mov_b32_dpp v187, v105 row_shl:15 row_mask:0xf bank_mask:0xf bound_ctrl:1
	v_mov_b32_dpp v185, v105 row_shl:14 row_mask:0xf bank_mask:0xf bound_ctrl:1
	s_and_saveexec_b64 s[46:47], s[4:5]
	s_cbranch_execz .LBB0_1124
	v_add_co_u32_e32 v168, vcc, 0x5000, v178
	s_nop 1
	v_addc_co_u32_e32 v169, vcc, 0, v179, vcc
	global_store_dwordx4 v[168:169], v[102:105], off offset:2112 sc0 sc1
.LBB0_1124:
	s_or_b64 exec, exec, s[46:47]
	s_and_saveexec_b64 s[46:47], s[8:9]
	s_cbranch_execz .LBB0_1126
	v_pk_add_f32 v[216:217], v[216:217], 0 op_sel_hi:[1,0]
	v_pk_add_f32 v[220:221], v[220:221], 0 op_sel_hi:[1,0]
	s_waitcnt vmcnt(0)
	v_pk_mul_f32 v[216:217], v[142:143], v[216:217]
	v_pk_add_f32 v[214:215], v[214:215], 0 op_sel_hi:[1,0]
	v_pk_mul_f32 v[220:221], v[144:145], v[220:221]
	v_pk_fma_f32 v[216:217], v[122:123], v[138:139], v[216:217]
	v_pk_add_f32 v[218:219], v[218:219], 0 op_sel_hi:[1,0]
	v_pk_fma_f32 v[220:221], v[124:125], v[140:141], v[220:221]
	v_pk_fma_f32 v[214:215], v[134:135], v[214:215], v[216:217]
	v_pk_fma_f32 v[216:217], v[136:137], v[218:219], v[220:221]
	v_pk_add_f32 v[214:215], v[130:131], v[214:215]
	v_pk_add_f32 v[216:217], v[132:133], v[216:217]
	v_mul_f32_e32 v218, 0xbfb8aa3b, v214
	v_mul_f32_e32 v219, 0xbfb8aa3b, v215
	v_exp_f32_e32 v218, v218
	v_exp_f32_e32 v219, v219
	v_mul_f32_e32 v220, 0xbfb8aa3b, v216
	v_mul_f32_e32 v221, 0xbfb8aa3b, v217
	v_exp_f32_e32 v220, v220
	v_exp_f32_e32 v221, v221
	v_add_f32_e32 v218, 1.0, v218
	v_add_f32_e32 v219, 1.0, v219
	v_pk_add_f32 v[168:169], v[224:225], 0 op_sel_hi:[1,0]
	v_rcp_f32_e32 v218, v218
	v_rcp_f32_e32 v219, v219
	v_add_f32_e32 v220, 1.0, v220
	v_add_f32_e32 v221, 1.0, v221
	v_pk_add_f32 v[178:179], v[228:229], 0 op_sel_hi:[1,0]
	v_pk_mul_f32 v[168:169], v[158:159], v[168:169]
	v_rcp_f32_e32 v220, v220
	v_rcp_f32_e32 v221, v221
	v_pk_add_f32 v[222:223], v[222:223], 0 op_sel_hi:[1,0]
	v_pk_mul_f32 v[178:179], v[160:161], v[178:179]
	v_pk_fma_f32 v[168:169], v[102:103], v[154:155], v[168:169]
	v_pk_add_f32 v[224:225], v[226:227], 0 op_sel_hi:[1,0]
	v_pk_fma_f32 v[178:179], v[104:105], v[156:157], v[178:179]
	v_pk_fma_f32 v[168:169], v[146:147], v[222:223], v[168:169]
	v_pk_fma_f32 v[178:179], v[148:149], v[224:225], v[178:179]
	v_pk_add_f32 v[168:169], v[150:151], v[168:169]
	v_pk_mul_f32 v[214:215], v[214:215], v[218:219]
	v_pk_add_f32 v[178:179], v[152:153], v[178:179]
	v_pk_mul_f32 v[168:169], v[214:215], v[168:169]
	v_pk_mul_f32 v[214:215], v[216:217], v[220:221]
	v_cvt_pk_bf16_f32 v168, v168, v169
	v_pk_mul_f32 v[178:179], v[214:215], v[178:179]
	s_nop 0
	v_cvt_pk_bf16_f32 v169, v178, v179
	v_mov_b64_e32 v[178:179], s[22:23]
	v_mad_i64_i32 v[178:179], s[48:49], v243, s72, v[178:179]
	v_lshl_add_u64 v[178:179], v[176:177], 1, v[178:179]
	global_store_dwordx2 v[178:179], v[168:169], off offset:32 sc0 sc1
.LBB0_1126:
	s_or_b64 exec, exec, s[46:47]
	v_mov_b32_dpp v168, v114 row_shr:1 row_mask:0xf bank_mask:0xf bound_ctrl:1
	v_mov_b32_dpp v169, v115 row_shr:1 row_mask:0xf bank_mask:0xf bound_ctrl:1
	v_mov_b32_dpp v218, v116 row_shr:1 row_mask:0xf bank_mask:0xf bound_ctrl:1
	v_mov_b32_dpp v219, v117 row_shr:1 row_mask:0xf bank_mask:0xf bound_ctrl:1
	v_mov_b32_dpp v178, v114 row_shr:2 row_mask:0xf bank_mask:0xf bound_ctrl:1
	v_mov_b32_dpp v179, v115 row_shr:2 row_mask:0xf bank_mask:0xf bound_ctrl:1
	v_pk_add_f32 v[212:213], v[212:213], v[218:219]
	v_pk_add_f32 v[168:169], v[208:209], v[168:169]
	v_mov_b32_dpp v220, v116 row_shr:2 row_mask:0xf bank_mask:0xf bound_ctrl:1
	v_mov_b32_dpp v221, v117 row_shr:2 row_mask:0xf bank_mask:0xf bound_ctrl:1
	v_pk_add_f32 v[178:179], v[206:207], v[178:179]
	s_waitcnt vmcnt(0)
	v_pk_mul_f32 v[168:169], v[142:143], v[168:169]
	v_pk_mul_f32 v[206:207], v[144:145], v[212:213]
	v_pk_add_f32 v[208:209], v[210:211], v[220:221]
	v_pk_fma_f32 v[206:207], v[116:117], v[140:141], v[206:207]
	v_pk_fma_f32 v[168:169], v[114:115], v[138:139], v[168:169]
	v_mov_b32_dpp v218, v88 row_shr:1 row_mask:0xf bank_mask:0xf bound_ctrl:1
	v_pk_fma_f32 v[168:169], v[134:135], v[178:179], v[168:169]
	v_pk_fma_f32 v[178:179], v[136:137], v[208:209], v[206:207]
	v_mov_b32_dpp v206, v86 row_shr:1 row_mask:0xf bank_mask:0xf bound_ctrl:1
	v_mov_b32_dpp v207, v87 row_shr:1 row_mask:0xf bank_mask:0xf bound_ctrl:1
	v_mov_b32_dpp v219, v89 row_shr:1 row_mask:0xf bank_mask:0xf bound_ctrl:1
	v_pk_add_f32 v[186:187], v[186:187], v[218:219]
	v_pk_add_f32 v[182:183], v[182:183], v[206:207]
	v_mov_b32_dpp v208, v86 row_shr:2 row_mask:0xf bank_mask:0xf bound_ctrl:1
	v_mov_b32_dpp v209, v87 row_shr:2 row_mask:0xf bank_mask:0xf bound_ctrl:1
	v_mov_b32_dpp v220, v88 row_shr:2 row_mask:0xf bank_mask:0xf bound_ctrl:1
	v_mov_b32_dpp v221, v89 row_shr:2 row_mask:0xf bank_mask:0xf bound_ctrl:1
	v_pk_mul_f32 v[182:183], v[158:159], v[182:183]
	v_pk_mul_f32 v[186:187], v[160:161], v[186:187]
	v_pk_add_f32 v[178:179], v[132:133], v[178:179]
	v_pk_add_f32 v[168:169], v[130:131], v[168:169]
	v_pk_add_f32 v[184:185], v[184:185], v[220:221]
	v_pk_add_f32 v[180:181], v[180:181], v[208:209]
	v_pk_fma_f32 v[186:187], v[88:89], v[156:157], v[186:187]
	v_pk_fma_f32 v[182:183], v[86:87], v[154:155], v[182:183]
	v_mov_b32_dpp v214, v114 row_shl:15 row_mask:0xf bank_mask:0xf bound_ctrl:1
	v_pk_fma_f32 v[180:181], v[146:147], v[180:181], v[182:183]
	v_pk_fma_f32 v[182:183], v[148:149], v[184:185], v[186:187]
	v_mul_f32_e32 v184, 0xbfb8aa3b, v168
	v_mul_f32_e32 v185, 0xbfb8aa3b, v169
	v_mul_f32_e32 v186, 0xbfb8aa3b, v178
	v_mul_f32_e32 v187, 0xbfb8aa3b, v179
	v_exp_f32_e32 v184, v184
	v_exp_f32_e32 v185, v185
	v_exp_f32_e32 v186, v186
	v_exp_f32_e32 v187, v187
	v_add_f32_e32 v184, 1.0, v184
	v_add_f32_e32 v185, 1.0, v185
	v_add_f32_e32 v186, 1.0, v186
	v_add_f32_e32 v187, 1.0, v187
	v_rcp_f32_e32 v184, v184
	v_rcp_f32_e32 v185, v185
	v_rcp_f32_e32 v186, v186
	v_rcp_f32_e32 v187, v187
	v_pk_add_f32 v[182:183], v[152:153], v[182:183]
	v_pk_add_f32 v[180:181], v[150:151], v[180:181]
	v_pk_mul_f32 v[168:169], v[168:169], v[184:185]
	v_pk_mul_f32 v[178:179], v[178:179], v[186:187]
	v_pk_mul_f32 v[168:169], v[168:169], v[180:181]
	v_pk_mul_f32 v[178:179], v[178:179], v[182:183]
	v_cvt_pk_bf16_f32 v168, v168, v169
	v_cvt_pk_bf16_f32 v169, v178, v179
	v_mov_b32_dpp v215, v115 row_shl:15 row_mask:0xf bank_mask:0xf bound_ctrl:1
	global_store_dwordx2 v[192:193], v[168:169], off offset:32 sc0 sc1
	v_mov_b32_dpp v168, v98 row_shr:1 row_mask:0xf bank_mask:0xf bound_ctrl:1
	v_mov_b32_dpp v169, v99 row_shr:1 row_mask:0xf bank_mask:0xf bound_ctrl:1
	v_mov_b32_dpp v216, v114 row_shl:14 row_mask:0xf bank_mask:0xf bound_ctrl:1
	v_mov_b32_dpp v217, v115 row_shl:14 row_mask:0xf bank_mask:0xf bound_ctrl:1
	v_mov_b32_dpp v222, v116 row_shl:15 row_mask:0xf bank_mask:0xf bound_ctrl:1
	v_mov_b32_dpp v223, v117 row_shl:15 row_mask:0xf bank_mask:0xf bound_ctrl:1
	v_mov_b32_dpp v186, v98 row_shr:2 row_mask:0xf bank_mask:0xf bound_ctrl:1
	v_mov_b32_dpp v187, v99 row_shr:2 row_mask:0xf bank_mask:0xf bound_ctrl:1
	v_mov_b32_dpp v192, v100 row_shr:1 row_mask:0xf bank_mask:0xf bound_ctrl:1
	v_mov_b32_dpp v193, v101 row_shr:1 row_mask:0xf bank_mask:0xf bound_ctrl:1
	v_pk_add_f32 v[168:169], v[214:215], v[168:169]
	v_mov_b32_dpp v210, v86 row_shl:15 row_mask:0xf bank_mask:0xf bound_ctrl:1
	v_mov_b32_dpp v211, v87 row_shl:15 row_mask:0xf bank_mask:0xf bound_ctrl:1
	v_mov_b32_dpp v226, v88 row_shl:15 row_mask:0xf bank_mask:0xf bound_ctrl:1
	v_mov_b32_dpp v227, v89 row_shl:15 row_mask:0xf bank_mask:0xf bound_ctrl:1
	v_pk_add_f32 v[192:193], v[222:223], v[192:193]
	v_pk_add_f32 v[186:187], v[216:217], v[186:187]
	v_pk_mul_f32 v[168:169], v[142:143], v[168:169]
	v_mov_b32_dpp v216, v74 row_shr:1 row_mask:0xf bank_mask:0xf bound_ctrl:1
	v_mov_b32_dpp v217, v75 row_shr:1 row_mask:0xf bank_mask:0xf bound_ctrl:1
	v_mov_b32_dpp v220, v76 row_shr:1 row_mask:0xf bank_mask:0xf bound_ctrl:1
	v_mov_b32_dpp v221, v77 row_shr:1 row_mask:0xf bank_mask:0xf bound_ctrl:1
	v_mov_b32_dpp v224, v116 row_shl:14 row_mask:0xf bank_mask:0xf bound_ctrl:1
	v_mov_b32_dpp v225, v117 row_shl:14 row_mask:0xf bank_mask:0xf bound_ctrl:1
	v_mov_b32_dpp v212, v86 row_shl:14 row_mask:0xf bank_mask:0xf bound_ctrl:1
	v_mov_b32_dpp v213, v87 row_shl:14 row_mask:0xf bank_mask:0xf bound_ctrl:1
	v_mov_b32_dpp v206, v100 row_shr:2 row_mask:0xf bank_mask:0xf bound_ctrl:1
	v_mov_b32_dpp v207, v101 row_shr:2 row_mask:0xf bank_mask:0xf bound_ctrl:1
	v_pk_mul_f32 v[192:193], v[144:145], v[192:193]
	v_pk_fma_f32 v[168:169], v[98:99], v[138:139], v[168:169]
	v_mov_b32_dpp v218, v74 row_shr:2 row_mask:0xf bank_mask:0xf bound_ctrl:1
	v_mov_b32_dpp v219, v75 row_shr:2 row_mask:0xf bank_mask:0xf bound_ctrl:1
	v_pk_add_f32 v[220:221], v[226:227], v[220:221]
	v_pk_add_f32 v[210:211], v[210:211], v[216:217]
	v_mov_b32_dpp v228, v88 row_shl:14 row_mask:0xf bank_mask:0xf bound_ctrl:1
	v_mov_b32_dpp v229, v89 row_shl:14 row_mask:0xf bank_mask:0xf bound_ctrl:1
	v_pk_add_f32 v[206:207], v[224:225], v[206:207]
	v_pk_fma_f32 v[192:193], v[100:101], v[140:141], v[192:193]
	v_pk_fma_f32 v[168:169], v[134:135], v[186:187], v[168:169]
	v_mov_b32_dpp v222, v76 row_shr:2 row_mask:0xf bank_mask:0xf bound_ctrl:1
	v_mov_b32_dpp v223, v77 row_shr:2 row_mask:0xf bank_mask:0xf bound_ctrl:1
	v_pk_add_f32 v[212:213], v[212:213], v[218:219]
	v_pk_mul_f32 v[210:211], v[158:159], v[210:211]
	v_pk_mul_f32 v[218:219], v[160:161], v[220:221]
	v_pk_fma_f32 v[186:187], v[136:137], v[206:207], v[192:193]
	v_pk_add_f32 v[168:169], v[130:131], v[168:169]
	v_pk_add_f32 v[216:217], v[228:229], v[222:223]
	v_pk_fma_f32 v[218:219], v[76:77], v[156:157], v[218:219]
	v_pk_fma_f32 v[210:211], v[74:75], v[154:155], v[210:211]
	v_pk_add_f32 v[214:215], v[132:133], v[186:187]
	v_pk_fma_f32 v[210:211], v[146:147], v[212:213], v[210:211]
	v_pk_fma_f32 v[212:213], v[148:149], v[216:217], v[218:219]
	v_mul_f32_e32 v216, 0xbfb8aa3b, v168
	v_mul_f32_e32 v217, 0xbfb8aa3b, v169
	v_exp_f32_e32 v216, v216
	v_exp_f32_e32 v217, v217
	v_mul_f32_e32 v218, 0xbfb8aa3b, v214
	v_mul_f32_e32 v219, 0xbfb8aa3b, v215
	v_exp_f32_e32 v218, v218
	v_exp_f32_e32 v219, v219
	v_add_f32_e32 v216, 1.0, v216
	v_add_f32_e32 v217, 1.0, v217
	v_rcp_f32_e32 v216, v216
	v_rcp_f32_e32 v217, v217
	v_add_f32_e32 v218, 1.0, v218
	v_add_f32_e32 v219, 1.0, v219
	v_rcp_f32_e32 v218, v218
	v_rcp_f32_e32 v219, v219
	v_pk_add_f32 v[210:211], v[150:151], v[210:211]
	v_pk_mul_f32 v[168:169], v[168:169], v[216:217]
	v_pk_add_f32 v[212:213], v[152:153], v[212:213]
	v_pk_mul_f32 v[168:169], v[168:169], v[210:211]
	v_pk_mul_f32 v[210:211], v[214:215], v[218:219]
	v_cvt_pk_bf16_f32 v168, v168, v169
	v_pk_mul_f32 v[210:211], v[210:211], v[212:213]
	v_mov_b32_dpp v180, v98 row_shl:15 row_mask:0xf bank_mask:0xf bound_ctrl:1
	v_cvt_pk_bf16_f32 v169, v210, v211
	v_mov_b32_dpp v178, v98 row_shl:14 row_mask:0xf bank_mask:0xf bound_ctrl:1
	v_mov_b32_dpp v181, v99 row_shl:15 row_mask:0xf bank_mask:0xf bound_ctrl:1
	v_mov_b32_dpp v179, v99 row_shl:14 row_mask:0xf bank_mask:0xf bound_ctrl:1
	v_mov_b32_dpp v184, v100 row_shl:15 row_mask:0xf bank_mask:0xf bound_ctrl:1
	v_mov_b32_dpp v182, v100 row_shl:14 row_mask:0xf bank_mask:0xf bound_ctrl:1
	v_mov_b32_dpp v185, v101 row_shl:15 row_mask:0xf bank_mask:0xf bound_ctrl:1
	v_mov_b32_dpp v183, v101 row_shl:14 row_mask:0xf bank_mask:0xf bound_ctrl:1
	v_mov_b32_dpp v192, v74 row_shl:15 row_mask:0xf bank_mask:0xf bound_ctrl:1
	v_mov_b32_dpp v186, v74 row_shl:14 row_mask:0xf bank_mask:0xf bound_ctrl:1
	v_mov_b32_dpp v193, v75 row_shl:15 row_mask:0xf bank_mask:0xf bound_ctrl:1
	v_mov_b32_dpp v187, v75 row_shl:14 row_mask:0xf bank_mask:0xf bound_ctrl:1
	v_mov_b32_dpp v208, v76 row_shl:15 row_mask:0xf bank_mask:0xf bound_ctrl:1
	v_mov_b32_dpp v206, v76 row_shl:14 row_mask:0xf bank_mask:0xf bound_ctrl:1
	v_mov_b32_dpp v209, v77 row_shl:15 row_mask:0xf bank_mask:0xf bound_ctrl:1
	v_mov_b32_dpp v207, v77 row_shl:14 row_mask:0xf bank_mask:0xf bound_ctrl:1
	global_store_dwordx2 v[194:195], v[168:169], off offset:32 sc0 sc1
	v_mov_b32_dpp v212, v82 row_shr:1 row_mask:0xf bank_mask:0xf bound_ctrl:1
	v_mov_b32_dpp v194, v82 row_shr:2 row_mask:0xf bank_mask:0xf bound_ctrl:1
	v_mov_b32_dpp v213, v83 row_shr:1 row_mask:0xf bank_mask:0xf bound_ctrl:1
	v_mov_b32_dpp v195, v83 row_shr:2 row_mask:0xf bank_mask:0xf bound_ctrl:1
	v_mov_b32_dpp v214, v84 row_shr:1 row_mask:0xf bank_mask:0xf bound_ctrl:1
	v_mov_b32_dpp v210, v84 row_shr:2 row_mask:0xf bank_mask:0xf bound_ctrl:1
	v_mov_b32_dpp v215, v85 row_shr:1 row_mask:0xf bank_mask:0xf bound_ctrl:1
	v_mov_b32_dpp v211, v85 row_shr:2 row_mask:0xf bank_mask:0xf bound_ctrl:1
	s_and_saveexec_b64 s[46:47], s[6:7]
	s_cbranch_execz .LBB0_1128
	global_store_dwordx4 v[188:189], v[82:85], off offset:64 sc0 sc1
.LBB0_1128:
	s_or_b64 exec, exec, s[46:47]
	v_mov_b32_dpp v220, v66 row_shr:1 row_mask:0xf bank_mask:0xf bound_ctrl:1
	v_mov_b32_dpp v216, v66 row_shr:2 row_mask:0xf bank_mask:0xf bound_ctrl:1
	v_mov_b32_dpp v221, v67 row_shr:1 row_mask:0xf bank_mask:0xf bound_ctrl:1
	v_mov_b32_dpp v217, v67 row_shr:2 row_mask:0xf bank_mask:0xf bound_ctrl:1
	v_mov_b32_dpp v222, v68 row_shr:1 row_mask:0xf bank_mask:0xf bound_ctrl:1
	v_mov_b32_dpp v218, v68 row_shr:2 row_mask:0xf bank_mask:0xf bound_ctrl:1
	v_mov_b32_dpp v223, v69 row_shr:1 row_mask:0xf bank_mask:0xf bound_ctrl:1
	v_mov_b32_dpp v219, v69 row_shr:2 row_mask:0xf bank_mask:0xf bound_ctrl:1
	s_and_saveexec_b64 s[46:47], s[6:7]
	s_cbranch_execz .LBB0_1130
	v_add_co_u32_e32 v168, vcc, 0x5000, v188
	s_nop 1
	v_addc_co_u32_e32 v169, vcc, 0, v189, vcc
	global_store_dwordx4 v[168:169], v[66:69], off offset:2112 sc0 sc1
.LBB0_1130:
	s_or_b64 exec, exec, s[46:47]
	v_pk_add_f32 v[184:185], v[184:185], v[214:215]
	v_pk_add_f32 v[180:181], v[180:181], v[212:213]
	v_pk_mul_f32 v[184:185], v[144:145], v[184:185]
	v_pk_mul_f32 v[180:181], v[142:143], v[180:181]
	v_pk_add_f32 v[182:183], v[182:183], v[210:211]
	v_pk_add_f32 v[178:179], v[178:179], v[194:195]
	v_pk_fma_f32 v[184:185], v[84:85], v[140:141], v[184:185]
	v_pk_fma_f32 v[180:181], v[82:83], v[138:139], v[180:181]
	v_pk_add_f32 v[168:169], v[208:209], v[222:223]
	v_pk_fma_f32 v[178:179], v[134:135], v[178:179], v[180:181]
	v_pk_fma_f32 v[180:181], v[136:137], v[182:183], v[184:185]
	v_pk_add_f32 v[178:179], v[130:131], v[178:179]
	v_pk_add_f32 v[180:181], v[132:133], v[180:181]
	v_mul_f32_e32 v182, 0xbfb8aa3b, v178
	v_mul_f32_e32 v183, 0xbfb8aa3b, v179
	v_mul_f32_e32 v184, 0xbfb8aa3b, v180
	v_mul_f32_e32 v185, 0xbfb8aa3b, v181
	v_exp_f32_e32 v182, v182
	v_exp_f32_e32 v183, v183
	v_exp_f32_e32 v184, v184
	v_exp_f32_e32 v185, v185
	v_add_f32_e32 v182, 1.0, v182
	v_add_f32_e32 v183, 1.0, v183
	v_add_f32_e32 v184, 1.0, v184
	v_add_f32_e32 v185, 1.0, v185
	v_pk_add_f32 v[188:189], v[192:193], v[220:221]
	v_rcp_f32_e32 v182, v182
	v_rcp_f32_e32 v183, v183
	v_rcp_f32_e32 v184, v184
	v_rcp_f32_e32 v185, v185
	v_pk_mul_f32 v[188:189], v[158:159], v[188:189]
	v_pk_mul_f32 v[168:169], v[160:161], v[168:169]
	v_pk_add_f32 v[192:193], v[206:207], v[218:219]
	v_pk_add_f32 v[186:187], v[186:187], v[216:217]
	v_pk_fma_f32 v[168:169], v[68:69], v[156:157], v[168:169]
	v_pk_fma_f32 v[188:189], v[66:67], v[154:155], v[188:189]
	v_pk_fma_f32 v[168:169], v[148:149], v[192:193], v[168:169]
	v_pk_fma_f32 v[186:187], v[146:147], v[186:187], v[188:189]
	v_pk_add_f32 v[168:169], v[152:153], v[168:169]
	v_pk_add_f32 v[186:187], v[150:151], v[186:187]
	v_pk_mul_f32 v[178:179], v[178:179], v[182:183]
	v_pk_mul_f32 v[180:181], v[180:181], v[184:185]
	v_pk_mul_f32 v[178:179], v[178:179], v[186:187]
	v_pk_mul_f32 v[168:169], v[180:181], v[168:169]
	v_cvt_pk_bf16_f32 v178, v178, v179
	v_cvt_pk_bf16_f32 v179, v168, v169
	global_store_dwordx2 v[198:199], v[178:179], off offset:32 sc0 sc1
	v_mov_b32_dpp v206, v58 row_shr:1 row_mask:0xf bank_mask:0xf bound_ctrl:1
	v_mov_b32_dpp v198, v58 row_shr:2 row_mask:0xf bank_mask:0xf bound_ctrl:1
	v_mov_b32_dpp v188, v58 row_shl:15 row_mask:0xf bank_mask:0xf bound_ctrl:1
	v_mov_b32_dpp v186, v58 row_shl:14 row_mask:0xf bank_mask:0xf bound_ctrl:1
	v_mov_b32_dpp v207, v59 row_shr:1 row_mask:0xf bank_mask:0xf bound_ctrl:1
	v_mov_b32_dpp v199, v59 row_shr:2 row_mask:0xf bank_mask:0xf bound_ctrl:1
	v_mov_b32_dpp v189, v59 row_shl:15 row_mask:0xf bank_mask:0xf bound_ctrl:1
	v_mov_b32_dpp v187, v59 row_shl:14 row_mask:0xf bank_mask:0xf bound_ctrl:1
	v_mov_b32_dpp v210, v60 row_shr:1 row_mask:0xf bank_mask:0xf bound_ctrl:1
	v_mov_b32_dpp v208, v60 row_shr:2 row_mask:0xf bank_mask:0xf bound_ctrl:1
	v_mov_b32_dpp v194, v60 row_shl:15 row_mask:0xf bank_mask:0xf bound_ctrl:1
	v_mov_b32_dpp v192, v60 row_shl:14 row_mask:0xf bank_mask:0xf bound_ctrl:1
	v_mov_b32_dpp v211, v61 row_shr:1 row_mask:0xf bank_mask:0xf bound_ctrl:1
	v_mov_b32_dpp v209, v61 row_shr:2 row_mask:0xf bank_mask:0xf bound_ctrl:1
	v_mov_b32_dpp v195, v61 row_shl:15 row_mask:0xf bank_mask:0xf bound_ctrl:1
	v_mov_b32_dpp v193, v61 row_shl:14 row_mask:0xf bank_mask:0xf bound_ctrl:1
	s_and_saveexec_b64 s[46:47], s[4:5]
	s_cbranch_execz .LBB0_1132
	global_store_dwordx4 v[190:191], v[58:61], off offset:64 sc0 sc1
.LBB0_1132:
	s_or_b64 exec, exec, s[46:47]
	v_mov_b32_dpp v214, v38 row_shr:1 row_mask:0xf bank_mask:0xf bound_ctrl:1
	v_mov_b32_dpp v212, v38 row_shr:2 row_mask:0xf bank_mask:0xf bound_ctrl:1
	v_mov_b32_dpp v180, v38 row_shl:15 row_mask:0xf bank_mask:0xf bound_ctrl:1
	v_mov_b32_dpp v178, v38 row_shl:14 row_mask:0xf bank_mask:0xf bound_ctrl:1
	v_mov_b32_dpp v215, v39 row_shr:1 row_mask:0xf bank_mask:0xf bound_ctrl:1
	v_mov_b32_dpp v213, v39 row_shr:2 row_mask:0xf bank_mask:0xf bound_ctrl:1
	v_mov_b32_dpp v181, v39 row_shl:15 row_mask:0xf bank_mask:0xf bound_ctrl:1
	v_mov_b32_dpp v179, v39 row_shl:14 row_mask:0xf bank_mask:0xf bound_ctrl:1
	v_mov_b32_dpp v218, v40 row_shr:1 row_mask:0xf bank_mask:0xf bound_ctrl:1
	v_mov_b32_dpp v216, v40 row_shr:2 row_mask:0xf bank_mask:0xf bound_ctrl:1
	v_mov_b32_dpp v184, v40 row_shl:15 row_mask:0xf bank_mask:0xf bound_ctrl:1
	v_mov_b32_dpp v182, v40 row_shl:14 row_mask:0xf bank_mask:0xf bound_ctrl:1
	v_mov_b32_dpp v219, v41 row_shr:1 row_mask:0xf bank_mask:0xf bound_ctrl:1
	v_mov_b32_dpp v217, v41 row_shr:2 row_mask:0xf bank_mask:0xf bound_ctrl:1
	v_mov_b32_dpp v185, v41 row_shl:15 row_mask:0xf bank_mask:0xf bound_ctrl:1
	v_mov_b32_dpp v183, v41 row_shl:14 row_mask:0xf bank_mask:0xf bound_ctrl:1
	s_and_saveexec_b64 s[46:47], s[4:5]
	s_cbranch_execz .LBB0_1134
	v_add_co_u32_e32 v168, vcc, 0x5000, v190
	s_nop 1
	v_addc_co_u32_e32 v169, vcc, 0, v191, vcc
	global_store_dwordx4 v[168:169], v[38:41], off offset:2112 sc0 sc1
.LBB0_1134:
	s_or_b64 exec, exec, s[46:47]
	s_and_saveexec_b64 s[46:47], s[8:9]
	s_cbranch_execz .LBB0_1136
	v_pk_add_f32 v[206:207], v[206:207], 0 op_sel_hi:[1,0]
	v_pk_add_f32 v[210:211], v[210:211], 0 op_sel_hi:[1,0]
	v_pk_mul_f32 v[206:207], v[142:143], v[206:207]
	v_pk_add_f32 v[198:199], v[198:199], 0 op_sel_hi:[1,0]
	v_pk_mul_f32 v[210:211], v[144:145], v[210:211]
	v_pk_fma_f32 v[206:207], v[58:59], v[138:139], v[206:207]
	v_pk_add_f32 v[208:209], v[208:209], 0 op_sel_hi:[1,0]
	v_pk_fma_f32 v[210:211], v[60:61], v[140:141], v[210:211]
	v_pk_fma_f32 v[198:199], v[134:135], v[198:199], v[206:207]
	v_pk_fma_f32 v[206:207], v[136:137], v[208:209], v[210:211]
	v_pk_add_f32 v[198:199], v[130:131], v[198:199]
	v_pk_add_f32 v[206:207], v[132:133], v[206:207]
	v_mul_f32_e32 v208, 0xbfb8aa3b, v198
	v_mul_f32_e32 v209, 0xbfb8aa3b, v199
	v_exp_f32_e32 v208, v208
	v_exp_f32_e32 v209, v209
	v_mul_f32_e32 v210, 0xbfb8aa3b, v206
	v_mul_f32_e32 v211, 0xbfb8aa3b, v207
	v_exp_f32_e32 v210, v210
	v_exp_f32_e32 v211, v211
	v_add_f32_e32 v208, 1.0, v208
	v_add_f32_e32 v209, 1.0, v209
	v_pk_add_f32 v[168:169], v[214:215], 0 op_sel_hi:[1,0]
	v_rcp_f32_e32 v208, v208
	v_rcp_f32_e32 v209, v209
	v_add_f32_e32 v210, 1.0, v210
	v_add_f32_e32 v211, 1.0, v211
	v_pk_add_f32 v[190:191], v[218:219], 0 op_sel_hi:[1,0]
	v_pk_mul_f32 v[168:169], v[158:159], v[168:169]
	v_rcp_f32_e32 v210, v210
	v_rcp_f32_e32 v211, v211
	v_pk_add_f32 v[212:213], v[212:213], 0 op_sel_hi:[1,0]
	v_pk_mul_f32 v[190:191], v[160:161], v[190:191]
	v_pk_fma_f32 v[168:169], v[38:39], v[154:155], v[168:169]
	v_pk_add_f32 v[214:215], v[216:217], 0 op_sel_hi:[1,0]
	v_pk_fma_f32 v[190:191], v[40:41], v[156:157], v[190:191]
	v_pk_fma_f32 v[168:169], v[146:147], v[212:213], v[168:169]
	v_pk_fma_f32 v[190:191], v[148:149], v[214:215], v[190:191]
	v_pk_add_f32 v[168:169], v[150:151], v[168:169]
	v_pk_mul_f32 v[198:199], v[198:199], v[208:209]
	v_pk_add_f32 v[190:191], v[152:153], v[190:191]
	v_pk_mul_f32 v[168:169], v[198:199], v[168:169]
	v_pk_mul_f32 v[198:199], v[206:207], v[210:211]
	v_cvt_pk_bf16_f32 v168, v168, v169
	v_pk_mul_f32 v[190:191], v[198:199], v[190:191]
	s_nop 0
	v_cvt_pk_bf16_f32 v169, v190, v191
	v_mov_b64_e32 v[190:191], s[22:23]
	v_mad_i64_i32 v[190:191], s[48:49], v244, s72, v[190:191]
	v_lshl_add_u64 v[190:191], v[176:177], 1, v[190:191]
	global_store_dwordx2 v[190:191], v[168:169], off offset:32 sc0 sc1
.LBB0_1136:
	s_or_b64 exec, exec, s[46:47]
	v_mov_b32_dpp v168, v50 row_shr:1 row_mask:0xf bank_mask:0xf bound_ctrl:1
	v_mov_b32_dpp v169, v51 row_shr:1 row_mask:0xf bank_mask:0xf bound_ctrl:1
	v_mov_b32_dpp v208, v52 row_shr:1 row_mask:0xf bank_mask:0xf bound_ctrl:1
	v_mov_b32_dpp v209, v53 row_shr:1 row_mask:0xf bank_mask:0xf bound_ctrl:1
	v_mov_b32_dpp v190, v50 row_shr:2 row_mask:0xf bank_mask:0xf bound_ctrl:1
	v_mov_b32_dpp v191, v51 row_shr:2 row_mask:0xf bank_mask:0xf bound_ctrl:1
	v_pk_add_f32 v[194:195], v[194:195], v[208:209]
	v_pk_add_f32 v[168:169], v[188:189], v[168:169]
	v_mov_b32_dpp v210, v52 row_shr:2 row_mask:0xf bank_mask:0xf bound_ctrl:1
	v_mov_b32_dpp v211, v53 row_shr:2 row_mask:0xf bank_mask:0xf bound_ctrl:1
	v_pk_add_f32 v[186:187], v[186:187], v[190:191]
	v_pk_mul_f32 v[168:169], v[142:143], v[168:169]
	v_pk_mul_f32 v[190:191], v[144:145], v[194:195]
	v_pk_add_f32 v[188:189], v[192:193], v[210:211]
	v_pk_fma_f32 v[190:191], v[52:53], v[140:141], v[190:191]
	v_pk_fma_f32 v[168:169], v[50:51], v[138:139], v[168:169]
	v_mov_b32_dpp v192, v24 row_shr:1 row_mask:0xf bank_mask:0xf bound_ctrl:1
	v_pk_fma_f32 v[168:169], v[134:135], v[186:187], v[168:169]
	v_pk_fma_f32 v[186:187], v[136:137], v[188:189], v[190:191]
	v_mov_b32_dpp v188, v22 row_shr:1 row_mask:0xf bank_mask:0xf bound_ctrl:1
	v_mov_b32_dpp v189, v23 row_shr:1 row_mask:0xf bank_mask:0xf bound_ctrl:1
	v_mov_b32_dpp v193, v25 row_shr:1 row_mask:0xf bank_mask:0xf bound_ctrl:1
	v_pk_add_f32 v[184:185], v[184:185], v[192:193]
	v_pk_add_f32 v[180:181], v[180:181], v[188:189]
	v_mov_b32_dpp v190, v22 row_shr:2 row_mask:0xf bank_mask:0xf bound_ctrl:1
	v_mov_b32_dpp v191, v23 row_shr:2 row_mask:0xf bank_mask:0xf bound_ctrl:1
	v_mov_b32_dpp v210, v24 row_shr:2 row_mask:0xf bank_mask:0xf bound_ctrl:1
	v_mov_b32_dpp v211, v25 row_shr:2 row_mask:0xf bank_mask:0xf bound_ctrl:1
	v_pk_mul_f32 v[180:181], v[158:159], v[180:181]
	v_pk_mul_f32 v[184:185], v[160:161], v[184:185]
	v_pk_add_f32 v[168:169], v[130:131], v[168:169]
	v_pk_add_f32 v[182:183], v[182:183], v[210:211]
	v_pk_add_f32 v[178:179], v[178:179], v[190:191]
	v_pk_fma_f32 v[184:185], v[24:25], v[156:157], v[184:185]
	v_pk_fma_f32 v[180:181], v[22:23], v[154:155], v[180:181]
	v_pk_add_f32 v[186:187], v[132:133], v[186:187]
	v_pk_fma_f32 v[178:179], v[146:147], v[178:179], v[180:181]
	v_pk_fma_f32 v[180:181], v[148:149], v[182:183], v[184:185]
	v_mul_f32_e32 v182, 0xbfb8aa3b, v168
	v_mul_f32_e32 v183, 0xbfb8aa3b, v169
	v_exp_f32_e32 v182, v182
	v_exp_f32_e32 v183, v183
	v_mul_f32_e32 v184, 0xbfb8aa3b, v186
	v_mul_f32_e32 v185, 0xbfb8aa3b, v187
	v_exp_f32_e32 v184, v184
	v_exp_f32_e32 v185, v185
	v_add_f32_e32 v182, 1.0, v182
	v_add_f32_e32 v183, 1.0, v183
	v_rcp_f32_e32 v182, v182
	v_rcp_f32_e32 v183, v183
	v_add_f32_e32 v184, 1.0, v184
	v_add_f32_e32 v185, 1.0, v185
	v_rcp_f32_e32 v184, v184
	v_rcp_f32_e32 v185, v185
	v_pk_add_f32 v[178:179], v[150:151], v[178:179]
	v_pk_mul_f32 v[168:169], v[168:169], v[182:183]
	v_pk_add_f32 v[180:181], v[152:153], v[180:181]
	v_pk_mul_f32 v[168:169], v[168:169], v[178:179]
	v_pk_mul_f32 v[178:179], v[186:187], v[184:185]
	v_cvt_pk_bf16_f32 v168, v168, v169
	v_pk_mul_f32 v[178:179], v[178:179], v[180:181]
	v_mov_b32_dpp v198, v50 row_shl:15 row_mask:0xf bank_mask:0xf bound_ctrl:1
	v_cvt_pk_bf16_f32 v169, v178, v179
	v_mov_b32_dpp v199, v51 row_shl:15 row_mask:0xf bank_mask:0xf bound_ctrl:1
	global_store_dwordx2 v[200:201], v[168:169], off offset:32 sc0 sc1
	v_mov_b32_dpp v168, v34 row_shr:1 row_mask:0xf bank_mask:0xf bound_ctrl:1
	v_mov_b32_dpp v169, v35 row_shr:1 row_mask:0xf bank_mask:0xf bound_ctrl:1
	v_mov_b32_dpp v212, v52 row_shl:15 row_mask:0xf bank_mask:0xf bound_ctrl:1
	v_mov_b32_dpp v213, v53 row_shl:15 row_mask:0xf bank_mask:0xf bound_ctrl:1
	v_mov_b32_dpp v188, v36 row_shr:1 row_mask:0xf bank_mask:0xf bound_ctrl:1
	v_mov_b32_dpp v189, v37 row_shr:1 row_mask:0xf bank_mask:0xf bound_ctrl:1
	v_pk_add_f32 v[168:169], v[198:199], v[168:169]
	v_mov_b32_dpp v206, v50 row_shl:14 row_mask:0xf bank_mask:0xf bound_ctrl:1
	v_mov_b32_dpp v207, v51 row_shl:14 row_mask:0xf bank_mask:0xf bound_ctrl:1
	v_mov_b32_dpp v194, v22 row_shl:15 row_mask:0xf bank_mask:0xf bound_ctrl:1
	v_mov_b32_dpp v195, v23 row_shl:15 row_mask:0xf bank_mask:0xf bound_ctrl:1
	v_mov_b32_dpp v186, v34 row_shr:2 row_mask:0xf bank_mask:0xf bound_ctrl:1
	v_mov_b32_dpp v187, v35 row_shr:2 row_mask:0xf bank_mask:0xf bound_ctrl:1
	v_pk_add_f32 v[188:189], v[212:213], v[188:189]
	v_pk_mul_f32 v[168:169], v[142:143], v[168:169]
	v_mov_b32_dpp v200, v10 row_shr:1 row_mask:0xf bank_mask:0xf bound_ctrl:1
	v_mov_b32_dpp v201, v11 row_shr:1 row_mask:0xf bank_mask:0xf bound_ctrl:1
	v_mov_b32_dpp v214, v52 row_shl:14 row_mask:0xf bank_mask:0xf bound_ctrl:1
	v_mov_b32_dpp v215, v53 row_shl:14 row_mask:0xf bank_mask:0xf bound_ctrl:1
	v_mov_b32_dpp v216, v24 row_shl:15 row_mask:0xf bank_mask:0xf bound_ctrl:1
	v_mov_b32_dpp v217, v25 row_shl:15 row_mask:0xf bank_mask:0xf bound_ctrl:1
	v_mov_b32_dpp v190, v36 row_shr:2 row_mask:0xf bank_mask:0xf bound_ctrl:1
	v_mov_b32_dpp v191, v37 row_shr:2 row_mask:0xf bank_mask:0xf bound_ctrl:1
	v_pk_add_f32 v[186:187], v[206:207], v[186:187]
	v_pk_mul_f32 v[188:189], v[144:145], v[188:189]
	v_pk_fma_f32 v[168:169], v[34:35], v[138:139], v[168:169]
	v_mov_b32_dpp v210, v12 row_shr:1 row_mask:0xf bank_mask:0xf bound_ctrl:1
	v_mov_b32_dpp v211, v13 row_shr:1 row_mask:0xf bank_mask:0xf bound_ctrl:1
	v_pk_add_f32 v[194:195], v[194:195], v[200:201]
	v_mov_b32_dpp v208, v22 row_shl:14 row_mask:0xf bank_mask:0xf bound_ctrl:1
	v_mov_b32_dpp v209, v23 row_shl:14 row_mask:0xf bank_mask:0xf bound_ctrl:1
	v_pk_add_f32 v[190:191], v[214:215], v[190:191]
	v_pk_fma_f32 v[188:189], v[36:37], v[140:141], v[188:189]
	v_pk_fma_f32 v[168:169], v[134:135], v[186:187], v[168:169]
	v_mov_b32_dpp v206, v10 row_shr:2 row_mask:0xf bank_mask:0xf bound_ctrl:1
	v_mov_b32_dpp v207, v11 row_shr:2 row_mask:0xf bank_mask:0xf bound_ctrl:1
	v_pk_add_f32 v[210:211], v[216:217], v[210:211]
	v_pk_mul_f32 v[194:195], v[158:159], v[194:195]
	v_mov_b32_dpp v218, v24 row_shl:14 row_mask:0xf bank_mask:0xf bound_ctrl:1
	v_mov_b32_dpp v219, v25 row_shl:14 row_mask:0xf bank_mask:0xf bound_ctrl:1
	v_pk_fma_f32 v[186:187], v[136:137], v[190:191], v[188:189]
	v_pk_add_f32 v[168:169], v[130:131], v[168:169]
	v_mov_b32_dpp v212, v12 row_shr:2 row_mask:0xf bank_mask:0xf bound_ctrl:1
	v_mov_b32_dpp v213, v13 row_shr:2 row_mask:0xf bank_mask:0xf bound_ctrl:1
	v_pk_add_f32 v[206:207], v[208:209], v[206:207]
	v_pk_mul_f32 v[208:209], v[160:161], v[210:211]
	v_pk_fma_f32 v[194:195], v[10:11], v[154:155], v[194:195]
	v_pk_add_f32 v[198:199], v[132:133], v[186:187]
	v_pk_add_f32 v[200:201], v[218:219], v[212:213]
	v_pk_fma_f32 v[208:209], v[12:13], v[156:157], v[208:209]
	v_pk_fma_f32 v[194:195], v[146:147], v[206:207], v[194:195]
	v_mul_f32_e32 v206, 0xbfb8aa3b, v168
	v_mul_f32_e32 v207, 0xbfb8aa3b, v169
	v_pk_fma_f32 v[200:201], v[148:149], v[200:201], v[208:209]
	v_exp_f32_e32 v206, v206
	v_exp_f32_e32 v207, v207
	v_mul_f32_e32 v208, 0xbfb8aa3b, v198
	v_mul_f32_e32 v209, 0xbfb8aa3b, v199
	v_exp_f32_e32 v208, v208
	v_exp_f32_e32 v209, v209
	v_add_f32_e32 v206, 1.0, v206
	v_add_f32_e32 v207, 1.0, v207
	v_rcp_f32_e32 v206, v206
	v_rcp_f32_e32 v207, v207
	v_add_f32_e32 v208, 1.0, v208
	v_add_f32_e32 v209, 1.0, v209
	v_rcp_f32_e32 v208, v208
	v_rcp_f32_e32 v209, v209
	v_pk_add_f32 v[194:195], v[150:151], v[194:195]
	v_pk_mul_f32 v[168:169], v[168:169], v[206:207]
	v_pk_add_f32 v[200:201], v[152:153], v[200:201]
	v_pk_mul_f32 v[168:169], v[168:169], v[194:195]
	v_pk_mul_f32 v[194:195], v[198:199], v[208:209]
	v_cvt_pk_bf16_f32 v168, v168, v169
	v_pk_mul_f32 v[194:195], v[194:195], v[200:201]
	v_mov_b32_dpp v180, v34 row_shl:15 row_mask:0xf bank_mask:0xf bound_ctrl:1
	v_cvt_pk_bf16_f32 v169, v194, v195
	v_mov_b32_dpp v178, v34 row_shl:14 row_mask:0xf bank_mask:0xf bound_ctrl:1
	v_mov_b32_dpp v181, v35 row_shl:15 row_mask:0xf bank_mask:0xf bound_ctrl:1
	v_mov_b32_dpp v179, v35 row_shl:14 row_mask:0xf bank_mask:0xf bound_ctrl:1
	v_mov_b32_dpp v184, v36 row_shl:15 row_mask:0xf bank_mask:0xf bound_ctrl:1
	v_mov_b32_dpp v182, v36 row_shl:14 row_mask:0xf bank_mask:0xf bound_ctrl:1
	v_mov_b32_dpp v185, v37 row_shl:15 row_mask:0xf bank_mask:0xf bound_ctrl:1
	v_mov_b32_dpp v183, v37 row_shl:14 row_mask:0xf bank_mask:0xf bound_ctrl:1
	v_mov_b32_dpp v188, v10 row_shl:15 row_mask:0xf bank_mask:0xf bound_ctrl:1
	v_mov_b32_dpp v186, v10 row_shl:14 row_mask:0xf bank_mask:0xf bound_ctrl:1
	v_mov_b32_dpp v189, v11 row_shl:15 row_mask:0xf bank_mask:0xf bound_ctrl:1
	v_mov_b32_dpp v187, v11 row_shl:14 row_mask:0xf bank_mask:0xf bound_ctrl:1
	v_mov_b32_dpp v192, v12 row_shl:15 row_mask:0xf bank_mask:0xf bound_ctrl:1
	v_mov_b32_dpp v190, v12 row_shl:14 row_mask:0xf bank_mask:0xf bound_ctrl:1
	v_mov_b32_dpp v193, v13 row_shl:15 row_mask:0xf bank_mask:0xf bound_ctrl:1
	v_mov_b32_dpp v191, v13 row_shl:14 row_mask:0xf bank_mask:0xf bound_ctrl:1
	global_store_dwordx2 v[202:203], v[168:169], off offset:32 sc0 sc1
	v_mov_b32_dpp v200, v18 row_shr:1 row_mask:0xf bank_mask:0xf bound_ctrl:1
	v_mov_b32_dpp v194, v18 row_shr:2 row_mask:0xf bank_mask:0xf bound_ctrl:1
	v_mov_b32_dpp v201, v19 row_shr:1 row_mask:0xf bank_mask:0xf bound_ctrl:1
	v_mov_b32_dpp v195, v19 row_shr:2 row_mask:0xf bank_mask:0xf bound_ctrl:1
	v_mov_b32_dpp v202, v20 row_shr:1 row_mask:0xf bank_mask:0xf bound_ctrl:1
	v_mov_b32_dpp v198, v20 row_shr:2 row_mask:0xf bank_mask:0xf bound_ctrl:1
	v_mov_b32_dpp v203, v21 row_shr:1 row_mask:0xf bank_mask:0xf bound_ctrl:1
	v_mov_b32_dpp v199, v21 row_shr:2 row_mask:0xf bank_mask:0xf bound_ctrl:1
	s_and_saveexec_b64 s[46:47], s[6:7]
	s_cbranch_execz .LBB0_1138
	global_store_dwordx4 v[196:197], v[18:21], off offset:64 sc0 sc1
.LBB0_1138:
	s_or_b64 exec, exec, s[46:47]
	v_mov_b32_dpp v210, v2 row_shr:1 row_mask:0xf bank_mask:0xf bound_ctrl:1
	v_mov_b32_dpp v206, v2 row_shr:2 row_mask:0xf bank_mask:0xf bound_ctrl:1
	v_mov_b32_dpp v211, v3 row_shr:1 row_mask:0xf bank_mask:0xf bound_ctrl:1
	v_mov_b32_dpp v207, v3 row_shr:2 row_mask:0xf bank_mask:0xf bound_ctrl:1
	v_mov_b32_dpp v212, v4 row_shr:1 row_mask:0xf bank_mask:0xf bound_ctrl:1
	v_mov_b32_dpp v208, v4 row_shr:2 row_mask:0xf bank_mask:0xf bound_ctrl:1
	v_mov_b32_dpp v213, v5 row_shr:1 row_mask:0xf bank_mask:0xf bound_ctrl:1
	v_mov_b32_dpp v209, v5 row_shr:2 row_mask:0xf bank_mask:0xf bound_ctrl:1
	s_and_saveexec_b64 s[46:47], s[6:7]
	s_cbranch_execz .LBB0_1140
	v_add_co_u32_e32 v168, vcc, 0x5000, v196
	s_nop 1
	v_addc_co_u32_e32 v169, vcc, 0, v197, vcc
	global_store_dwordx4 v[168:169], v[2:5], off offset:2112 sc0 sc1
.LBB0_1140:
	s_or_b64 exec, exec, s[46:47]
	v_pk_add_f32 v[168:169], v[192:193], v[212:213]
	v_pk_add_f32 v[188:189], v[188:189], v[210:211]
	v_pk_mul_f32 v[160:161], v[160:161], v[168:169]
	v_pk_mul_f32 v[158:159], v[158:159], v[188:189]
	v_pk_add_f32 v[190:191], v[190:191], v[208:209]
	v_pk_add_f32 v[186:187], v[186:187], v[206:207]
	v_pk_fma_f32 v[156:157], v[4:5], v[156:157], v[160:161]
	v_pk_fma_f32 v[154:155], v[2:3], v[154:155], v[158:159]
	v_pk_fma_f32 v[148:149], v[148:149], v[190:191], v[156:157]
	v_pk_fma_f32 v[146:147], v[146:147], v[186:187], v[154:155]
	v_pk_add_f32 v[148:149], v[152:153], v[148:149]
	v_pk_add_f32 v[146:147], v[150:151], v[146:147]
	v_pk_add_f32 v[150:151], v[184:185], v[202:203]
	v_pk_add_f32 v[152:153], v[180:181], v[200:201]
	v_pk_mul_f32 v[144:145], v[144:145], v[150:151]
	v_pk_mul_f32 v[142:143], v[142:143], v[152:153]
	v_pk_add_f32 v[154:155], v[182:183], v[198:199]
	v_pk_add_f32 v[156:157], v[178:179], v[194:195]
	v_pk_fma_f32 v[140:141], v[20:21], v[140:141], v[144:145]
	v_pk_fma_f32 v[138:139], v[18:19], v[138:139], v[142:143]
	v_pk_fma_f32 v[136:137], v[136:137], v[154:155], v[140:141]
	v_pk_fma_f32 v[134:135], v[134:135], v[156:157], v[138:139]
	v_pk_add_f32 v[132:133], v[132:133], v[136:137]
	v_pk_add_f32 v[130:131], v[130:131], v[134:135]
	v_mul_f32_e32 v136, 0xbfb8aa3b, v132
	v_mul_f32_e32 v134, 0xbfb8aa3b, v130
	v_mul_f32_e32 v135, 0xbfb8aa3b, v131
	v_mul_f32_e32 v137, 0xbfb8aa3b, v133
	v_exp_f32_e32 v134, v134
	v_exp_f32_e32 v135, v135
	v_exp_f32_e32 v136, v136
	v_exp_f32_e32 v137, v137
	v_add_f32_e32 v134, 1.0, v134
	v_add_f32_e32 v135, 1.0, v135
	v_add_f32_e32 v136, 1.0, v136
	v_add_f32_e32 v137, 1.0, v137
	v_rcp_f32_e32 v134, v134
	v_rcp_f32_e32 v135, v135
	v_rcp_f32_e32 v136, v136
	v_rcp_f32_e32 v137, v137
	s_mov_b64 s[46:47], 0
	v_pk_mul_f32 v[130:131], v[130:131], v[134:135]
	v_pk_mul_f32 v[132:133], v[132:133], v[136:137]
	v_pk_mul_f32 v[130:131], v[130:131], v[146:147]
	v_pk_mul_f32 v[132:133], v[132:133], v[148:149]
	v_cvt_pk_bf16_f32 v130, v130, v131
	v_cvt_pk_bf16_f32 v131, v132, v133
	global_store_dwordx2 v[204:205], v[130:131], off offset:32 sc0 sc1
.LBB0_1141:
	s_and_b64 vcc, exec, s[46:47]
	s_cbranch_vccz .LBB0_1094
	v_lshl_add_u32 v136, s20, 8, v238
	v_mov_b64_e32 v[130:131], s[28:29]
	v_mad_i64_i32 v[132:133], s[46:47], v136, s71, v[130:131]
	v_lshlrev_b64 v[134:135], 2, v[176:177]
	v_lshl_add_u64 v[132:133], v[132:133], 0, v[134:135]
	global_store_dwordx4 v[132:133], v[126:129], off sc0 sc1
	global_store_dwordx4 v[132:133], v[122:125], off offset:64 sc0 sc1
	s_nop 1
	v_add_co_u32_e32 v122, vcc, 0x5000, v132
	s_nop 1
	v_addc_co_u32_e32 v123, vcc, 0, v133, vcc
	global_store_dwordx4 v[122:123], v[110:113], off offset:2048 sc0 sc1
	global_store_dwordx4 v[122:123], v[102:105], off offset:2112 sc0 sc1
	s_nop 1
	v_or_b32_e32 v102, 16, v136
	v_mad_i64_i32 v[102:103], s[46:47], v102, s71, v[130:131]
	v_lshl_add_u64 v[102:103], v[102:103], 0, v[134:135]
	global_store_dwordx4 v[102:103], v[118:121], off sc0 sc1
	global_store_dwordx4 v[102:103], v[114:117], off offset:64 sc0 sc1
	v_add_co_u32_e32 v102, vcc, 0x5000, v102
	s_nop 1
	v_addc_co_u32_e32 v103, vcc, 0, v103, vcc
	global_store_dwordx4 v[102:103], v[94:97], off offset:2048 sc0 sc1
	global_store_dwordx4 v[102:103], v[86:89], off offset:2112 sc0 sc1
	s_nop 1
	v_or_b32_e32 v86, 32, v136
	v_mad_i64_i32 v[86:87], s[46:47], v86, s71, v[130:131]
	v_lshl_add_u64 v[86:87], v[86:87], 0, v[134:135]
	global_store_dwordx4 v[86:87], v[106:109], off sc0 sc1
	global_store_dwordx4 v[86:87], v[98:101], off offset:64 sc0 sc1
	v_add_co_u32_e32 v86, vcc, 0x5000, v86
	s_nop 1
	v_addc_co_u32_e32 v87, vcc, 0, v87, vcc
	global_store_dwordx4 v[86:87], v[78:81], off offset:2048 sc0 sc1
	global_store_dwordx4 v[86:87], v[74:77], off offset:2112 sc0 sc1
	s_nop 1
	v_or_b32_e32 v74, 48, v136
	v_mad_i64_i32 v[74:75], s[46:47], v74, s71, v[130:131]
	v_lshl_add_u64 v[74:75], v[74:75], 0, v[134:135]
	global_store_dwordx4 v[74:75], v[90:93], off sc0 sc1
	global_store_dwordx4 v[74:75], v[82:85], off offset:64 sc0 sc1
	v_add_co_u32_e32 v74, vcc, 0x5000, v74
	s_nop 1
	v_addc_co_u32_e32 v75, vcc, 0, v75, vcc
	global_store_dwordx4 v[74:75], v[70:73], off offset:2048 sc0 sc1
	global_store_dwordx4 v[74:75], v[66:69], off offset:2112 sc0 sc1
	s_nop 1
	v_add_u32_e32 v66, 0x80, v136
	v_mad_i64_i32 v[66:67], s[46:47], v66, s71, v[130:131]
	v_lshl_add_u64 v[66:67], v[66:67], 0, v[134:135]
	global_store_dwordx4 v[66:67], v[62:65], off sc0 sc1
	global_store_dwordx4 v[66:67], v[58:61], off offset:64 sc0 sc1
	s_nop 1
	v_add_co_u32_e32 v58, vcc, 0x5000, v66
	s_nop 1
	v_addc_co_u32_e32 v59, vcc, 0, v67, vcc
	global_store_dwordx4 v[58:59], v[46:49], off offset:2048 sc0 sc1
	global_store_dwordx4 v[58:59], v[38:41], off offset:2112 sc0 sc1
	s_nop 1
	v_add_u32_e32 v38, 0x90, v136
	v_mad_i64_i32 v[38:39], s[46:47], v38, s71, v[130:131]
	v_lshl_add_u64 v[38:39], v[38:39], 0, v[134:135]
	global_store_dwordx4 v[38:39], v[54:57], off sc0 sc1
	global_store_dwordx4 v[38:39], v[50:53], off offset:64 sc0 sc1
	v_add_co_u32_e32 v38, vcc, 0x5000, v38
	s_nop 1
	v_addc_co_u32_e32 v39, vcc, 0, v39, vcc
	global_store_dwordx4 v[38:39], v[30:33], off offset:2048 sc0 sc1
	global_store_dwordx4 v[38:39], v[22:25], off offset:2112 sc0 sc1
	s_nop 1
	v_add_u32_e32 v22, 0xa0, v136
	v_mad_i64_i32 v[22:23], s[46:47], v22, s71, v[130:131]
	v_lshl_add_u64 v[22:23], v[22:23], 0, v[134:135]
	global_store_dwordx4 v[22:23], v[42:45], off sc0 sc1
	global_store_dwordx4 v[22:23], v[34:37], off offset:64 sc0 sc1
	v_add_co_u32_e32 v22, vcc, 0x5000, v22
	s_nop 1
	v_addc_co_u32_e32 v23, vcc, 0, v23, vcc
	global_store_dwordx4 v[22:23], v[14:17], off offset:2048 sc0 sc1
	global_store_dwordx4 v[22:23], v[10:13], off offset:2112 sc0 sc1
	s_nop 1
	v_add_u32_e32 v10, 0xb0, v136
	v_mad_i64_i32 v[10:11], s[46:47], v10, s71, v[130:131]
	v_lshl_add_u64 v[10:11], v[10:11], 0, v[134:135]
	global_store_dwordx4 v[10:11], v[26:29], off sc0 sc1
	global_store_dwordx4 v[10:11], v[18:21], off offset:64 sc0 sc1
	v_add_co_u32_e32 v10, vcc, 0x5000, v10
	s_nop 1
	v_addc_co_u32_e32 v11, vcc, 0, v11, vcc
	global_store_dwordx4 v[10:11], v[6:9], off offset:2048 sc0 sc1
	global_store_dwordx4 v[10:11], v[2:5], off offset:2112 sc0 sc1
	s_branch .LBB0_1094

.LBB0_1297:
	ds_read_b128 v[126:129], v175
	ds_read_b128 v[134:137], v175 offset:1024
	ds_read_b128 v[138:141], v175 offset:2048
	ds_read_b128 v[142:145], v175 offset:3072
	s_add_u32 s30, s28, 0xffea0080
	s_addc_u32 s31, s29, -1
	s_cmpk_eq_i32 s60, 0x54
	s_cselect_b32 s35, s7, s31
	s_cselect_b32 s34, s6, s30
	s_cselect_b32 s31, s9, s59
	s_cselect_b32 s30, s8, s58
	v_lshl_add_u64 v[162:163], s[28:29], 0, v[150:151]
	s_add_i32 m0, s43, 0xc000
	ds_read_b128 v[158:161], v176
	ds_read_b128 v[178:181], v176 offset:1024
	ds_read_b128 v[182:185], v176 offset:2048
	ds_read_b128 v[186:189], v176 offset:3072
	ds_read_b128 v[190:193], v176 offset:4096
	ds_read_b128 v[194:197], v176 offset:5120
	ds_read_b128 v[198:201], v176 offset:6144
	ds_read_b128 v[202:205], v176 offset:7168
	global_load_lds_dwordx4 v[162:163], off
	v_lshl_add_u64 v[162:163], s[28:29], 0, v[152:153]
	s_add_i32 m0, s43, 0xe000
	s_nop 0
	global_load_lds_dwordx4 v[162:163], off
	s_waitcnt lgkmcnt(8)
	s_barrier
	s_waitcnt lgkmcnt(0)
	s_setprio 1
	s_waitcnt lgkmcnt(0)
	v_mfma_f32_16x16x32_bf16 v[130:133], v[126:129], v[158:161], v[130:133]
	v_mfma_f32_16x16x32_bf16 v[122:125], v[138:141], v[158:161], v[122:125]
	v_mfma_f32_16x16x32_bf16 v[118:121], v[126:129], v[182:185], v[118:121]
	v_mfma_f32_16x16x32_bf16 v[114:117], v[138:141], v[182:185], v[114:117]
	v_mfma_f32_16x16x32_bf16 v[102:105], v[126:129], v[190:193], v[102:105]
	v_mfma_f32_16x16x32_bf16 v[98:101], v[138:141], v[190:193], v[98:101]
	v_mfma_f32_16x16x32_bf16 v[86:89], v[126:129], v[198:201], v[86:89]
	v_mfma_f32_16x16x32_bf16 v[82:85], v[138:141], v[198:201], v[82:85]
	v_mfma_f32_16x16x32_bf16 v[130:133], v[134:137], v[178:181], v[130:133]
	v_mfma_f32_16x16x32_bf16 v[122:125], v[142:145], v[178:181], v[122:125]
	v_mfma_f32_16x16x32_bf16 v[118:121], v[134:137], v[186:189], v[118:121]
	v_mfma_f32_16x16x32_bf16 v[114:117], v[142:145], v[186:189], v[114:117]
	v_mfma_f32_16x16x32_bf16 v[102:105], v[134:137], v[194:197], v[102:105]
	v_mfma_f32_16x16x32_bf16 v[98:101], v[142:145], v[194:197], v[98:101]
	v_mfma_f32_16x16x32_bf16 v[86:89], v[134:137], v[202:205], v[86:89]
	v_mfma_f32_16x16x32_bf16 v[82:85], v[142:145], v[202:205], v[82:85]
	s_setprio 0
	s_barrier
	s_add_i32 s61, s51, s40
	v_lshl_add_u64 v[162:163], s[30:31], 0, v[146:147]
	s_mov_b32 m0, s61
	ds_read_b128 v[206:209], v177
	ds_read_b128 v[210:213], v177 offset:1024
	ds_read_b128 v[214:217], v177 offset:2048
	ds_read_b128 v[218:221], v177 offset:3072
	global_load_lds_dwordx4 v[162:163], off
	v_lshl_add_u64 v[168:169], s[30:31], 0, v[148:149]
	s_add_i32 m0, s61, 0x2000
	s_nop 0
	global_load_lds_dwordx4 v[168:169], off
	s_barrier
	s_waitcnt lgkmcnt(0)
	s_setprio 1
	s_waitcnt lgkmcnt(0)
	v_mfma_f32_16x16x32_bf16 v[110:113], v[206:209], v[158:161], v[110:113]
	v_mfma_f32_16x16x32_bf16 v[106:109], v[214:217], v[158:161], v[106:109]
	v_mfma_f32_16x16x32_bf16 v[94:97], v[206:209], v[182:185], v[94:97]
	v_mfma_f32_16x16x32_bf16 v[90:93], v[214:217], v[182:185], v[90:93]
	v_mfma_f32_16x16x32_bf16 v[78:81], v[206:209], v[190:193], v[78:81]
	v_mfma_f32_16x16x32_bf16 v[74:77], v[214:217], v[190:193], v[74:77]
	v_mfma_f32_16x16x32_bf16 v[70:73], v[206:209], v[198:201], v[70:73]
	v_mfma_f32_16x16x32_bf16 v[66:69], v[214:217], v[198:201], v[66:69]
	v_mfma_f32_16x16x32_bf16 v[110:113], v[210:213], v[178:181], v[110:113]
	v_mfma_f32_16x16x32_bf16 v[106:109], v[218:221], v[178:181], v[106:109]
	v_mfma_f32_16x16x32_bf16 v[94:97], v[210:213], v[186:189], v[94:97]
	v_mfma_f32_16x16x32_bf16 v[90:93], v[218:221], v[186:189], v[90:93]
	v_mfma_f32_16x16x32_bf16 v[78:81], v[210:213], v[194:197], v[78:81]
	v_mfma_f32_16x16x32_bf16 v[74:77], v[218:221], v[194:197], v[74:77]
	v_mfma_f32_16x16x32_bf16 v[70:73], v[210:213], v[202:205], v[70:73]
	v_mfma_f32_16x16x32_bf16 v[66:69], v[218:221], v[202:205], v[66:69]
	s_setprio 0
	s_mov_b32 m0, s43
	v_lshl_add_u64 v[222:223], s[34:35], 0, v[146:147]
	s_barrier
	ds_read_b128 v[158:161], v176 offset:16384
	ds_read_b128 v[178:181], v176 offset:17408
	ds_read_b128 v[182:185], v176 offset:18432
	ds_read_b128 v[186:189], v176 offset:19456
	ds_read_b128 v[190:193], v176 offset:20480
	ds_read_b128 v[194:197], v176 offset:21504
	ds_read_b128 v[198:201], v176 offset:22528
	ds_read_b128 v[202:205], v176 offset:23552
	global_load_lds_dwordx4 v[222:223], off
	v_lshl_add_u64 v[224:225], s[34:35], 0, v[148:149]
	s_mov_b32 m0, s44
	s_nop 0
	global_load_lds_dwordx4 v[224:225], off
	s_barrier
	s_waitcnt lgkmcnt(0)
	s_setprio 1
	s_waitcnt lgkmcnt(0)
	v_mfma_f32_16x16x32_bf16 v[62:65], v[126:129], v[158:161], v[62:65]
	v_mfma_f32_16x16x32_bf16 v[58:61], v[138:141], v[158:161], v[58:61]
	v_mfma_f32_16x16x32_bf16 v[54:57], v[126:129], v[182:185], v[54:57]
	v_mfma_f32_16x16x32_bf16 v[46:49], v[138:141], v[182:185], v[46:49]
	v_mfma_f32_16x16x32_bf16 v[38:41], v[126:129], v[190:193], v[38:41]
	v_mfma_f32_16x16x32_bf16 v[30:33], v[138:141], v[190:193], v[30:33]
	v_mfma_f32_16x16x32_bf16 v[22:25], v[126:129], v[198:201], v[22:25]
	v_mfma_f32_16x16x32_bf16 v[14:17], v[138:141], v[198:201], v[14:17]
	v_mfma_f32_16x16x32_bf16 v[62:65], v[134:137], v[178:181], v[62:65]
	v_mfma_f32_16x16x32_bf16 v[58:61], v[142:145], v[178:181], v[58:61]
	v_mfma_f32_16x16x32_bf16 v[54:57], v[134:137], v[186:189], v[54:57]
	v_mfma_f32_16x16x32_bf16 v[46:49], v[142:145], v[186:189], v[46:49]
	v_mfma_f32_16x16x32_bf16 v[38:41], v[134:137], v[194:197], v[38:41]
	v_mfma_f32_16x16x32_bf16 v[30:33], v[142:145], v[194:197], v[30:33]
	v_mfma_f32_16x16x32_bf16 v[22:25], v[134:137], v[202:205], v[22:25]
	v_mfma_f32_16x16x32_bf16 v[14:17], v[142:145], v[202:205], v[14:17]
	s_setprio 0
	s_barrier
	s_add_u32 s62, s30, 0x160000
	s_addc_u32 s63, s31, 0
	s_add_i32 s61, s52, s40
	v_lshl_add_u64 v[126:127], s[62:63], 0, v[146:147]
	s_mov_b32 m0, s61
	s_nop 0
	global_load_lds_dwordx4 v[126:127], off
	v_lshl_add_u64 v[126:127], s[62:63], 0, v[148:149]
	s_add_i32 m0, s61, 0x2000
	s_nop 0
	global_load_lds_dwordx4 v[126:127], off
	s_waitcnt vmcnt(6)
	s_barrier
	s_setprio 1
	v_mfma_f32_16x16x32_bf16 v[50:53], v[206:209], v[158:161], v[50:53]
	v_mfma_f32_16x16x32_bf16 v[42:45], v[214:217], v[158:161], v[42:45]
	v_mfma_f32_16x16x32_bf16 v[34:37], v[206:209], v[182:185], v[34:37]
	v_mfma_f32_16x16x32_bf16 v[26:29], v[214:217], v[182:185], v[26:29]
	v_mfma_f32_16x16x32_bf16 v[18:21], v[206:209], v[190:193], v[18:21]
	v_mfma_f32_16x16x32_bf16 v[10:13], v[214:217], v[190:193], v[10:13]
	v_mfma_f32_16x16x32_bf16 v[6:9], v[206:209], v[198:201], v[6:9]
	v_mfma_f32_16x16x32_bf16 v[2:5], v[214:217], v[198:201], v[2:5]
	v_mfma_f32_16x16x32_bf16 v[50:53], v[210:213], v[178:181], v[50:53]
	v_mfma_f32_16x16x32_bf16 v[42:45], v[218:221], v[178:181], v[42:45]
	v_mfma_f32_16x16x32_bf16 v[34:37], v[210:213], v[186:189], v[34:37]
	v_mfma_f32_16x16x32_bf16 v[26:29], v[218:221], v[186:189], v[26:29]
	v_mfma_f32_16x16x32_bf16 v[18:21], v[210:213], v[194:197], v[18:21]
	v_mfma_f32_16x16x32_bf16 v[10:13], v[218:221], v[194:197], v[10:13]
	v_mfma_f32_16x16x32_bf16 v[6:9], v[210:213], v[202:205], v[6:9]
	v_mfma_f32_16x16x32_bf16 v[2:5], v[218:221], v[202:205], v[2:5]
	s_setprio 0
	s_add_i32 s61, 0, 0x18000
	v_add_u32_e32 v142, s61, v173
	s_barrier
	ds_read_b128 v[126:129], v142
	ds_read_b128 v[134:137], v142 offset:1024
	ds_read_b128 v[138:141], v142 offset:2048
	ds_read_b128 v[142:145], v142 offset:3072
	s_add_u32 s34, s34, 0x160000
	s_addc_u32 s35, s35, 0
	s_mov_b32 m0, s45
	v_lshl_add_u64 v[206:207], s[34:35], 0, v[146:147]
	ds_read_b128 v[158:161], v176 offset:32768
	ds_read_b128 v[178:181], v176 offset:33792
	ds_read_b128 v[182:185], v176 offset:34816
	ds_read_b128 v[186:189], v176 offset:35840
	ds_read_b128 v[190:193], v176 offset:36864
	ds_read_b128 v[194:197], v176 offset:37888
	ds_read_b128 v[198:201], v176 offset:38912
	ds_read_b128 v[202:205], v176 offset:39936
	global_load_lds_dwordx4 v[206:207], off
	v_lshl_add_u64 v[206:207], s[34:35], 0, v[148:149]
	s_mov_b32 m0, s46
	s_nop 0
	global_load_lds_dwordx4 v[206:207], off
	s_waitcnt lgkmcnt(8)
	s_barrier
	s_waitcnt lgkmcnt(0)
	s_setprio 1
	s_waitcnt lgkmcnt(0)
	v_mfma_f32_16x16x32_bf16 v[130:133], v[126:129], v[158:161], v[130:133]
	v_mfma_f32_16x16x32_bf16 v[122:125], v[138:141], v[158:161], v[122:125]
	v_mfma_f32_16x16x32_bf16 v[118:121], v[126:129], v[182:185], v[118:121]
	v_mfma_f32_16x16x32_bf16 v[114:117], v[138:141], v[182:185], v[114:117]
	v_mfma_f32_16x16x32_bf16 v[102:105], v[126:129], v[190:193], v[102:105]
	v_mfma_f32_16x16x32_bf16 v[98:101], v[138:141], v[190:193], v[98:101]
	v_mfma_f32_16x16x32_bf16 v[86:89], v[126:129], v[198:201], v[86:89]
	v_mfma_f32_16x16x32_bf16 v[82:85], v[138:141], v[198:201], v[82:85]
	v_mfma_f32_16x16x32_bf16 v[130:133], v[134:137], v[178:181], v[130:133]
	v_mfma_f32_16x16x32_bf16 v[122:125], v[142:145], v[178:181], v[122:125]
	v_mfma_f32_16x16x32_bf16 v[118:121], v[134:137], v[186:189], v[118:121]
	v_mfma_f32_16x16x32_bf16 v[114:117], v[142:145], v[186:189], v[114:117]
	v_mfma_f32_16x16x32_bf16 v[102:105], v[134:137], v[194:197], v[102:105]
	v_mfma_f32_16x16x32_bf16 v[98:101], v[142:145], v[194:197], v[98:101]
	v_mfma_f32_16x16x32_bf16 v[86:89], v[134:137], v[202:205], v[86:89]
	v_mfma_f32_16x16x32_bf16 v[82:85], v[142:145], v[202:205], v[82:85]
	s_setprio 0
	s_barrier
	s_add_i32 s34, 0, 0x1c000
	s_add_i32 s35, s61, s40
	v_add_u32_e32 v218, s34, v173
	v_lshl_add_u64 v[162:163], v[162:163], 0, s[18:19]
	s_mov_b32 m0, s35
	ds_read_b128 v[206:209], v218
	ds_read_b128 v[210:213], v218 offset:1024
	ds_read_b128 v[214:217], v218 offset:2048
	ds_read_b128 v[218:221], v218 offset:3072
	global_load_lds_dwordx4 v[162:163], off
	v_lshl_add_u64 v[162:163], v[168:169], 0, s[18:19]
	s_add_i32 m0, s35, 0x2000
	s_nop 0
	global_load_lds_dwordx4 v[162:163], off
	s_barrier
	s_waitcnt lgkmcnt(0)
	s_setprio 1
	s_waitcnt lgkmcnt(0)
	v_mfma_f32_16x16x32_bf16 v[110:113], v[206:209], v[158:161], v[110:113]
	v_mfma_f32_16x16x32_bf16 v[106:109], v[214:217], v[158:161], v[106:109]
	v_mfma_f32_16x16x32_bf16 v[94:97], v[206:209], v[182:185], v[94:97]
	v_mfma_f32_16x16x32_bf16 v[90:93], v[214:217], v[182:185], v[90:93]
	v_mfma_f32_16x16x32_bf16 v[78:81], v[206:209], v[190:193], v[78:81]
	v_mfma_f32_16x16x32_bf16 v[74:77], v[214:217], v[190:193], v[74:77]
	v_mfma_f32_16x16x32_bf16 v[70:73], v[206:209], v[198:201], v[70:73]
	v_mfma_f32_16x16x32_bf16 v[66:69], v[214:217], v[198:201], v[66:69]
	v_mfma_f32_16x16x32_bf16 v[110:113], v[210:213], v[178:181], v[110:113]
	v_mfma_f32_16x16x32_bf16 v[106:109], v[218:221], v[178:181], v[106:109]
	v_mfma_f32_16x16x32_bf16 v[94:97], v[210:213], v[186:189], v[94:97]
	v_mfma_f32_16x16x32_bf16 v[90:93], v[218:221], v[186:189], v[90:93]
	v_mfma_f32_16x16x32_bf16 v[78:81], v[210:213], v[194:197], v[78:81]
	v_mfma_f32_16x16x32_bf16 v[74:77], v[218:221], v[194:197], v[74:77]
	v_mfma_f32_16x16x32_bf16 v[70:73], v[210:213], v[202:205], v[70:73]
	v_mfma_f32_16x16x32_bf16 v[66:69], v[218:221], v[202:205], v[66:69]
	s_setprio 0
	s_mov_b32 m0, s48
	v_lshl_add_u64 v[162:163], v[222:223], 0, s[18:19]
	s_barrier
	ds_read_b128 v[158:161], v176 offset:49152
	ds_read_b128 v[178:181], v176 offset:50176
	ds_read_b128 v[182:185], v176 offset:51200
	ds_read_b128 v[186:189], v176 offset:52224
	ds_read_b128 v[190:193], v176 offset:53248
	ds_read_b128 v[194:197], v176 offset:54272
	ds_read_b128 v[198:201], v176 offset:55296
	ds_read_b128 v[202:205], v176 offset:56320
	global_load_lds_dwordx4 v[162:163], off
	v_lshl_add_u64 v[162:163], v[224:225], 0, s[18:19]
	s_mov_b32 m0, s49
	s_nop 0
	global_load_lds_dwordx4 v[162:163], off
	s_barrier
	s_waitcnt lgkmcnt(0)
	s_setprio 1
	s_waitcnt lgkmcnt(0)
	v_mfma_f32_16x16x32_bf16 v[62:65], v[126:129], v[158:161], v[62:65]
	v_mfma_f32_16x16x32_bf16 v[58:61], v[138:141], v[158:161], v[58:61]
	v_mfma_f32_16x16x32_bf16 v[54:57], v[126:129], v[182:185], v[54:57]
	v_mfma_f32_16x16x32_bf16 v[46:49], v[138:141], v[182:185], v[46:49]
	v_mfma_f32_16x16x32_bf16 v[38:41], v[126:129], v[190:193], v[38:41]
	v_mfma_f32_16x16x32_bf16 v[30:33], v[138:141], v[190:193], v[30:33]
	v_mfma_f32_16x16x32_bf16 v[22:25], v[126:129], v[198:201], v[22:25]
	v_mfma_f32_16x16x32_bf16 v[14:17], v[138:141], v[198:201], v[14:17]
	v_mfma_f32_16x16x32_bf16 v[62:65], v[134:137], v[178:181], v[62:65]
	v_mfma_f32_16x16x32_bf16 v[58:61], v[142:145], v[178:181], v[58:61]
	v_mfma_f32_16x16x32_bf16 v[54:57], v[134:137], v[186:189], v[54:57]
	v_mfma_f32_16x16x32_bf16 v[46:49], v[142:145], v[186:189], v[46:49]
	v_mfma_f32_16x16x32_bf16 v[38:41], v[134:137], v[194:197], v[38:41]
	v_mfma_f32_16x16x32_bf16 v[30:33], v[142:145], v[194:197], v[30:33]
	v_mfma_f32_16x16x32_bf16 v[22:25], v[134:137], v[202:205], v[22:25]
	v_mfma_f32_16x16x32_bf16 v[14:17], v[142:145], v[202:205], v[14:17]
	s_setprio 0
	s_barrier
	s_add_u32 s30, s30, 0x160080
	s_addc_u32 s31, s31, 0
	s_add_i32 s34, s34, s40
	v_lshl_add_u64 v[126:127], s[30:31], 0, v[146:147]
	s_mov_b32 m0, s34
	s_nop 0
	global_load_lds_dwordx4 v[126:127], off
	v_lshl_add_u64 v[126:127], s[30:31], 0, v[148:149]
	s_add_i32 m0, s34, 0x2000
	s_nop 0
	global_load_lds_dwordx4 v[126:127], off
	s_waitcnt vmcnt(6)
	s_barrier
	s_setprio 1
	v_mfma_f32_16x16x32_bf16 v[50:53], v[206:209], v[158:161], v[50:53]
	v_mfma_f32_16x16x32_bf16 v[42:45], v[214:217], v[158:161], v[42:45]
	v_mfma_f32_16x16x32_bf16 v[34:37], v[206:209], v[182:185], v[34:37]
	v_mfma_f32_16x16x32_bf16 v[26:29], v[214:217], v[182:185], v[26:29]
	v_mfma_f32_16x16x32_bf16 v[18:21], v[206:209], v[190:193], v[18:21]
	v_mfma_f32_16x16x32_bf16 v[10:13], v[214:217], v[190:193], v[10:13]
	v_mfma_f32_16x16x32_bf16 v[6:9], v[206:209], v[198:201], v[6:9]
	v_mfma_f32_16x16x32_bf16 v[2:5], v[214:217], v[198:201], v[2:5]
	v_mfma_f32_16x16x32_bf16 v[50:53], v[210:213], v[178:181], v[50:53]
	v_mfma_f32_16x16x32_bf16 v[42:45], v[218:221], v[178:181], v[42:45]
	v_mfma_f32_16x16x32_bf16 v[34:37], v[210:213], v[186:189], v[34:37]
	v_mfma_f32_16x16x32_bf16 v[26:29], v[218:221], v[186:189], v[26:29]
	v_mfma_f32_16x16x32_bf16 v[18:21], v[210:213], v[194:197], v[18:21]
	v_mfma_f32_16x16x32_bf16 v[10:13], v[218:221], v[194:197], v[10:13]
	v_mfma_f32_16x16x32_bf16 v[6:9], v[210:213], v[202:205], v[6:9]
	v_mfma_f32_16x16x32_bf16 v[2:5], v[218:221], v[202:205], v[2:5]
	s_setprio 0
	s_add_i32 s60, s60, 2
	s_add_u32 s28, s28, 0x100
	s_addc_u32 s29, s29, 0
	s_add_u32 s58, s58, 0x100
	s_addc_u32 s59, s59, 0
	s_cmpk_gt_u32 s60, 0x55
	s_barrier
	s_cbranch_scc0 .LBB0_1297
	s_lshl_b32 s30, s56, 8
	s_add_i32 s29, s30, 0xffffc000
	s_lshr_b32 s29, s29, 4
	s_ashr_i32 s28, s56, 4
	s_or_b32 s29, s29, 4
	s_cmp_lt_i32 s56, 64
	s_cselect_b32 s28, s28, s29
	v_lshl_or_b32 v126, s57, 8, v174
	s_mul_hi_i32 s29, s28, 0xc000
	s_mul_i32 s28, s28, 0xc000
	v_add_u32_e32 v168, s30, v172
	s_add_u32 s28, s12, s28
	v_ashrrev_i32_e32 v127, 31, v126
	v_ashrrev_i32_e32 v169, 31, v168
	s_addc_u32 s29, s13, s29
	v_lshlrev_b64 v[158:159], 2, v[126:127]
	v_lshlrev_b64 v[162:163], 13, v[168:169]
	v_or_b32_e32 v194, 16, v168
	v_or_b32_e32 v210, 32, v168
	v_or_b32_e32 v168, 48, v168
	v_lshl_add_u64 v[126:127], s[28:29], 0, v[158:159]
	v_ashrrev_i32_e32 v195, 31, v194
	v_ashrrev_i32_e32 v211, 31, v210
	v_ashrrev_i32_e32 v169, 31, v168
	v_lshl_add_u64 v[128:129], v[126:127], 0, s[20:21]
	v_add_co_u32_e32 v126, vcc, s53, v126
	v_lshl_add_u64 v[160:161], s[14:15], 0, v[158:159]
	v_lshlrev_b64 v[242:243], 13, v[194:195]
	v_lshlrev_b64 v[244:245], 13, v[210:211]
	v_lshlrev_b64 v[168:169], 13, v[168:169]
	v_addc_co_u32_e32 v127, vcc, 0, v127, vcc
	v_lshl_add_u64 v[190:191], v[160:161], 0, v[162:163]
	v_lshl_add_u64 v[206:207], v[160:161], 0, v[242:243]
	v_lshl_add_u64 v[222:223], v[160:161], 0, v[244:245]
	v_lshl_add_u64 v[238:239], v[160:161], 0, v[168:169]
	global_load_dwordx4 v[138:141], v[128:129], off offset:64
	global_load_dwordx4 v[134:137], v[128:129], off offset:512
	global_load_dwordx4 v[142:145], v[126:127], off
	s_nop 0
	global_load_dwordx4 v[126:129], v[128:129], off offset:576
	s_nop 0
	global_load_dwordx4 v[178:181], v[190:191], off
	global_load_dwordx4 v[182:185], v[190:191], off offset:64
	global_load_dwordx4 v[186:189], v[190:191], off offset:512
	s_nop 0
	global_load_dwordx4 v[190:193], v[190:191], off offset:576
	s_nop 0
	global_load_dwordx4 v[194:197], v[206:207], off
	global_load_dwordx4 v[198:201], v[206:207], off offset:64
	global_load_dwordx4 v[202:205], v[206:207], off offset:512
	s_nop 0
	global_load_dwordx4 v[206:209], v[206:207], off offset:576
	s_nop 0
	global_load_dwordx4 v[210:213], v[222:223], off
	global_load_dwordx4 v[214:217], v[222:223], off offset:64
	global_load_dwordx4 v[218:221], v[222:223], off offset:512
	s_nop 0
	global_load_dwordx4 v[222:225], v[222:223], off offset:576
	s_nop 0
	global_load_dwordx4 v[226:229], v[238:239], off
	global_load_dwordx4 v[230:233], v[238:239], off offset:64
	global_load_dwordx4 v[234:237], v[238:239], off offset:512
	s_nop 0
	global_load_dwordx4 v[238:241], v[238:239], off offset:576
	v_lshl_add_u64 v[246:247], s[14:15], 0, v[162:163]
	v_lshl_add_u64 v[246:247], v[246:247], 0, v[158:159]
	s_waitcnt vmcnt(0)
	v_pk_fma_f32 v[108:109], v[108:109], v[128:129], v[192:193]
	v_pk_fma_f32 v[106:107], v[106:107], v[126:127], v[190:191]
	v_pk_fma_f32 v[112:113], v[112:113], v[136:137], v[188:189]
	v_pk_fma_f32 v[110:111], v[110:111], v[134:135], v[186:187]
	global_store_dwordx4 v[246:247], v[106:109], off offset:576 sc0 sc1
	global_store_dwordx4 v[246:247], v[110:113], off offset:512 sc0 sc1
	v_pk_fma_f32 v[92:93], v[92:93], v[128:129], v[208:209]
	v_lshl_add_u64 v[106:107], s[14:15], 0, v[242:243]
	v_lshl_add_u64 v[110:111], v[106:107], 0, v[158:159]
	v_pk_fma_f32 v[90:91], v[90:91], v[126:127], v[206:207]
	v_pk_fma_f32 v[96:97], v[96:97], v[136:137], v[204:205]
	v_pk_fma_f32 v[94:95], v[94:95], v[134:135], v[202:203]
	global_store_dwordx4 v[110:111], v[90:93], off offset:576 sc0 sc1
	global_store_dwordx4 v[110:111], v[94:97], off offset:512 sc0 sc1
	v_pk_fma_f32 v[76:77], v[76:77], v[128:129], v[224:225]
	v_lshl_add_u64 v[90:91], s[14:15], 0, v[244:245]
	v_lshl_add_u64 v[94:95], v[90:91], 0, v[158:159]
	v_pk_fma_f32 v[74:75], v[74:75], v[126:127], v[222:223]
	v_pk_fma_f32 v[80:81], v[80:81], v[136:137], v[220:221]
	v_pk_fma_f32 v[78:79], v[78:79], v[134:135], v[218:219]
	global_store_dwordx4 v[94:95], v[74:77], off offset:576 sc0 sc1
	v_pk_fma_f32 v[108:109], v[120:121], v[144:145], v[196:197]
	v_pk_fma_f32 v[106:107], v[118:119], v[142:143], v[194:195]
	v_lshl_add_u64 v[74:75], s[14:15], 0, v[168:169]
	v_pk_fma_f32 v[92:93], v[104:105], v[144:145], v[212:213]
	v_pk_fma_f32 v[90:91], v[102:103], v[142:143], v[210:211]
	global_store_dwordx4 v[94:95], v[78:81], off offset:512 sc0 sc1
	v_pk_fma_f32 v[76:77], v[88:89], v[144:145], v[228:229]
	v_pk_fma_f32 v[132:133], v[132:133], v[144:145], v[180:181]
	v_lshl_add_u64 v[78:79], v[74:75], 0, v[158:159]
	v_pk_fma_f32 v[74:75], v[86:87], v[142:143], v[226:227]
	v_pk_fma_f32 v[130:131], v[130:131], v[142:143], v[178:179]
	v_pk_fma_f32 v[124:125], v[124:125], v[140:141], v[184:185]
	v_pk_fma_f32 v[122:123], v[122:123], v[138:139], v[182:183]
	global_store_dwordx4 v[110:111], v[106:109], off sc0 sc1
	global_store_dwordx4 v[94:95], v[90:93], off sc0 sc1
	global_store_dwordx4 v[78:79], v[74:77], off sc0 sc1
	v_pk_fma_f32 v[108:109], v[116:117], v[140:141], v[200:201]
	v_pk_fma_f32 v[106:107], v[114:115], v[138:139], v[198:199]
	v_pk_fma_f32 v[92:93], v[100:101], v[140:141], v[216:217]
	v_pk_fma_f32 v[90:91], v[98:99], v[138:139], v[214:215]
	v_pk_fma_f32 v[76:77], v[84:85], v[140:141], v[232:233]
	v_pk_fma_f32 v[74:75], v[82:83], v[138:139], v[230:231]
	v_pk_fma_f32 v[72:73], v[72:73], v[136:137], v[236:237]
	v_pk_fma_f32 v[70:71], v[70:71], v[134:135], v[234:235]
	v_pk_fma_f32 v[68:69], v[68:69], v[128:129], v[240:241]
	v_pk_fma_f32 v[66:67], v[66:67], v[126:127], v[238:239]
	v_lshl_add_u64 v[168:169], v[162:163], 0, s[22:23]
	global_store_dwordx4 v[246:247], v[130:133], off sc0 sc1
	global_store_dwordx4 v[246:247], v[122:125], off offset:64 sc0 sc1
	global_store_dwordx4 v[110:111], v[106:109], off offset:64 sc0 sc1
	global_store_dwordx4 v[94:95], v[90:93], off offset:64 sc0 sc1
	global_store_dwordx4 v[78:79], v[74:77], off offset:64 sc0 sc1
	global_store_dwordx4 v[78:79], v[70:73], off offset:512 sc0 sc1
	global_store_dwordx4 v[78:79], v[66:69], off offset:576 sc0 sc1
	v_lshl_add_u64 v[182:183], v[162:163], 0, s[24:25]
	v_lshl_add_u64 v[108:109], v[162:163], 0, s[26:27]
	v_lshl_add_u64 v[66:67], v[160:161], 0, v[168:169]
	global_load_dwordx4 v[110:113], v[66:67], off
	global_load_dwordx4 v[114:117], v[66:67], off offset:64
	global_load_dwordx4 v[118:121], v[66:67], off offset:512
	global_load_dwordx4 v[122:125], v[66:67], off offset:576
	v_lshl_add_u64 v[66:67], v[160:161], 0, v[182:183]
	global_load_dwordx4 v[130:133], v[66:67], off
	global_load_dwordx4 v[178:181], v[66:67], off offset:64
	global_load_dwordx4 v[102:105], v[66:67], off offset:512
	global_load_dwordx4 v[98:101], v[66:67], off offset:576
	v_lshl_add_u64 v[66:67], v[160:161], 0, v[108:109]
	v_lshl_add_u64 v[106:107], v[162:163], 0, s[16:17]
	global_load_dwordx4 v[94:97], v[66:67], off
	global_load_dwordx4 v[90:93], v[66:67], off offset:64
	global_load_dwordx4 v[86:89], v[66:67], off offset:512
	global_load_dwordx4 v[82:85], v[66:67], off offset:576
	v_lshl_add_u64 v[66:67], v[160:161], 0, v[106:107]
	global_load_dwordx4 v[78:81], v[66:67], off
	global_load_dwordx4 v[74:77], v[66:67], off offset:64
	global_load_dwordx4 v[70:73], v[66:67], off offset:512
	s_nop 0
	global_load_dwordx4 v[66:69], v[66:67], off offset:576
	v_lshl_add_u64 v[160:161], s[14:15], 0, v[168:169]
	v_lshl_add_u64 v[160:161], v[160:161], 0, v[158:159]
	s_waitcnt vmcnt(0)
	v_pk_fma_f32 v[44:45], v[44:45], v[128:129], v[124:125]
	v_pk_fma_f32 v[42:43], v[42:43], v[126:127], v[122:123]
	v_pk_fma_f32 v[52:53], v[52:53], v[136:137], v[120:121]
	v_pk_fma_f32 v[50:51], v[50:51], v[134:135], v[118:119]
	global_store_dwordx4 v[160:161], v[42:45], off offset:576 sc0 sc1
	global_store_dwordx4 v[160:161], v[50:53], off offset:512 sc0 sc1
	v_pk_fma_f32 v[28:29], v[28:29], v[128:129], v[100:101]
	v_lshl_add_u64 v[42:43], s[14:15], 0, v[182:183]
	v_lshl_add_u64 v[50:51], v[42:43], 0, v[158:159]
	v_pk_fma_f32 v[26:27], v[26:27], v[126:127], v[98:99]
	v_pk_fma_f32 v[36:37], v[36:37], v[136:137], v[104:105]
	v_pk_fma_f32 v[34:35], v[34:35], v[134:135], v[102:103]
	global_store_dwordx4 v[50:51], v[26:29], off offset:576 sc0 sc1
	global_store_dwordx4 v[50:51], v[34:37], off offset:512 sc0 sc1
	v_pk_fma_f32 v[12:13], v[12:13], v[128:129], v[84:85]
	v_lshl_add_u64 v[26:27], s[14:15], 0, v[108:109]
	v_lshl_add_u64 v[34:35], v[26:27], 0, v[158:159]
	v_pk_fma_f32 v[10:11], v[10:11], v[126:127], v[82:83]
	v_pk_fma_f32 v[20:21], v[20:21], v[136:137], v[88:89]
	v_pk_fma_f32 v[18:19], v[18:19], v[134:135], v[86:87]
	global_store_dwordx4 v[34:35], v[10:13], off offset:576 sc0 sc1
	v_pk_fma_f32 v[44:45], v[56:57], v[144:145], v[132:133]
	v_pk_fma_f32 v[42:43], v[54:55], v[142:143], v[130:131]
	v_lshl_add_u64 v[10:11], s[14:15], 0, v[106:107]
	v_pk_fma_f32 v[28:29], v[40:41], v[144:145], v[96:97]
	v_pk_fma_f32 v[26:27], v[38:39], v[142:143], v[94:95]
	global_store_dwordx4 v[34:35], v[18:21], off offset:512 sc0 sc1
	v_pk_fma_f32 v[12:13], v[24:25], v[144:145], v[80:81]
	v_pk_fma_f32 v[64:65], v[64:65], v[144:145], v[112:113]
	v_lshl_add_u64 v[18:19], v[10:11], 0, v[158:159]
	v_pk_fma_f32 v[10:11], v[22:23], v[142:143], v[78:79]
	v_pk_fma_f32 v[62:63], v[62:63], v[142:143], v[110:111]
	v_pk_fma_f32 v[60:61], v[60:61], v[140:141], v[116:117]
	v_pk_fma_f32 v[58:59], v[58:59], v[138:139], v[114:115]
	global_store_dwordx4 v[50:51], v[42:45], off sc0 sc1
	global_store_dwordx4 v[34:35], v[26:29], off sc0 sc1
	global_store_dwordx4 v[18:19], v[10:13], off sc0 sc1
	v_pk_fma_f32 v[44:45], v[48:49], v[140:141], v[180:181]
	v_pk_fma_f32 v[42:43], v[46:47], v[138:139], v[178:179]
	v_pk_fma_f32 v[28:29], v[32:33], v[140:141], v[92:93]
	v_pk_fma_f32 v[26:27], v[30:31], v[138:139], v[90:91]
	v_pk_fma_f32 v[12:13], v[16:17], v[140:141], v[76:77]
	v_pk_fma_f32 v[10:11], v[14:15], v[138:139], v[74:75]
	v_pk_fma_f32 v[8:9], v[8:9], v[136:137], v[72:73]
	v_pk_fma_f32 v[6:7], v[6:7], v[134:135], v[70:71]
	v_pk_fma_f32 v[4:5], v[4:5], v[128:129], v[68:69]
	v_pk_fma_f32 v[2:3], v[2:3], v[126:127], v[66:67]
	s_and_b64 vcc, exec, s[4:5]
	s_mov_b32 s57, s54
	s_mov_b32 s56, s55
	s_mov_b64 s[30:31], s[8:9]
	s_mov_b64 s[28:29], s[6:7]
	global_store_dwordx4 v[160:161], v[62:65], off sc0 sc1
	global_store_dwordx4 v[160:161], v[58:61], off offset:64 sc0 sc1
	global_store_dwordx4 v[50:51], v[42:45], off offset:64 sc0 sc1
	global_store_dwordx4 v[34:35], v[26:29], off offset:64 sc0 sc1
	global_store_dwordx4 v[18:19], v[10:13], off offset:64 sc0 sc1
	global_store_dwordx4 v[18:19], v[6:9], off offset:512 sc0 sc1
	global_store_dwordx4 v[18:19], v[2:5], off offset:576 sc0 sc1
	s_cbranch_vccz .LBB0_1286
	s_waitcnt vmcnt(0)
	s_cmpk_gt_u32 s38, 0xff
	s_cbranch_scc1 .LBB0_1301
	s_barrier
